# v15 + GEMM K-loops: m0-hazard s_nop removed by reordering with address VALU, duplicate lgkmcnt(0) waits removed
# baseline (speedup 1.0000x reference)
; #define PG8_STAGE(bufoff, gbase, voff) do { _Pragma("unroll") for (int _i = 0; _i < 2; ++_i) \
;         __builtin_amdgcn_global_load_lds((const unsigned*)((const char*)(gbase) + (voff)[_i]), (LAS unsigned*)(lds + (bufoff) + ldsw + _i * 8192), 16, 0, 0); } while (0)
; #define PG8_LDA(dst, b, h) do { _Pragma("unroll") for (int m = 0; m < 4; ++m) _Pragma("unroll") for (int k = 0; k < 2; ++k) dst[m][k] = *(const LAS bf16x8*)(lds + PG8_SA(b, h) + aoff + m * 2048 + k * 1024); } while (0)
; #define PG8_WAIT_V(n) asm volatile("s_waitcnt vmcnt(" #n ")" ::: "memory")
; template <class Epi, class Sched>
; __device__ __forceinline__ void gemm_phase(const int wv, LAS unsigned char* lds, const Gemm g, const Sched& S, const Epi& E) {
;     ...
;         for (int t = 0; t < nt; t += 2) {
;             const bool last = (t == nt - 2);
;             const char* a1 = cA + (size_t)(t + 1) * kstepA;
;             const char* a2 = last ? nA : cA + (size_t)(t + 2) * kstepA; const char* b2 = last ? nB : cB + (size_t)(t + 2) * kstep;
;             const char* a3 = a2 + kstepA; const char* b3 = b2 + kstep;
;             if (last && has_next) S.a_ready(nxt);
;             PG8_LDB(B0, 0, 0); PG8_SCHED; PG8_LDA(At, 0, 0); PG8_STAGE(PG8_SA(1, 1), a1 + hstepA, voffA);
;             PG8_WAIT_L(8); PG8_BAR; PG8_WAIT_L(0); PG8_MMA(0, 0, At, B0); PG8_BAR; PG8_SCHED;
;             PG8_LDB(B1, 0, 1); PG8_STAGE(PG8_SB(0, 0), b2, voffB);
;             PG8_BAR; PG8_WAIT_L(0); PG8_MMA(0, 1, At, B1); PG8_BAR;
;             PG8_LDA(At, 0, 1); PG8_STAGE(PG8_SA(0, 0), a2, voffA);
;             PG8_BAR; PG8_WAIT_L(0); PG8_MMA(1, 0, At, B0); PG8_BAR; PG8_SCHED;
;             PG8_STAGE(PG8_SB(0, 1), b2 + hstepB, voffB);
;             PG8_WAIT_V(6); PG8_BAR; PG8_MMA(1, 1, At, B1); PG8_BAR;
;             PG8_LDB(B0, 1, 0); PG8_SCHED; PG8_LDA(At, 1, 0); PG8_STAGE(PG8_SA(0, 1), a2 + hstepA, voffA);
;             PG8_WAIT_L(8); PG8_BAR; PG8_WAIT_L(0); PG8_MMA(0, 0, At, B0); PG8_BAR; PG8_SCHED;
;             PG8_LDB(B1, 1, 1); PG8_STAGE(PG8_SB(1, 0), b3, voffB);
;             PG8_BAR; PG8_WAIT_L(0); PG8_MMA(0, 1, At, B1); PG8_BAR;
;             PG8_LDA(At, 1, 1); PG8_STAGE(PG8_SA(1, 0), a3, voffA);
;             PG8_BAR; PG8_WAIT_L(0); PG8_MMA(1, 0, At, B0); PG8_BAR; PG8_SCHED;
;             PG8_STAGE(PG8_SB(1, 1), b3 + hstepB, voffB);
;             PG8_WAIT_V(6); PG8_BAR; PG8_MMA(1, 1, At, B1); PG8_BAR;
.LBB0_147:
	s_add_u32 s24, s22, 0xfffc0080
	s_addc_u32 s25, s23, -1
	s_add_i32 s31, 0, 0x10000
	v_add_u32_e32 v150, s31, v152
	ds_read_b128 v[142:145], v150
	ds_read_b128 v[146:149], v150 offset:1024
	ds_read_b128 v[160:163], v150 offset:2048
	ds_read_b128 v[164:167], v150 offset:3072
	s_cmp_eq_u32 s30, 12
	s_cselect_b32 s27, s1, s25
	s_cselect_b32 s26, s3, s24
	s_cselect_b32 s25, s13, s29
	s_cselect_b32 s24, s15, s28
	v_lshl_add_u64 v[150:151], s[22:23], 0, v[138:139]
	s_add_i32 m0, s45, 0xc000
	ds_read_b128 v[168:171], v158
	ds_read_b128 v[172:175], v158 offset:1024
	ds_read_b128 v[180:183], v158 offset:2048
	ds_read_b128 v[192:195], v158 offset:3072
	ds_read_b128 v[196:199], v158 offset:4096
	ds_read_b128 v[200:203], v158 offset:5120
	ds_read_b128 v[204:207], v158 offset:6144
	ds_read_b128 v[208:211], v158 offset:7168
	global_load_lds_dwordx4 v[150:151], off
	s_add_i32 m0, s45, 0xe000
	v_lshl_add_u64 v[150:151], s[22:23], 0, v[140:141]
	global_load_lds_dwordx4 v[150:151], off
	s_waitcnt lgkmcnt(8)
	s_barrier
	s_waitcnt lgkmcnt(0)
	v_mfma_f32_16x16x32_bf16 v[126:129], v[142:145], v[168:171], v[126:129]
	v_mfma_f32_16x16x32_bf16 v[122:125], v[160:163], v[168:171], v[122:125]
	v_mfma_f32_16x16x32_bf16 v[110:113], v[142:145], v[180:183], v[110:113]
	v_mfma_f32_16x16x32_bf16 v[106:109], v[160:163], v[180:183], v[106:109]
	v_mfma_f32_16x16x32_bf16 v[94:97], v[142:145], v[196:199], v[94:97]
	v_mfma_f32_16x16x32_bf16 v[90:93], v[160:163], v[196:199], v[90:93]
	v_mfma_f32_16x16x32_bf16 v[78:81], v[142:145], v[204:207], v[78:81]
	v_mfma_f32_16x16x32_bf16 v[74:77], v[160:163], v[204:207], v[74:77]
	v_mfma_f32_16x16x32_bf16 v[126:129], v[146:149], v[172:175], v[126:129]
	v_mfma_f32_16x16x32_bf16 v[122:125], v[164:167], v[172:175], v[122:125]
	v_mfma_f32_16x16x32_bf16 v[110:113], v[146:149], v[192:195], v[110:113]
	v_mfma_f32_16x16x32_bf16 v[106:109], v[164:167], v[192:195], v[106:109]
	v_mfma_f32_16x16x32_bf16 v[94:97], v[146:149], v[200:203], v[94:97]
	v_mfma_f32_16x16x32_bf16 v[90:93], v[164:167], v[200:203], v[90:93]
	v_mfma_f32_16x16x32_bf16 v[78:81], v[146:149], v[208:211], v[78:81]
	v_mfma_f32_16x16x32_bf16 v[74:77], v[164:167], v[208:211], v[74:77]
	s_barrier
	s_add_i32 s52, 0, 0x14000
	v_add_u32_e32 v150, s52, v152
	s_add_i32 s31, s31, s44
	ds_read_b128 v[212:215], v150
	ds_read_b128 v[216:219], v150 offset:1024
	ds_read_b128 v[220:223], v150 offset:2048
	ds_read_b128 v[224:227], v150 offset:3072
	v_lshl_add_u64 v[150:151], s[24:25], 0, v[132:133]
	s_mov_b32 m0, s31
	v_lshl_add_u64 v[176:177], s[24:25], 0, v[136:137]
	global_load_lds_dwordx4 v[150:151], off
	s_add_i32 m0, s31, 0x2000
	s_nop 0
	global_load_lds_dwordx4 v[176:177], off
	s_barrier
	s_waitcnt lgkmcnt(0)
	v_mfma_f32_16x16x32_bf16 v[118:121], v[212:215], v[168:171], v[118:121]
	v_mfma_f32_16x16x32_bf16 v[114:117], v[220:223], v[168:171], v[114:117]
	v_mfma_f32_16x16x32_bf16 v[102:105], v[212:215], v[180:183], v[102:105]
	v_mfma_f32_16x16x32_bf16 v[98:101], v[220:223], v[180:183], v[98:101]
	v_mfma_f32_16x16x32_bf16 v[86:89], v[212:215], v[196:199], v[86:89]
	v_mfma_f32_16x16x32_bf16 v[82:85], v[220:223], v[196:199], v[82:85]
	v_mfma_f32_16x16x32_bf16 v[70:73], v[212:215], v[204:207], v[70:73]
	v_mfma_f32_16x16x32_bf16 v[66:69], v[220:223], v[204:207], v[66:69]
	v_mfma_f32_16x16x32_bf16 v[118:121], v[216:219], v[172:175], v[118:121]
	v_mfma_f32_16x16x32_bf16 v[114:117], v[224:227], v[172:175], v[114:117]
	v_mfma_f32_16x16x32_bf16 v[102:105], v[216:219], v[192:195], v[102:105]
	v_mfma_f32_16x16x32_bf16 v[98:101], v[224:227], v[192:195], v[98:101]
	v_mfma_f32_16x16x32_bf16 v[86:89], v[216:219], v[200:203], v[86:89]
	v_mfma_f32_16x16x32_bf16 v[82:85], v[224:227], v[200:203], v[82:85]
	v_mfma_f32_16x16x32_bf16 v[70:73], v[216:219], v[208:211], v[70:73]
	v_mfma_f32_16x16x32_bf16 v[66:69], v[224:227], v[208:211], v[66:69]
	s_mov_b32 m0, s45
	v_lshl_add_u64 v[228:229], s[26:27], 0, v[130:131]
	s_barrier
	ds_read_b128 v[168:171], v158 offset:16384
	ds_read_b128 v[172:175], v158 offset:17408
	ds_read_b128 v[180:183], v158 offset:18432
	ds_read_b128 v[192:195], v158 offset:19456
	ds_read_b128 v[196:199], v158 offset:20480
	ds_read_b128 v[200:203], v158 offset:21504
	ds_read_b128 v[204:207], v158 offset:22528
	ds_read_b128 v[208:211], v158 offset:23552
	global_load_lds_dwordx4 v[228:229], off
	s_mov_b32 m0, s46
	v_lshl_add_u64 v[230:231], s[26:27], 0, v[134:135]
	global_load_lds_dwordx4 v[230:231], off
	s_barrier
	s_waitcnt lgkmcnt(0)
	v_mfma_f32_16x16x32_bf16 v[62:65], v[142:145], v[168:171], v[62:65]
	v_mfma_f32_16x16x32_bf16 v[58:61], v[160:163], v[168:171], v[58:61]
	v_mfma_f32_16x16x32_bf16 v[46:49], v[142:145], v[180:183], v[46:49]
	v_mfma_f32_16x16x32_bf16 v[42:45], v[160:163], v[180:183], v[42:45]
	v_mfma_f32_16x16x32_bf16 v[30:33], v[142:145], v[196:199], v[30:33]
	v_mfma_f32_16x16x32_bf16 v[26:29], v[160:163], v[196:199], v[26:29]
	v_mfma_f32_16x16x32_bf16 v[14:17], v[142:145], v[204:207], v[14:17]
	v_mfma_f32_16x16x32_bf16 v[10:13], v[160:163], v[204:207], v[10:13]
	v_mfma_f32_16x16x32_bf16 v[62:65], v[146:149], v[172:175], v[62:65]
	v_mfma_f32_16x16x32_bf16 v[58:61], v[164:167], v[172:175], v[58:61]
	v_mfma_f32_16x16x32_bf16 v[46:49], v[146:149], v[192:195], v[46:49]
	v_mfma_f32_16x16x32_bf16 v[42:45], v[164:167], v[192:195], v[42:45]
	v_mfma_f32_16x16x32_bf16 v[30:33], v[146:149], v[200:203], v[30:33]
	v_mfma_f32_16x16x32_bf16 v[26:29], v[164:167], v[200:203], v[26:29]
	v_mfma_f32_16x16x32_bf16 v[14:17], v[146:149], v[208:211], v[14:17]
	v_mfma_f32_16x16x32_bf16 v[10:13], v[164:167], v[208:211], v[10:13]
	s_barrier
; #define PG8_STAGE(bufoff, gbase, voff) do { _Pragma("unroll") for (int _i = 0; _i < 2; ++_i) \
;         __builtin_amdgcn_global_load_lds((const unsigned*)((const char*)(gbase) + (voff)[_i]), (LAS unsigned*)(lds + (bufoff) + ldsw + _i * 8192), 16, 0, 0); } while (0)
; #define PG8_LDA(dst, b, h) do { _Pragma("unroll") for (int m = 0; m < 4; ++m) _Pragma("unroll") for (int k = 0; k < 2; ++k) dst[m][k] = *(const LAS bf16x8*)(lds + PG8_SA(b, h) + aoff + m * 2048 + k * 1024); } while (0)
; #define PG8_WAIT_V(n) asm volatile("s_waitcnt vmcnt(" #n ")" ::: "memory")
; template <class Epi, class Sched>
; __device__ __forceinline__ void gemm_phase(const int wv, LAS unsigned char* lds, const Gemm g, const Sched& S, const Epi& E) {
;     ...
;         for (int t = 0; t < nt; t += 2) {
;             const bool last = (t == nt - 2);
;             const char* a1 = cA + (size_t)(t + 1) * kstepA;
;             const char* a2 = last ? nA : cA + (size_t)(t + 2) * kstepA; const char* b2 = last ? nB : cB + (size_t)(t + 2) * kstep;
;             const char* a3 = a2 + kstepA; const char* b3 = b2 + kstep;
;             if (last && has_next) S.a_ready(nxt);
;             PG8_LDB(B0, 0, 0); PG8_SCHED; PG8_LDA(At, 0, 0); PG8_STAGE(PG8_SA(1, 1), a1 + hstepA, voffA);
;             PG8_WAIT_L(8); PG8_BAR; PG8_WAIT_L(0); PG8_MMA(0, 0, At, B0); PG8_BAR; PG8_SCHED;
;             PG8_LDB(B1, 0, 1); PG8_STAGE(PG8_SB(0, 0), b2, voffB);
;             PG8_BAR; PG8_WAIT_L(0); PG8_MMA(0, 1, At, B1); PG8_BAR;
;             PG8_LDA(At, 0, 1); PG8_STAGE(PG8_SA(0, 0), a2, voffA);
;             PG8_BAR; PG8_WAIT_L(0); PG8_MMA(1, 0, At, B0); PG8_BAR; PG8_SCHED;
;             PG8_STAGE(PG8_SB(0, 1), b2 + hstepB, voffB);
;             PG8_WAIT_V(6); PG8_BAR; PG8_MMA(1, 1, At, B1); PG8_BAR;
;             PG8_LDB(B0, 1, 0); PG8_SCHED; PG8_LDA(At, 1, 0); PG8_STAGE(PG8_SA(0, 1), a2 + hstepA, voffA);
;             PG8_WAIT_L(8); PG8_BAR; PG8_WAIT_L(0); PG8_MMA(0, 0, At, B0); PG8_BAR; PG8_SCHED;
;             PG8_LDB(B1, 1, 1); PG8_STAGE(PG8_SB(1, 0), b3, voffB);
;             PG8_BAR; PG8_WAIT_L(0); PG8_MMA(0, 1, At, B1); PG8_BAR;
;             PG8_LDA(At, 1, 1); PG8_STAGE(PG8_SA(1, 0), a3, voffA);
;             PG8_BAR; PG8_WAIT_L(0); PG8_MMA(1, 0, At, B0); PG8_BAR; PG8_SCHED;
;             PG8_STAGE(PG8_SB(1, 1), b3 + hstepB, voffB);
;             PG8_WAIT_V(6); PG8_BAR; PG8_MMA(1, 1, At, B1); PG8_BAR;
	s_add_u32 s34, s24, 0x40000
	s_addc_u32 s35, s25, 0
	s_add_i32 s31, s52, s44
	s_mov_b32 m0, s31
	v_lshl_add_u64 v[142:143], s[34:35], 0, v[132:133]
	global_load_lds_dwordx4 v[142:143], off
	s_add_i32 m0, s31, 0x2000
	v_lshl_add_u64 v[142:143], s[34:35], 0, v[136:137]
	global_load_lds_dwordx4 v[142:143], off
	s_waitcnt vmcnt(6)
	s_barrier
	v_mfma_f32_16x16x32_bf16 v[54:57], v[212:215], v[168:171], v[54:57]
	v_mfma_f32_16x16x32_bf16 v[50:53], v[220:223], v[168:171], v[50:53]
	v_mfma_f32_16x16x32_bf16 v[38:41], v[212:215], v[180:183], v[38:41]
	v_mfma_f32_16x16x32_bf16 v[34:37], v[220:223], v[180:183], v[34:37]
	v_mfma_f32_16x16x32_bf16 v[22:25], v[212:215], v[196:199], v[22:25]
	v_mfma_f32_16x16x32_bf16 v[18:21], v[220:223], v[196:199], v[18:21]
	v_mfma_f32_16x16x32_bf16 v[6:9], v[212:215], v[204:207], v[6:9]
	v_mfma_f32_16x16x32_bf16 v[2:5], v[220:223], v[204:207], v[2:5]
	v_mfma_f32_16x16x32_bf16 v[54:57], v[216:219], v[172:175], v[54:57]
	v_mfma_f32_16x16x32_bf16 v[50:53], v[224:227], v[172:175], v[50:53]
	v_mfma_f32_16x16x32_bf16 v[38:41], v[216:219], v[192:195], v[38:41]
	v_mfma_f32_16x16x32_bf16 v[34:37], v[224:227], v[192:195], v[34:37]
	v_mfma_f32_16x16x32_bf16 v[22:25], v[216:219], v[200:203], v[22:25]
	v_mfma_f32_16x16x32_bf16 v[18:21], v[224:227], v[200:203], v[18:21]
	v_mfma_f32_16x16x32_bf16 v[6:9], v[216:219], v[208:211], v[6:9]
	v_mfma_f32_16x16x32_bf16 v[2:5], v[224:227], v[208:211], v[2:5]
	s_add_i32 s31, 0, 0x18000
	v_add_u32_e32 v159, s31, v152
	s_barrier
	ds_read_b128 v[142:145], v159
	ds_read_b128 v[146:149], v159 offset:1024
	ds_read_b128 v[160:163], v159 offset:2048
	ds_read_b128 v[164:167], v159 offset:3072
	s_add_u32 s26, s26, 0x40000
	s_addc_u32 s27, s27, 0
	s_mov_b32 m0, s47
	v_lshl_add_u64 v[212:213], s[26:27], 0, v[130:131]
	ds_read_b128 v[168:171], v158 offset:32768
	ds_read_b128 v[172:175], v158 offset:33792
	ds_read_b128 v[180:183], v158 offset:34816
	ds_read_b128 v[192:195], v158 offset:35840
	ds_read_b128 v[196:199], v158 offset:36864
	ds_read_b128 v[200:203], v158 offset:37888
	ds_read_b128 v[204:207], v158 offset:38912
	ds_read_b128 v[208:211], v158 offset:39936
	global_load_lds_dwordx4 v[212:213], off
	s_mov_b32 m0, s48
	v_lshl_add_u64 v[212:213], s[26:27], 0, v[134:135]
	global_load_lds_dwordx4 v[212:213], off
	s_waitcnt lgkmcnt(8)
	s_barrier
	s_waitcnt lgkmcnt(0)
	v_mfma_f32_16x16x32_bf16 v[126:129], v[142:145], v[168:171], v[126:129]
	v_mfma_f32_16x16x32_bf16 v[122:125], v[160:163], v[168:171], v[122:125]
	v_mfma_f32_16x16x32_bf16 v[110:113], v[142:145], v[180:183], v[110:113]
	v_mfma_f32_16x16x32_bf16 v[106:109], v[160:163], v[180:183], v[106:109]
	v_mfma_f32_16x16x32_bf16 v[94:97], v[142:145], v[196:199], v[94:97]
	v_mfma_f32_16x16x32_bf16 v[90:93], v[160:163], v[196:199], v[90:93]
	v_mfma_f32_16x16x32_bf16 v[78:81], v[142:145], v[204:207], v[78:81]
	v_mfma_f32_16x16x32_bf16 v[74:77], v[160:163], v[204:207], v[74:77]
	v_mfma_f32_16x16x32_bf16 v[126:129], v[146:149], v[172:175], v[126:129]
	v_mfma_f32_16x16x32_bf16 v[122:125], v[164:167], v[172:175], v[122:125]
	v_mfma_f32_16x16x32_bf16 v[110:113], v[146:149], v[192:195], v[110:113]
	v_mfma_f32_16x16x32_bf16 v[106:109], v[164:167], v[192:195], v[106:109]
	v_mfma_f32_16x16x32_bf16 v[94:97], v[146:149], v[200:203], v[94:97]
	v_mfma_f32_16x16x32_bf16 v[90:93], v[164:167], v[200:203], v[90:93]
	v_mfma_f32_16x16x32_bf16 v[78:81], v[146:149], v[208:211], v[78:81]
	v_mfma_f32_16x16x32_bf16 v[74:77], v[164:167], v[208:211], v[74:77]
	s_barrier
	s_add_i32 s26, 0, 0x1c000
	s_add_i32 s27, s31, s44
	v_add_u32_e32 v159, s26, v152
	v_lshl_add_u64 v[150:151], v[150:151], 0, s[88:89]
	s_mov_b32 m0, s27
	ds_read_b128 v[212:215], v159
	ds_read_b128 v[216:219], v159 offset:1024
	ds_read_b128 v[220:223], v159 offset:2048
	ds_read_b128 v[224:227], v159 offset:3072
	global_load_lds_dwordx4 v[150:151], off
	s_add_i32 m0, s27, 0x2000
	v_lshl_add_u64 v[150:151], v[176:177], 0, s[88:89]
	global_load_lds_dwordx4 v[150:151], off
	s_barrier
; #define PG8_BAR __builtin_amdgcn_s_barrier()
; template <class Epi, class Sched>
; __device__ __forceinline__ void gemm_phase(const int wv, LAS unsigned char* lds, const Gemm g, const Sched& S, const Epi& E) {
;     ...
;         for (int t = 0; t < nt; t += 2) {
;             const bool last = (t == nt - 2);
;             const char* a1 = cA + (size_t)(t + 1) * kstepA;
;             const char* a2 = last ? nA : cA + (size_t)(t + 2) * kstepA; const char* b2 = last ? nB : cB + (size_t)(t + 2) * kstep;
;             const char* a3 = a2 + kstepA; const char* b3 = b2 + kstep;
;             if (last && has_next) S.a_ready(nxt);
;             PG8_LDB(B0, 0, 0); PG8_SCHED; PG8_LDA(At, 0, 0); PG8_STAGE(PG8_SA(1, 1), a1 + hstepA, voffA);
;             PG8_WAIT_L(8); PG8_BAR; PG8_WAIT_L(0); PG8_MMA(0, 0, At, B0); PG8_BAR; PG8_SCHED;
;             PG8_LDB(B1, 0, 1); PG8_STAGE(PG8_SB(0, 0), b2, voffB);
;             PG8_BAR; PG8_WAIT_L(0); PG8_MMA(0, 1, At, B1); PG8_BAR;
;             PG8_LDA(At, 0, 1); PG8_STAGE(PG8_SA(0, 0), a2, voffA);
;             PG8_BAR; PG8_WAIT_L(0); PG8_MMA(1, 0, At, B0); PG8_BAR; PG8_SCHED;
;             PG8_STAGE(PG8_SB(0, 1), b2 + hstepB, voffB);
;             PG8_WAIT_V(6); PG8_BAR; PG8_MMA(1, 1, At, B1); PG8_BAR;
;             PG8_LDB(B0, 1, 0); PG8_SCHED; PG8_LDA(At, 1, 0); PG8_STAGE(PG8_SA(0, 1), a2 + hstepA, voffA);
;             PG8_WAIT_L(8); PG8_BAR; PG8_WAIT_L(0); PG8_MMA(0, 0, At, B0); PG8_BAR; PG8_SCHED;
;             PG8_LDB(B1, 1, 1); PG8_STAGE(PG8_SB(1, 0), b3, voffB);
;             PG8_BAR; PG8_WAIT_L(0); PG8_MMA(0, 1, At, B1); PG8_BAR;
;             PG8_LDA(At, 1, 1); PG8_STAGE(PG8_SA(1, 0), a3, voffA);
;             PG8_BAR; PG8_WAIT_L(0); PG8_MMA(1, 0, At, B0); PG8_BAR; PG8_SCHED;
;             PG8_STAGE(PG8_SB(1, 1), b3 + hstepB, voffB);
;             PG8_WAIT_V(6); PG8_BAR; PG8_MMA(1, 1, At, B1); PG8_BAR;
;     __device__ __forceinline__ void operator()(const f32x4 (&acc)[2][2][4][2], const Unit& u, int wr, int wc, int fr, int fq) const {
;         const int row0 = (u.pm >> 6) * TB + (u.pm & 63) * 256 + wr * 64 + fr; const int pn = u.pn;
;         bf16_t* base; int ld, colt, act;
;         if (pn < 34) { base = qkvr; ld = QKVR_LD; colt = pn * 256; act = 0; }
;         else if (pn < 42) { base = gr; ld = 2048; colt = (pn - 34) * 256; act = 1; }
;         else { base = gates; ld = 2048; colt = (pn - 42) * 256; act = 2; }
	s_waitcnt lgkmcnt(0)
	v_mfma_f32_16x16x32_bf16 v[118:121], v[212:215], v[168:171], v[118:121]
	v_mfma_f32_16x16x32_bf16 v[114:117], v[220:223], v[168:171], v[114:117]
	v_mfma_f32_16x16x32_bf16 v[102:105], v[212:215], v[180:183], v[102:105]
	v_mfma_f32_16x16x32_bf16 v[98:101], v[220:223], v[180:183], v[98:101]
	v_mfma_f32_16x16x32_bf16 v[86:89], v[212:215], v[196:199], v[86:89]
	v_mfma_f32_16x16x32_bf16 v[82:85], v[220:223], v[196:199], v[82:85]
	v_mfma_f32_16x16x32_bf16 v[70:73], v[212:215], v[204:207], v[70:73]
	v_mfma_f32_16x16x32_bf16 v[66:69], v[220:223], v[204:207], v[66:69]
	v_mfma_f32_16x16x32_bf16 v[118:121], v[216:219], v[172:175], v[118:121]
	v_mfma_f32_16x16x32_bf16 v[114:117], v[224:227], v[172:175], v[114:117]
	v_mfma_f32_16x16x32_bf16 v[102:105], v[216:219], v[192:195], v[102:105]
	v_mfma_f32_16x16x32_bf16 v[98:101], v[224:227], v[192:195], v[98:101]
	v_mfma_f32_16x16x32_bf16 v[86:89], v[216:219], v[200:203], v[86:89]
	v_mfma_f32_16x16x32_bf16 v[82:85], v[224:227], v[200:203], v[82:85]
	v_mfma_f32_16x16x32_bf16 v[70:73], v[216:219], v[208:211], v[70:73]
	v_mfma_f32_16x16x32_bf16 v[66:69], v[224:227], v[208:211], v[66:69]
	s_mov_b32 m0, s49
	v_lshl_add_u64 v[150:151], v[228:229], 0, s[88:89]
	s_barrier
	ds_read_b128 v[168:171], v158 offset:49152
	ds_read_b128 v[172:175], v158 offset:50176
	ds_read_b128 v[180:183], v158 offset:51200
	ds_read_b128 v[192:195], v158 offset:52224
	ds_read_b128 v[196:199], v158 offset:53248
	ds_read_b128 v[200:203], v158 offset:54272
	ds_read_b128 v[204:207], v158 offset:55296
	ds_read_b128 v[208:211], v158 offset:56320
	global_load_lds_dwordx4 v[150:151], off
	s_mov_b32 m0, s50
	v_lshl_add_u64 v[150:151], v[230:231], 0, s[88:89]
	global_load_lds_dwordx4 v[150:151], off
	s_barrier
	s_waitcnt lgkmcnt(0)
	v_mfma_f32_16x16x32_bf16 v[62:65], v[142:145], v[168:171], v[62:65]
	v_mfma_f32_16x16x32_bf16 v[58:61], v[160:163], v[168:171], v[58:61]
	v_mfma_f32_16x16x32_bf16 v[46:49], v[142:145], v[180:183], v[46:49]
	v_mfma_f32_16x16x32_bf16 v[42:45], v[160:163], v[180:183], v[42:45]
	v_mfma_f32_16x16x32_bf16 v[30:33], v[142:145], v[196:199], v[30:33]
	v_mfma_f32_16x16x32_bf16 v[26:29], v[160:163], v[196:199], v[26:29]
	v_mfma_f32_16x16x32_bf16 v[14:17], v[142:145], v[204:207], v[14:17]
	v_mfma_f32_16x16x32_bf16 v[10:13], v[160:163], v[204:207], v[10:13]
	v_mfma_f32_16x16x32_bf16 v[62:65], v[146:149], v[172:175], v[62:65]
	v_mfma_f32_16x16x32_bf16 v[58:61], v[164:167], v[172:175], v[58:61]
	v_mfma_f32_16x16x32_bf16 v[46:49], v[146:149], v[192:195], v[46:49]
	v_mfma_f32_16x16x32_bf16 v[42:45], v[164:167], v[192:195], v[42:45]
	v_mfma_f32_16x16x32_bf16 v[30:33], v[146:149], v[200:203], v[30:33]
	v_mfma_f32_16x16x32_bf16 v[26:29], v[164:167], v[200:203], v[26:29]
	v_mfma_f32_16x16x32_bf16 v[14:17], v[146:149], v[208:211], v[14:17]
	v_mfma_f32_16x16x32_bf16 v[10:13], v[164:167], v[208:211], v[10:13]
	s_barrier
	s_add_u32 s24, s24, 0x40080
	s_addc_u32 s25, s25, 0
	s_add_i32 s26, s26, s44
	s_mov_b32 m0, s26
	v_lshl_add_u64 v[142:143], s[24:25], 0, v[132:133]
	global_load_lds_dwordx4 v[142:143], off
	s_add_i32 m0, s26, 0x2000
	v_lshl_add_u64 v[142:143], s[24:25], 0, v[136:137]
	global_load_lds_dwordx4 v[142:143], off
	s_waitcnt vmcnt(6)
	s_barrier
	v_mfma_f32_16x16x32_bf16 v[54:57], v[212:215], v[168:171], v[54:57]
	v_mfma_f32_16x16x32_bf16 v[50:53], v[220:223], v[168:171], v[50:53]
	v_mfma_f32_16x16x32_bf16 v[38:41], v[212:215], v[180:183], v[38:41]
	v_mfma_f32_16x16x32_bf16 v[34:37], v[220:223], v[180:183], v[34:37]
	v_mfma_f32_16x16x32_bf16 v[22:25], v[212:215], v[196:199], v[22:25]
	v_mfma_f32_16x16x32_bf16 v[18:21], v[220:223], v[196:199], v[18:21]
	v_mfma_f32_16x16x32_bf16 v[6:9], v[212:215], v[204:207], v[6:9]
	v_mfma_f32_16x16x32_bf16 v[2:5], v[220:223], v[204:207], v[2:5]
	v_mfma_f32_16x16x32_bf16 v[54:57], v[216:219], v[172:175], v[54:57]
	v_mfma_f32_16x16x32_bf16 v[50:53], v[224:227], v[172:175], v[50:53]
	v_mfma_f32_16x16x32_bf16 v[38:41], v[216:219], v[192:195], v[38:41]
	v_mfma_f32_16x16x32_bf16 v[34:37], v[224:227], v[192:195], v[34:37]
	v_mfma_f32_16x16x32_bf16 v[22:25], v[216:219], v[200:203], v[22:25]
	v_mfma_f32_16x16x32_bf16 v[18:21], v[224:227], v[200:203], v[18:21]
	v_mfma_f32_16x16x32_bf16 v[6:9], v[216:219], v[208:211], v[6:9]
	v_mfma_f32_16x16x32_bf16 v[2:5], v[224:227], v[208:211], v[2:5]
	s_add_i32 s30, s30, 2
	s_add_u32 s22, s22, 0x100
	s_addc_u32 s23, s23, 0
	s_add_u32 s28, s28, 0x100
	s_addc_u32 s29, s29, 0
	s_cmp_gt_u32 s30, 13
	s_barrier
	s_cbranch_scc0 .LBB0_147
	s_cmp_gt_i32 s0, 33
	s_mov_b64 s[22:23], -1
	s_cbranch_scc0 .LBB0_153
	s_lshl_b32 s1, s0, 8
	s_cmp_gt_u32 s0, 41
	s_mov_b64 s[28:29], -1
	s_mov_b64 s[24:25], -1
	s_cbranch_scc0 .LBB0_151
	s_add_i32 s3, s1, 0xffffd600
	s_mov_b64 s[24:25], 0

; #define PG8_STAGE(bufoff, gbase, voff) do { _Pragma("unroll") for (int _i = 0; _i < 2; ++_i) \
;         __builtin_amdgcn_global_load_lds((const unsigned*)((const char*)(gbase) + (voff)[_i]), (LAS unsigned*)(lds + (bufoff) + ldsw + _i * 8192), 16, 0, 0); } while (0)
; #define PG8_LDA(dst, b, h) do { _Pragma("unroll") for (int m = 0; m < 4; ++m) _Pragma("unroll") for (int k = 0; k < 2; ++k) dst[m][k] = *(const LAS bf16x8*)(lds + PG8_SA(b, h) + aoff + m * 2048 + k * 1024); } while (0)
; #define PG8_WAIT_V(n) asm volatile("s_waitcnt vmcnt(" #n ")" ::: "memory")
; template <class Epi, class Sched>
; __device__ __forceinline__ void gemm_phase(const int wv, LAS unsigned char* lds, const Gemm g, const Sched& S, const Epi& E) {
;     ...
;         for (int t = 0; t < nt; t += 2) {
;             const bool last = (t == nt - 2);
;             const char* a1 = cA + (size_t)(t + 1) * kstepA;
;             const char* a2 = last ? nA : cA + (size_t)(t + 2) * kstepA; const char* b2 = last ? nB : cB + (size_t)(t + 2) * kstep;
;             const char* a3 = a2 + kstepA; const char* b3 = b2 + kstep;
;             if (last && has_next) S.a_ready(nxt);
;             PG8_LDB(B0, 0, 0); PG8_SCHED; PG8_LDA(At, 0, 0); PG8_STAGE(PG8_SA(1, 1), a1 + hstepA, voffA);
;             PG8_WAIT_L(8); PG8_BAR; PG8_WAIT_L(0); PG8_MMA(0, 0, At, B0); PG8_BAR; PG8_SCHED;
;             PG8_LDB(B1, 0, 1); PG8_STAGE(PG8_SB(0, 0), b2, voffB);
;             PG8_BAR; PG8_WAIT_L(0); PG8_MMA(0, 1, At, B1); PG8_BAR;
;             PG8_LDA(At, 0, 1); PG8_STAGE(PG8_SA(0, 0), a2, voffA);
;             PG8_BAR; PG8_WAIT_L(0); PG8_MMA(1, 0, At, B0); PG8_BAR; PG8_SCHED;
;             PG8_STAGE(PG8_SB(0, 1), b2 + hstepB, voffB);
;             PG8_WAIT_V(6); PG8_BAR; PG8_MMA(1, 1, At, B1); PG8_BAR;
;             PG8_LDB(B0, 1, 0); PG8_SCHED; PG8_LDA(At, 1, 0); PG8_STAGE(PG8_SA(0, 1), a2 + hstepA, voffA);
;             PG8_WAIT_L(8); PG8_BAR; PG8_WAIT_L(0); PG8_MMA(0, 0, At, B0); PG8_BAR; PG8_SCHED;
;             PG8_LDB(B1, 1, 1); PG8_STAGE(PG8_SB(1, 0), b3, voffB);
;             PG8_BAR; PG8_WAIT_L(0); PG8_MMA(0, 1, At, B1); PG8_BAR;
;             PG8_LDA(At, 1, 1); PG8_STAGE(PG8_SA(1, 0), a3, voffA);
;             PG8_BAR; PG8_WAIT_L(0); PG8_MMA(1, 0, At, B0); PG8_BAR; PG8_SCHED;
;             PG8_STAGE(PG8_SB(1, 1), b3 + hstepB, voffB);
;             PG8_WAIT_V(6); PG8_BAR; PG8_MMA(1, 1, At, B1); PG8_BAR;
.LBB0_577:
	ds_read_b128 v[144:147], v151
	ds_read_b128 v[154:157], v151 offset:1024
	ds_read_b128 v[158:161], v151 offset:2048
	ds_read_b128 v[162:165], v151 offset:3072
	s_add_u32 s22, s20, 0xfffe0080
	s_addc_u32 s23, s21, -1
	s_cmp_eq_u32 s46, 4
	s_cselect_b32 s25, s13, s23
	s_cselect_b32 s24, s42, s22
	s_cselect_b32 s23, s11, s45
	s_cselect_b32 s22, s43, s44
	v_lshl_add_u64 v[200:201], s[20:21], 0, v[136:137]
	s_add_i32 m0, s19, 0xc000
	ds_read_b128 v[166:169], v152
	ds_read_b128 v[170:173], v152 offset:1024
	ds_read_b128 v[174:177], v152 offset:2048
	ds_read_b128 v[180:183], v152 offset:3072
	ds_read_b128 v[184:187], v152 offset:4096
	ds_read_b128 v[188:191], v152 offset:5120
	ds_read_b128 v[192:195], v152 offset:6144
	ds_read_b128 v[196:199], v152 offset:7168
	global_load_lds_dwordx4 v[200:201], off
	s_add_i32 m0, s19, 0xe000
	v_lshl_add_u64 v[200:201], s[20:21], 0, v[138:139]
	global_load_lds_dwordx4 v[200:201], off
	s_waitcnt lgkmcnt(8)
	s_barrier
	s_waitcnt lgkmcnt(0)
	v_mfma_f32_16x16x32_bf16 v[124:127], v[144:147], v[166:169], v[124:127]
	v_mfma_f32_16x16x32_bf16 v[120:123], v[158:161], v[166:169], v[120:123]
	v_mfma_f32_16x16x32_bf16 v[116:119], v[144:147], v[174:177], v[116:119]
	v_mfma_f32_16x16x32_bf16 v[104:107], v[158:161], v[174:177], v[104:107]
	v_mfma_f32_16x16x32_bf16 v[96:99], v[144:147], v[184:187], v[96:99]
	v_mfma_f32_16x16x32_bf16 v[88:91], v[158:161], v[184:187], v[88:91]
	v_mfma_f32_16x16x32_bf16 v[80:83], v[144:147], v[192:195], v[80:83]
	v_mfma_f32_16x16x32_bf16 v[72:75], v[158:161], v[192:195], v[72:75]
	v_mfma_f32_16x16x32_bf16 v[124:127], v[154:157], v[170:173], v[124:127]
	v_mfma_f32_16x16x32_bf16 v[120:123], v[162:165], v[170:173], v[120:123]
	v_mfma_f32_16x16x32_bf16 v[116:119], v[154:157], v[180:183], v[116:119]
	v_mfma_f32_16x16x32_bf16 v[104:107], v[162:165], v[180:183], v[104:107]
	v_mfma_f32_16x16x32_bf16 v[96:99], v[154:157], v[188:191], v[96:99]
	v_mfma_f32_16x16x32_bf16 v[88:91], v[162:165], v[188:191], v[88:91]
	v_mfma_f32_16x16x32_bf16 v[80:83], v[154:157], v[196:199], v[80:83]
	v_mfma_f32_16x16x32_bf16 v[72:75], v[162:165], v[196:199], v[72:75]
	s_barrier
	s_add_i32 s47, s39, s31
	v_lshl_add_u64 v[216:217], s[22:23], 0, v[130:131]
	s_mov_b32 m0, s47
	ds_read_b128 v[200:203], v153
	ds_read_b128 v[204:207], v153 offset:1024
	ds_read_b128 v[208:211], v153 offset:2048
	ds_read_b128 v[212:215], v153 offset:3072
	global_load_lds_dwordx4 v[216:217], off
	s_add_i32 m0, s47, 0x2000
	v_lshl_add_u64 v[218:219], s[22:23], 0, v[134:135]
	global_load_lds_dwordx4 v[218:219], off
	s_barrier
	s_waitcnt lgkmcnt(0)
	v_mfma_f32_16x16x32_bf16 v[112:115], v[200:203], v[166:169], v[112:115]
	v_mfma_f32_16x16x32_bf16 v[108:111], v[208:211], v[166:169], v[108:111]
	v_mfma_f32_16x16x32_bf16 v[100:103], v[200:203], v[174:177], v[100:103]
	v_mfma_f32_16x16x32_bf16 v[92:95], v[208:211], v[174:177], v[92:95]
	v_mfma_f32_16x16x32_bf16 v[84:87], v[200:203], v[184:187], v[84:87]
	v_mfma_f32_16x16x32_bf16 v[76:79], v[208:211], v[184:187], v[76:79]
	v_mfma_f32_16x16x32_bf16 v[68:71], v[200:203], v[192:195], v[68:71]
	v_mfma_f32_16x16x32_bf16 v[64:67], v[208:211], v[192:195], v[64:67]
	v_mfma_f32_16x16x32_bf16 v[112:115], v[204:207], v[170:173], v[112:115]
	v_mfma_f32_16x16x32_bf16 v[108:111], v[212:215], v[170:173], v[108:111]
	v_mfma_f32_16x16x32_bf16 v[100:103], v[204:207], v[180:183], v[100:103]
	v_mfma_f32_16x16x32_bf16 v[92:95], v[212:215], v[180:183], v[92:95]
	v_mfma_f32_16x16x32_bf16 v[84:87], v[204:207], v[188:191], v[84:87]
	v_mfma_f32_16x16x32_bf16 v[76:79], v[212:215], v[188:191], v[76:79]
	v_mfma_f32_16x16x32_bf16 v[68:71], v[204:207], v[196:199], v[68:71]
	v_mfma_f32_16x16x32_bf16 v[64:67], v[212:215], v[196:199], v[64:67]
	s_mov_b32 m0, s19
	v_lshl_add_u64 v[220:221], s[24:25], 0, v[128:129]
	s_barrier
	ds_read_b128 v[166:169], v152 offset:16384
	ds_read_b128 v[170:173], v152 offset:17408
	ds_read_b128 v[174:177], v152 offset:18432
	ds_read_b128 v[180:183], v152 offset:19456
	ds_read_b128 v[184:187], v152 offset:20480
	ds_read_b128 v[188:191], v152 offset:21504
	ds_read_b128 v[192:195], v152 offset:22528
	ds_read_b128 v[196:199], v152 offset:23552
	global_load_lds_dwordx4 v[220:221], off
	s_mov_b32 m0, s33
	v_lshl_add_u64 v[222:223], s[24:25], 0, v[132:133]
	global_load_lds_dwordx4 v[222:223], off
	s_barrier
	s_waitcnt lgkmcnt(0)
	v_mfma_f32_16x16x32_bf16 v[60:63], v[144:147], v[166:169], v[60:63]
	v_mfma_f32_16x16x32_bf16 v[56:59], v[158:161], v[166:169], v[56:59]
	v_mfma_f32_16x16x32_bf16 v[48:51], v[144:147], v[174:177], v[48:51]
	v_mfma_f32_16x16x32_bf16 v[40:43], v[158:161], v[174:177], v[40:43]
	v_mfma_f32_16x16x32_bf16 v[32:35], v[144:147], v[184:187], v[32:35]
	v_mfma_f32_16x16x32_bf16 v[24:27], v[158:161], v[184:187], v[24:27]
	v_mfma_f32_16x16x32_bf16 v[16:19], v[144:147], v[192:195], v[16:19]
	v_mfma_f32_16x16x32_bf16 v[8:11], v[158:161], v[192:195], v[8:11]
	v_mfma_f32_16x16x32_bf16 v[60:63], v[154:157], v[170:173], v[60:63]
	v_mfma_f32_16x16x32_bf16 v[56:59], v[162:165], v[170:173], v[56:59]
	v_mfma_f32_16x16x32_bf16 v[48:51], v[154:157], v[180:183], v[48:51]
	v_mfma_f32_16x16x32_bf16 v[40:43], v[162:165], v[180:183], v[40:43]
	v_mfma_f32_16x16x32_bf16 v[32:35], v[154:157], v[188:191], v[32:35]
	v_mfma_f32_16x16x32_bf16 v[24:27], v[162:165], v[188:191], v[24:27]
	v_mfma_f32_16x16x32_bf16 v[16:19], v[154:157], v[196:199], v[16:19]
	v_mfma_f32_16x16x32_bf16 v[8:11], v[162:165], v[196:199], v[8:11]
	s_barrier
	s_add_u32 s48, s22, 0x20000
	s_addc_u32 s49, s23, 0
	s_add_i32 s47, s40, s31
	s_mov_b32 m0, s47
	v_lshl_add_u64 v[144:145], s[48:49], 0, v[130:131]
	global_load_lds_dwordx4 v[144:145], off
	s_add_i32 m0, s47, 0x2000
	v_lshl_add_u64 v[144:145], s[48:49], 0, v[134:135]
	global_load_lds_dwordx4 v[144:145], off
	s_waitcnt vmcnt(6)
	s_barrier
; #define PG8_STAGE(bufoff, gbase, voff) do { _Pragma("unroll") for (int _i = 0; _i < 2; ++_i) \
;         __builtin_amdgcn_global_load_lds((const unsigned*)((const char*)(gbase) + (voff)[_i]), (LAS unsigned*)(lds + (bufoff) + ldsw + _i * 8192), 16, 0, 0); } while (0)
; #define PG8_LDA(dst, b, h) do { _Pragma("unroll") for (int m = 0; m < 4; ++m) _Pragma("unroll") for (int k = 0; k < 2; ++k) dst[m][k] = *(const LAS bf16x8*)(lds + PG8_SA(b, h) + aoff + m * 2048 + k * 1024); } while (0)
; #define PG8_WAIT_V(n) asm volatile("s_waitcnt vmcnt(" #n ")" ::: "memory")
; template <class Epi, class Sched>
; __device__ __forceinline__ void gemm_phase(const int wv, LAS unsigned char* lds, const Gemm g, const Sched& S, const Epi& E) {
;     ...
;         for (int t = 0; t < nt; t += 2) {
;             const bool last = (t == nt - 2);
;             const char* a1 = cA + (size_t)(t + 1) * kstepA;
;             const char* a2 = last ? nA : cA + (size_t)(t + 2) * kstepA; const char* b2 = last ? nB : cB + (size_t)(t + 2) * kstep;
;             const char* a3 = a2 + kstepA; const char* b3 = b2 + kstep;
;             if (last && has_next) S.a_ready(nxt);
;             PG8_LDB(B0, 0, 0); PG8_SCHED; PG8_LDA(At, 0, 0); PG8_STAGE(PG8_SA(1, 1), a1 + hstepA, voffA);
;             PG8_WAIT_L(8); PG8_BAR; PG8_WAIT_L(0); PG8_MMA(0, 0, At, B0); PG8_BAR; PG8_SCHED;
;             PG8_LDB(B1, 0, 1); PG8_STAGE(PG8_SB(0, 0), b2, voffB);
;             PG8_BAR; PG8_WAIT_L(0); PG8_MMA(0, 1, At, B1); PG8_BAR;
;             PG8_LDA(At, 0, 1); PG8_STAGE(PG8_SA(0, 0), a2, voffA);
;             PG8_BAR; PG8_WAIT_L(0); PG8_MMA(1, 0, At, B0); PG8_BAR; PG8_SCHED;
;             PG8_STAGE(PG8_SB(0, 1), b2 + hstepB, voffB);
;             PG8_WAIT_V(6); PG8_BAR; PG8_MMA(1, 1, At, B1); PG8_BAR;
;             PG8_LDB(B0, 1, 0); PG8_SCHED; PG8_LDA(At, 1, 0); PG8_STAGE(PG8_SA(0, 1), a2 + hstepA, voffA);
;             PG8_WAIT_L(8); PG8_BAR; PG8_WAIT_L(0); PG8_MMA(0, 0, At, B0); PG8_BAR; PG8_SCHED;
;             PG8_LDB(B1, 1, 1); PG8_STAGE(PG8_SB(1, 0), b3, voffB);
;             PG8_BAR; PG8_WAIT_L(0); PG8_MMA(0, 1, At, B1); PG8_BAR;
;             PG8_LDA(At, 1, 1); PG8_STAGE(PG8_SA(1, 0), a3, voffA);
;             PG8_BAR; PG8_WAIT_L(0); PG8_MMA(1, 0, At, B0); PG8_BAR; PG8_SCHED;
;             PG8_STAGE(PG8_SB(1, 1), b3 + hstepB, voffB);
;             PG8_WAIT_V(6); PG8_BAR; PG8_MMA(1, 1, At, B1); PG8_BAR;
	v_mfma_f32_16x16x32_bf16 v[52:55], v[200:203], v[166:169], v[52:55]
	v_mfma_f32_16x16x32_bf16 v[44:47], v[208:211], v[166:169], v[44:47]
	v_mfma_f32_16x16x32_bf16 v[36:39], v[200:203], v[174:177], v[36:39]
	v_mfma_f32_16x16x32_bf16 v[28:31], v[208:211], v[174:177], v[28:31]
	v_mfma_f32_16x16x32_bf16 v[20:23], v[200:203], v[184:187], v[20:23]
	v_mfma_f32_16x16x32_bf16 v[12:15], v[208:211], v[184:187], v[12:15]
	v_mfma_f32_16x16x32_bf16 v[4:7], v[200:203], v[192:195], v[4:7]
	v_mfma_f32_16x16x32_bf16 v[0:3], v[208:211], v[192:195], v[0:3]
	v_mfma_f32_16x16x32_bf16 v[52:55], v[204:207], v[170:173], v[52:55]
	v_mfma_f32_16x16x32_bf16 v[44:47], v[212:215], v[170:173], v[44:47]
	v_mfma_f32_16x16x32_bf16 v[36:39], v[204:207], v[180:183], v[36:39]
	v_mfma_f32_16x16x32_bf16 v[28:31], v[212:215], v[180:183], v[28:31]
	v_mfma_f32_16x16x32_bf16 v[20:23], v[204:207], v[188:191], v[20:23]
	v_mfma_f32_16x16x32_bf16 v[12:15], v[212:215], v[188:191], v[12:15]
	v_mfma_f32_16x16x32_bf16 v[4:7], v[204:207], v[196:199], v[4:7]
	v_mfma_f32_16x16x32_bf16 v[0:3], v[212:215], v[196:199], v[0:3]
	s_add_i32 s47, 0, 0x18000
	v_add_u32_e32 v162, s47, v149
	s_barrier
	ds_read_b128 v[144:147], v162
	ds_read_b128 v[154:157], v162 offset:1024
	ds_read_b128 v[158:161], v162 offset:2048
	ds_read_b128 v[162:165], v162 offset:3072
	s_add_u32 s24, s24, 0x20000
	s_addc_u32 s25, s25, 0
	s_mov_b32 m0, s34
	v_lshl_add_u64 v[200:201], s[24:25], 0, v[128:129]
	ds_read_b128 v[166:169], v152 offset:32768
	ds_read_b128 v[170:173], v152 offset:33792
	ds_read_b128 v[174:177], v152 offset:34816
	ds_read_b128 v[180:183], v152 offset:35840
	ds_read_b128 v[184:187], v152 offset:36864
	ds_read_b128 v[188:191], v152 offset:37888
	ds_read_b128 v[192:195], v152 offset:38912
	ds_read_b128 v[196:199], v152 offset:39936
	global_load_lds_dwordx4 v[200:201], off
	s_mov_b32 m0, s35
	v_lshl_add_u64 v[200:201], s[24:25], 0, v[132:133]
	global_load_lds_dwordx4 v[200:201], off
	s_waitcnt lgkmcnt(8)
	s_barrier
	s_waitcnt lgkmcnt(0)
	v_mfma_f32_16x16x32_bf16 v[124:127], v[144:147], v[166:169], v[124:127]
	v_mfma_f32_16x16x32_bf16 v[120:123], v[158:161], v[166:169], v[120:123]
	v_mfma_f32_16x16x32_bf16 v[116:119], v[144:147], v[174:177], v[116:119]
	v_mfma_f32_16x16x32_bf16 v[104:107], v[158:161], v[174:177], v[104:107]
	v_mfma_f32_16x16x32_bf16 v[96:99], v[144:147], v[184:187], v[96:99]
	v_mfma_f32_16x16x32_bf16 v[88:91], v[158:161], v[184:187], v[88:91]
	v_mfma_f32_16x16x32_bf16 v[80:83], v[144:147], v[192:195], v[80:83]
	v_mfma_f32_16x16x32_bf16 v[72:75], v[158:161], v[192:195], v[72:75]
	v_mfma_f32_16x16x32_bf16 v[124:127], v[154:157], v[170:173], v[124:127]
	v_mfma_f32_16x16x32_bf16 v[120:123], v[162:165], v[170:173], v[120:123]
	v_mfma_f32_16x16x32_bf16 v[116:119], v[154:157], v[180:183], v[116:119]
	v_mfma_f32_16x16x32_bf16 v[104:107], v[162:165], v[180:183], v[104:107]
	v_mfma_f32_16x16x32_bf16 v[96:99], v[154:157], v[188:191], v[96:99]
	v_mfma_f32_16x16x32_bf16 v[88:91], v[162:165], v[188:191], v[88:91]
	v_mfma_f32_16x16x32_bf16 v[80:83], v[154:157], v[196:199], v[80:83]
	v_mfma_f32_16x16x32_bf16 v[72:75], v[162:165], v[196:199], v[72:75]
	s_barrier
	s_add_i32 s24, 0, 0x1c000
	s_add_i32 s25, s47, s31
	v_add_u32_e32 v212, s24, v149
	v_lshl_add_u64 v[216:217], v[216:217], 0, s[8:9]
	s_mov_b32 m0, s25
	ds_read_b128 v[200:203], v212
	ds_read_b128 v[204:207], v212 offset:1024
	ds_read_b128 v[208:211], v212 offset:2048
	ds_read_b128 v[212:215], v212 offset:3072
	global_load_lds_dwordx4 v[216:217], off
	s_add_i32 m0, s25, 0x2000
	v_lshl_add_u64 v[216:217], v[218:219], 0, s[8:9]
	global_load_lds_dwordx4 v[216:217], off
	s_barrier
	s_waitcnt lgkmcnt(0)
	v_mfma_f32_16x16x32_bf16 v[112:115], v[200:203], v[166:169], v[112:115]
	v_mfma_f32_16x16x32_bf16 v[108:111], v[208:211], v[166:169], v[108:111]
	v_mfma_f32_16x16x32_bf16 v[100:103], v[200:203], v[174:177], v[100:103]
	v_mfma_f32_16x16x32_bf16 v[92:95], v[208:211], v[174:177], v[92:95]
	v_mfma_f32_16x16x32_bf16 v[84:87], v[200:203], v[184:187], v[84:87]
	v_mfma_f32_16x16x32_bf16 v[76:79], v[208:211], v[184:187], v[76:79]
	v_mfma_f32_16x16x32_bf16 v[68:71], v[200:203], v[192:195], v[68:71]
	v_mfma_f32_16x16x32_bf16 v[64:67], v[208:211], v[192:195], v[64:67]
	v_mfma_f32_16x16x32_bf16 v[112:115], v[204:207], v[170:173], v[112:115]
	v_mfma_f32_16x16x32_bf16 v[108:111], v[212:215], v[170:173], v[108:111]
	v_mfma_f32_16x16x32_bf16 v[100:103], v[204:207], v[180:183], v[100:103]
	v_mfma_f32_16x16x32_bf16 v[92:95], v[212:215], v[180:183], v[92:95]
	v_mfma_f32_16x16x32_bf16 v[84:87], v[204:207], v[188:191], v[84:87]
	v_mfma_f32_16x16x32_bf16 v[76:79], v[212:215], v[188:191], v[76:79]
	v_mfma_f32_16x16x32_bf16 v[68:71], v[204:207], v[196:199], v[68:71]
	v_mfma_f32_16x16x32_bf16 v[64:67], v[212:215], v[196:199], v[64:67]
	s_mov_b32 m0, s37
	v_lshl_add_u64 v[216:217], v[220:221], 0, s[8:9]
	s_barrier
	ds_read_b128 v[166:169], v152 offset:49152
	ds_read_b128 v[170:173], v152 offset:50176
	ds_read_b128 v[174:177], v152 offset:51200
	ds_read_b128 v[180:183], v152 offset:52224
	ds_read_b128 v[184:187], v152 offset:53248
	ds_read_b128 v[188:191], v152 offset:54272
	ds_read_b128 v[192:195], v152 offset:55296
	ds_read_b128 v[196:199], v152 offset:56320
	global_load_lds_dwordx4 v[216:217], off
	s_mov_b32 m0, s38
	v_lshl_add_u64 v[216:217], v[222:223], 0, s[8:9]
	global_load_lds_dwordx4 v[216:217], off
	s_barrier
; template <class Epi, class Sched>
; __device__ __forceinline__ void gemm_phase(const int wv, LAS unsigned char* lds, const Gemm g, const Sched& S, const Epi& E) {
;     ...
;         for (int t = 0; t < nt; t += 2) {
;             const bool last = (t == nt - 2);
;             const char* a1 = cA + (size_t)(t + 1) * kstepA;
;             const char* a2 = last ? nA : cA + (size_t)(t + 2) * kstepA; const char* b2 = last ? nB : cB + (size_t)(t + 2) * kstep;
;             const char* a3 = a2 + kstepA; const char* b3 = b2 + kstep;
;             if (last && has_next) S.a_ready(nxt);
;             PG8_LDB(B0, 0, 0); PG8_SCHED; PG8_LDA(At, 0, 0); PG8_STAGE(PG8_SA(1, 1), a1 + hstepA, voffA);
;             PG8_WAIT_L(8); PG8_BAR; PG8_WAIT_L(0); PG8_MMA(0, 0, At, B0); PG8_BAR; PG8_SCHED;
;             PG8_LDB(B1, 0, 1); PG8_STAGE(PG8_SB(0, 0), b2, voffB);
;             PG8_BAR; PG8_WAIT_L(0); PG8_MMA(0, 1, At, B1); PG8_BAR;
;             PG8_LDA(At, 0, 1); PG8_STAGE(PG8_SA(0, 0), a2, voffA);
;             PG8_BAR; PG8_WAIT_L(0); PG8_MMA(1, 0, At, B0); PG8_BAR; PG8_SCHED;
;             PG8_STAGE(PG8_SB(0, 1), b2 + hstepB, voffB);
;             PG8_WAIT_V(6); PG8_BAR; PG8_MMA(1, 1, At, B1); PG8_BAR;
;             PG8_LDB(B0, 1, 0); PG8_SCHED; PG8_LDA(At, 1, 0); PG8_STAGE(PG8_SA(0, 1), a2 + hstepA, voffA);
;             PG8_WAIT_L(8); PG8_BAR; PG8_WAIT_L(0); PG8_MMA(0, 0, At, B0); PG8_BAR; PG8_SCHED;
;             PG8_LDB(B1, 1, 1); PG8_STAGE(PG8_SB(1, 0), b3, voffB);
;             PG8_BAR; PG8_WAIT_L(0); PG8_MMA(0, 1, At, B1); PG8_BAR;
;             PG8_LDA(At, 1, 1); PG8_STAGE(PG8_SA(1, 0), a3, voffA);
;             PG8_BAR; PG8_WAIT_L(0); PG8_MMA(1, 0, At, B0); PG8_BAR; PG8_SCHED;
;             PG8_STAGE(PG8_SB(1, 1), b3 + hstepB, voffB);
;             PG8_WAIT_V(6); PG8_BAR; PG8_MMA(1, 1, At, B1); PG8_BAR;
;     __device__ __forceinline__ void operator()(const f32x4 (&acc)[2][2][4][2], const Unit& u, int wr, int wc, int fr, int fq) const {
;         const int row0 = u.pm * 256 + wr * 64 + fr; const int col0 = u.pn * 256 + wc * 32 + 8 * fq;
; #pragma unroll
;         for (int ai = 0; ai < 2; ++ai) {
;             u32x4 gv[4][2], yv[4][2];
; #pragma unroll
;             for (int m = 0; m < 4; ++m)
; #pragma unroll
;                 for (int bj = 0; bj < 2; ++bj) {
;                     const int row = row0 + ai * 128 + m * 16, col = col0 + bj * 128;
	s_waitcnt lgkmcnt(0)
	v_mfma_f32_16x16x32_bf16 v[60:63], v[144:147], v[166:169], v[60:63]
	v_mfma_f32_16x16x32_bf16 v[56:59], v[158:161], v[166:169], v[56:59]
	v_mfma_f32_16x16x32_bf16 v[48:51], v[144:147], v[174:177], v[48:51]
	v_mfma_f32_16x16x32_bf16 v[40:43], v[158:161], v[174:177], v[40:43]
	v_mfma_f32_16x16x32_bf16 v[32:35], v[144:147], v[184:187], v[32:35]
	v_mfma_f32_16x16x32_bf16 v[24:27], v[158:161], v[184:187], v[24:27]
	v_mfma_f32_16x16x32_bf16 v[16:19], v[144:147], v[192:195], v[16:19]
	v_mfma_f32_16x16x32_bf16 v[8:11], v[158:161], v[192:195], v[8:11]
	v_mfma_f32_16x16x32_bf16 v[60:63], v[154:157], v[170:173], v[60:63]
	v_mfma_f32_16x16x32_bf16 v[56:59], v[162:165], v[170:173], v[56:59]
	v_mfma_f32_16x16x32_bf16 v[48:51], v[154:157], v[180:183], v[48:51]
	v_mfma_f32_16x16x32_bf16 v[40:43], v[162:165], v[180:183], v[40:43]
	v_mfma_f32_16x16x32_bf16 v[32:35], v[154:157], v[188:191], v[32:35]
	v_mfma_f32_16x16x32_bf16 v[24:27], v[162:165], v[188:191], v[24:27]
	v_mfma_f32_16x16x32_bf16 v[16:19], v[154:157], v[196:199], v[16:19]
	v_mfma_f32_16x16x32_bf16 v[8:11], v[162:165], v[196:199], v[8:11]
	s_barrier
	s_add_u32 s22, s22, 0x20080
	s_addc_u32 s23, s23, 0
	s_add_i32 s24, s24, s31
	s_mov_b32 m0, s24
	v_lshl_add_u64 v[144:145], s[22:23], 0, v[130:131]
	global_load_lds_dwordx4 v[144:145], off
	s_add_i32 m0, s24, 0x2000
	v_lshl_add_u64 v[144:145], s[22:23], 0, v[134:135]
	global_load_lds_dwordx4 v[144:145], off
	s_waitcnt vmcnt(6)
	s_barrier
	v_mfma_f32_16x16x32_bf16 v[52:55], v[200:203], v[166:169], v[52:55]
	v_mfma_f32_16x16x32_bf16 v[44:47], v[208:211], v[166:169], v[44:47]
	v_mfma_f32_16x16x32_bf16 v[36:39], v[200:203], v[174:177], v[36:39]
	v_mfma_f32_16x16x32_bf16 v[28:31], v[208:211], v[174:177], v[28:31]
	v_mfma_f32_16x16x32_bf16 v[20:23], v[200:203], v[184:187], v[20:23]
	v_mfma_f32_16x16x32_bf16 v[12:15], v[208:211], v[184:187], v[12:15]
	v_mfma_f32_16x16x32_bf16 v[4:7], v[200:203], v[192:195], v[4:7]
	v_mfma_f32_16x16x32_bf16 v[0:3], v[208:211], v[192:195], v[0:3]
	v_mfma_f32_16x16x32_bf16 v[52:55], v[204:207], v[170:173], v[52:55]
	v_mfma_f32_16x16x32_bf16 v[44:47], v[212:215], v[170:173], v[44:47]
	v_mfma_f32_16x16x32_bf16 v[36:39], v[204:207], v[180:183], v[36:39]
	v_mfma_f32_16x16x32_bf16 v[28:31], v[212:215], v[180:183], v[28:31]
	v_mfma_f32_16x16x32_bf16 v[20:23], v[204:207], v[188:191], v[20:23]
	v_mfma_f32_16x16x32_bf16 v[12:15], v[212:215], v[188:191], v[12:15]
	v_mfma_f32_16x16x32_bf16 v[4:7], v[204:207], v[196:199], v[4:7]
	v_mfma_f32_16x16x32_bf16 v[0:3], v[212:215], v[196:199], v[0:3]
	s_add_i32 s46, s46, 2
	s_add_u32 s20, s20, 0x100
	s_addc_u32 s21, s21, 0
	s_add_u32 s44, s44, 0x100
	s_addc_u32 s45, s45, 0
	s_cmp_gt_u32 s46, 5
	s_barrier
	s_cbranch_scc0 .LBB0_577
	v_lshl_add_u32 v146, s18, 8, v148
	v_lshl_or_b32 v144, s41, 8, v150
	v_ashrrev_i32_e32 v147, 31, v146
	v_or_b32_e32 v170, 16, v146
	v_ashrrev_i32_e32 v145, 31, v144
	v_lshlrev_b64 v[154:155], 12, v[146:147]
	v_ashrrev_i32_e32 v171, 31, v170
	v_lshl_add_u64 v[154:155], s[4:5], 0, v[154:155]
	v_lshlrev_b64 v[144:145], 1, v[144:145]
	v_lshlrev_b64 v[162:163], 12, v[170:171]
	v_lshl_add_u64 v[158:159], v[154:155], 0, v[144:145]
	v_lshl_add_u64 v[162:163], s[4:5], 0, v[162:163]
	global_load_dwordx4 v[154:157], v[158:159], off
	s_nop 0
	global_load_dwordx4 v[158:161], v[158:159], off offset:256
	v_lshl_add_u64 v[166:167], v[162:163], 0, v[144:145]
	global_load_dwordx4 v[162:165], v[166:167], off
	v_or_b32_e32 v188, 32, v146
	global_load_dwordx4 v[166:169], v[166:167], off offset:256
	v_or_b32_e32 v190, 48, v146
	v_ashrrev_i32_e32 v189, 31, v188
	v_ashrrev_i32_e32 v191, 31, v190
	v_lshlrev_b64 v[174:175], 12, v[188:189]
	v_lshlrev_b64 v[176:177], 12, v[190:191]
	v_lshlrev_b64 v[172:173], 11, v[146:147]
	v_lshlrev_b64 v[192:193], 11, v[170:171]
	v_lshl_add_u64 v[170:171], s[4:5], 0, v[174:175]
	v_lshl_add_u64 v[174:175], s[4:5], 0, v[176:177]
	v_lshl_add_u64 v[172:173], s[2:3], 0, v[172:173]
	v_lshl_add_u64 v[176:177], v[170:171], 0, v[144:145]
	v_lshl_add_u64 v[184:185], v[174:175], 0, v[144:145]
	v_lshl_add_u64 v[194:195], v[172:173], 0, v[144:145]
	global_load_dwordx4 v[170:173], v[176:177], off
	s_nop 0
	global_load_dwordx4 v[174:177], v[176:177], off offset:256
	s_nop 0
	global_load_dwordx4 v[180:183], v[184:185], off
	s_nop 0
	global_load_dwordx4 v[184:187], v[184:185], off offset:256
	s_and_b64 vcc, exec, s[0:1]
	s_mov_b32 s41, s10
	s_mov_b32 s18, s12
	s_mov_b64 s[22:23], s[16:17]
	s_mov_b64 s[20:21], s[14:15]
	s_waitcnt vmcnt(0)
; __device__ __forceinline__ unsigned cvt_pk_bf16(float lo, float hi) { unsigned r; asm volatile("v_cvt_pk_bf16_f32 %0, %1, %2" : "=v"(r) : "v"(lo), "v"(hi)); return r; }
; __device__ __forceinline__ float bflo(unsigned u) { return __uint_as_float(u << 16); }
; __device__ __forceinline__ float bfhi(unsigned u) { return __uint_as_float(u & 0xffff0000u); }
;     __device__ __forceinline__ void operator()(const f32x4 (&acc)[2][2][4][2], const Unit& u, int wr, int wc, int fr, int fq) const {
;     ...
;             for (int m = 0; m < 4; ++m)
; #pragma unroll
;                 for (int bj = 0; bj < 2; ++bj) {
;                     const int row = row0 + ai * 128 + m * 16, col = col0 + bj * 128;
;                     const u32x4 g = gv[m][bj];
;                     const f32x4 a0 = acc[ai][bj][m][0], a1 = acc[ai][bj][m][1];
;                     float r[8] = {a0[0] * bflo(g.x), a0[1] * bfhi(g.x), a0[2] * bflo(g.y), a0[3] * bfhi(g.y), a1[0] * bflo(g.z), a1[1] * bfhi(g.z), a1[2] * bflo(g.w), a1[3] * bfhi(g.w)};
;                     if (SECOND) { const u32x4 y = yv[m][bj];
;                         r[0] += bflo(y.x); r[1] += bfhi(y.x); r[2] += bflo(y.y); r[3] += bfhi(y.y); r[4] += bflo(y.z); r[5] += bfhi(y.z); r[6] += bflo(y.w); r[7] += bfhi(y.w); }
;                     u32x4 w; w.x = cvt_pk_bf16(r[0], r[1]); w.y = cvt_pk_bf16(r[2], r[3]); w.z = cvt_pk_bf16(r[4], r[5]); w.w = cvt_pk_bf16(r[6], r[7]);
;                     *(u32x4*)(Y + (size_t)row * 1024 + col) = w;
;                 }
	v_lshlrev_b32_e32 v147, 16, v154
	v_lshlrev_b32_e32 v201, 16, v160
	v_and_b32_e32 v154, 0xffff0000, v154
	v_lshlrev_b32_e32 v196, 16, v155
	v_and_b32_e32 v155, 0xffff0000, v155
	v_lshlrev_b32_e32 v197, 16, v156
	v_and_b32_e32 v156, 0xffff0000, v156
	v_lshlrev_b32_e32 v198, 16, v157
	v_and_b32_e32 v157, 0xffff0000, v157
	v_and_b32_e32 v160, 0xffff0000, v160
	v_lshlrev_b32_e32 v202, 16, v161
	v_and_b32_e32 v161, 0xffff0000, v161
	v_mul_f32_e32 v124, v124, v147
	v_mul_f32_e32 v147, v108, v201
	v_lshlrev_b32_e32 v108, 16, v162
	v_lshlrev_b32_e32 v199, 16, v158
	v_and_b32_e32 v158, 0xffff0000, v158
	v_lshlrev_b32_e32 v200, 16, v159
	v_and_b32_e32 v159, 0xffff0000, v159
	v_mul_f32_e32 v125, v125, v154
	v_mul_f32_e32 v127, v127, v155
	v_mul_f32_e32 v120, v120, v197
	v_mul_f32_e32 v121, v121, v156
	v_mul_f32_e32 v123, v123, v157
	v_mul_f32_e32 v154, v109, v160
	v_mul_f32_e32 v155, v110, v202
	v_mul_f32_e32 v156, v111, v161
	v_and_b32_e32 v109, 0xffff0000, v162
	v_lshlrev_b32_e32 v110, 16, v163
	v_and_b32_e32 v111, 0xffff0000, v163
	v_lshlrev_b32_e32 v157, 16, v164
	v_mul_f32_e32 v116, v116, v108
	v_cvt_pk_bf16_f32 v108, v124, v125
	v_mul_f32_e32 v126, v126, v196
	v_mul_f32_e32 v122, v122, v198
	v_mul_f32_e32 v112, v112, v199
	v_mul_f32_e32 v113, v113, v158
	v_mul_f32_e32 v115, v115, v159
	v_lshlrev_b32_e32 v159, 16, v165
	v_mul_f32_e32 v117, v117, v109
	v_mul_f32_e32 v118, v118, v110
	v_mul_f32_e32 v119, v119, v111
	v_cvt_pk_bf16_f32 v109, v126, v127
	v_cvt_pk_bf16_f32 v110, v120, v121
	v_cvt_pk_bf16_f32 v111, v122, v123
	v_mul_f32_e32 v120, v104, v157
	global_store_dwordx4 v[194:195], v[108:111], off
	v_and_b32_e32 v104, 0xffff0000, v165
	v_mul_f32_e32 v114, v114, v200
	v_cvt_pk_bf16_f32 v108, v112, v113
	v_and_b32_e32 v158, 0xffff0000, v164
	v_cvt_pk_bf16_f32 v109, v114, v115
	v_cvt_pk_bf16_f32 v110, v147, v154
	v_cvt_pk_bf16_f32 v111, v155, v156
	global_store_dwordx4 v[194:195], v[108:111], off offset:256
	v_mul_f32_e32 v107, v107, v104
	v_mul_f32_e32 v121, v105, v158
	v_mul_f32_e32 v108, v106, v159
	v_cvt_pk_bf16_f32 v104, v116, v117
	v_cvt_pk_bf16_f32 v105, v118, v119
	v_cvt_pk_bf16_f32 v106, v120, v121
	v_cvt_pk_bf16_f32 v107, v108, v107
	v_lshl_add_u64 v[108:109], s[2:3], 0, v[192:193]
	v_lshl_add_u64 v[108:109], v[108:109], 0, v[144:145]
	global_store_dwordx4 v[108:109], v[104:107], off
	s_nop 1
	v_lshlrev_b32_e32 v104, 16, v166
	v_mul_f32_e32 v100, v100, v104
	v_and_b32_e32 v104, 0xffff0000, v166
	v_mul_f32_e32 v101, v101, v104
	v_lshlrev_b32_e32 v104, 16, v167
	v_mul_f32_e32 v102, v102, v104
	v_and_b32_e32 v104, 0xffff0000, v167
	v_mul_f32_e32 v103, v103, v104
	v_lshlrev_b32_e32 v104, 16, v168
	v_mul_f32_e32 v104, v92, v104
	v_and_b32_e32 v92, 0xffff0000, v168
	v_mul_f32_e32 v105, v93, v92
	v_lshlrev_b32_e32 v92, 16, v169
	v_mul_f32_e32 v106, v94, v92
	v_and_b32_e32 v92, 0xffff0000, v169
	v_mul_f32_e32 v95, v95, v92
	v_cvt_pk_bf16_f32 v92, v100, v101
	v_cvt_pk_bf16_f32 v93, v102, v103
	v_cvt_pk_bf16_f32 v94, v104, v105
	v_cvt_pk_bf16_f32 v95, v106, v95
	global_store_dwordx4 v[108:109], v[92:95], off offset:256
	v_add_u32_e32 v102, 0xb0, v146
	v_ashrrev_i32_e32 v103, 31, v102
	v_lshlrev_b32_e32 v94, 16, v170
	v_mul_f32_e32 v94, v96, v94
	v_lshlrev_b32_e32 v96, 16, v171
	v_and_b32_e32 v95, 0xffff0000, v170
	v_mul_f32_e32 v96, v98, v96
	v_lshlrev_b32_e32 v98, 16, v172
	v_mul_f32_e32 v95, v97, v95
	v_and_b32_e32 v97, 0xffff0000, v171
	v_mul_f32_e32 v98, v88, v98
	v_and_b32_e32 v88, 0xffff0000, v172
	v_lshlrev_b64 v[92:93], 11, v[188:189]
	v_mul_f32_e32 v97, v99, v97
	v_mul_f32_e32 v99, v89, v88
	v_lshlrev_b32_e32 v88, 16, v173
	v_mul_f32_e32 v100, v90, v88
	v_and_b32_e32 v88, 0xffff0000, v173
	v_lshl_add_u64 v[92:93], s[2:3], 0, v[92:93]
	v_mul_f32_e32 v91, v91, v88
	v_cvt_pk_bf16_f32 v88, v94, v95
	v_lshl_add_u64 v[92:93], v[92:93], 0, v[144:145]
	v_cvt_pk_bf16_f32 v89, v96, v97
	v_cvt_pk_bf16_f32 v90, v98, v99
	v_cvt_pk_bf16_f32 v91, v100, v91
	global_store_dwordx4 v[92:93], v[88:91], off
	v_add_u32_e32 v96, 0x80, v146
	v_ashrrev_i32_e32 v97, 31, v96
	v_lshlrev_b32_e32 v88, 16, v174
	v_mul_f32_e32 v84, v84, v88
	v_and_b32_e32 v88, 0xffff0000, v174
	v_mul_f32_e32 v85, v85, v88
	v_lshlrev_b32_e32 v88, 16, v175
	v_mul_f32_e32 v86, v86, v88
	v_and_b32_e32 v88, 0xffff0000, v175
	v_mul_f32_e32 v87, v87, v88
	v_lshlrev_b32_e32 v88, 16, v176
	v_mul_f32_e32 v88, v76, v88
	v_and_b32_e32 v76, 0xffff0000, v176
	v_mul_f32_e32 v89, v77, v76
	v_lshlrev_b32_e32 v76, 16, v177
	v_mul_f32_e32 v90, v78, v76
	v_and_b32_e32 v76, 0xffff0000, v177
	v_mul_f32_e32 v79, v79, v76
	v_cvt_pk_bf16_f32 v76, v84, v85
	v_cvt_pk_bf16_f32 v77, v86, v87
	v_cvt_pk_bf16_f32 v78, v88, v89
	v_cvt_pk_bf16_f32 v79, v90, v79
	global_store_dwordx4 v[92:93], v[76:79], off offset:256
	v_add_u32_e32 v98, 0x90, v146
	v_ashrrev_i32_e32 v99, 31, v98
	v_lshlrev_b32_e32 v78, 16, v180
	v_mul_f32_e32 v78, v80, v78
	v_lshlrev_b32_e32 v80, 16, v181
	v_and_b32_e32 v79, 0xffff0000, v180
	v_mul_f32_e32 v80, v82, v80
	v_lshlrev_b32_e32 v82, 16, v182
	v_mul_f32_e32 v79, v81, v79
	v_and_b32_e32 v81, 0xffff0000, v181
	v_mul_f32_e32 v82, v72, v82
	v_and_b32_e32 v72, 0xffff0000, v182
	v_lshlrev_b64 v[76:77], 11, v[190:191]
	v_mul_f32_e32 v81, v83, v81
	v_mul_f32_e32 v83, v73, v72
	v_lshlrev_b32_e32 v72, 16, v183
	v_mul_f32_e32 v84, v74, v72
	v_and_b32_e32 v72, 0xffff0000, v183
	v_lshl_add_u64 v[76:77], s[2:3], 0, v[76:77]
	v_mul_f32_e32 v75, v75, v72
	v_cvt_pk_bf16_f32 v72, v78, v79
	v_lshl_add_u64 v[76:77], v[76:77], 0, v[144:145]
	v_cvt_pk_bf16_f32 v73, v80, v81
	v_cvt_pk_bf16_f32 v74, v82, v83
	v_cvt_pk_bf16_f32 v75, v84, v75
	global_store_dwordx4 v[76:77], v[72:75], off
	v_add_u32_e32 v100, 0xa0, v146
; __device__ __forceinline__ unsigned cvt_pk_bf16(float lo, float hi) { unsigned r; asm volatile("v_cvt_pk_bf16_f32 %0, %1, %2" : "=v"(r) : "v"(lo), "v"(hi)); return r; }
; __device__ __forceinline__ float bflo(unsigned u) { return __uint_as_float(u << 16); }
; __device__ __forceinline__ float bfhi(unsigned u) { return __uint_as_float(u & 0xffff0000u); }
;     __device__ __forceinline__ void operator()(const f32x4 (&acc)[2][2][4][2], const Unit& u, int wr, int wc, int fr, int fq) const {
;     ...
;         for (int ai = 0; ai < 2; ++ai) {
;             u32x4 gv[4][2], yv[4][2];
; #pragma unroll
;             for (int m = 0; m < 4; ++m)
; #pragma unroll
;                 for (int bj = 0; bj < 2; ++bj) {
;                     const int row = row0 + ai * 128 + m * 16, col = col0 + bj * 128;
;                     gv[m][bj] = *(const u32x4*)(gates + (size_t)row * 2048 + SECOND * 1024 + col);
;                     if (SECOND) yv[m][bj] = *(const u32x4*)(Y + (size_t)row * 1024 + col);
;                 }
; #pragma unroll
;             for (int m = 0; m < 4; ++m)
; #pragma unroll
;                 for (int bj = 0; bj < 2; ++bj) {
;                     const int row = row0 + ai * 128 + m * 16, col = col0 + bj * 128;
;                     const u32x4 g = gv[m][bj];
;                     const f32x4 a0 = acc[ai][bj][m][0], a1 = acc[ai][bj][m][1];
;                     float r[8] = {a0[0] * bflo(g.x), a0[1] * bfhi(g.x), a0[2] * bflo(g.y), a0[3] * bfhi(g.y), a1[0] * bflo(g.z), a1[1] * bfhi(g.z), a1[2] * bflo(g.w), a1[3] * bfhi(g.w)};
;                     if (SECOND) { const u32x4 y = yv[m][bj];
;                         r[0] += bflo(y.x); r[1] += bfhi(y.x); r[2] += bflo(y.y); r[3] += bfhi(y.y); r[4] += bflo(y.z); r[5] += bfhi(y.z); r[6] += bflo(y.w); r[7] += bfhi(y.w); }
;                     u32x4 w; w.x = cvt_pk_bf16(r[0], r[1]); w.y = cvt_pk_bf16(r[2], r[3]); w.z = cvt_pk_bf16(r[4], r[5]); w.w = cvt_pk_bf16(r[6], r[7]);
;                     *(u32x4*)(Y + (size_t)row * 1024 + col) = w;
	v_ashrrev_i32_e32 v101, 31, v100
	v_lshlrev_b32_e32 v72, 16, v184
	v_mul_f32_e32 v68, v68, v72
	v_and_b32_e32 v72, 0xffff0000, v184
	v_mul_f32_e32 v69, v69, v72
	v_lshlrev_b32_e32 v72, 16, v185
	v_mul_f32_e32 v70, v70, v72
	v_and_b32_e32 v72, 0xffff0000, v185
	v_mul_f32_e32 v71, v71, v72
	v_lshlrev_b32_e32 v72, 16, v186
	v_mul_f32_e32 v72, v64, v72
	v_and_b32_e32 v64, 0xffff0000, v186
	v_mul_f32_e32 v73, v65, v64
	v_lshlrev_b32_e32 v64, 16, v187
	v_mul_f32_e32 v74, v66, v64
	v_and_b32_e32 v64, 0xffff0000, v187
	v_mul_f32_e32 v67, v67, v64
	v_cvt_pk_bf16_f32 v64, v68, v69
	v_cvt_pk_bf16_f32 v65, v70, v71
	v_cvt_pk_bf16_f32 v66, v72, v73
	v_cvt_pk_bf16_f32 v67, v74, v67
	global_store_dwordx4 v[76:77], v[64:67], off offset:256
	v_lshlrev_b64 v[72:73], 12, v[98:99]
	v_lshl_add_u64 v[72:73], s[4:5], 0, v[72:73]
	v_lshlrev_b64 v[64:65], 12, v[96:97]
	v_lshl_add_u64 v[64:65], s[4:5], 0, v[64:65]
	v_lshl_add_u64 v[68:69], v[64:65], 0, v[144:145]
	global_load_dwordx4 v[64:67], v[68:69], off
	s_nop 0
	global_load_dwordx4 v[68:71], v[68:69], off offset:256
	v_lshl_add_u64 v[76:77], v[72:73], 0, v[144:145]
	global_load_dwordx4 v[72:75], v[76:77], off
	s_nop 0
	global_load_dwordx4 v[76:79], v[76:77], off offset:256
	v_lshlrev_b64 v[80:81], 12, v[100:101]
	v_lshl_add_u64 v[80:81], s[4:5], 0, v[80:81]
	v_lshl_add_u64 v[84:85], v[80:81], 0, v[144:145]
	global_load_dwordx4 v[80:83], v[84:85], off
	s_nop 0
	global_load_dwordx4 v[84:87], v[84:85], off offset:256
	v_lshlrev_b64 v[88:89], 12, v[102:103]
	v_lshl_add_u64 v[88:89], s[4:5], 0, v[88:89]
	v_lshl_add_u64 v[92:93], v[88:89], 0, v[144:145]
	global_load_dwordx4 v[88:91], v[92:93], off
	s_nop 0
	global_load_dwordx4 v[92:95], v[92:93], off offset:256
	v_lshlrev_b64 v[96:97], 11, v[96:97]
	s_waitcnt vmcnt(0)
; __device__ __forceinline__ unsigned cvt_pk_bf16(float lo, float hi) { unsigned r; asm volatile("v_cvt_pk_bf16_f32 %0, %1, %2" : "=v"(r) : "v"(lo), "v"(hi)); return r; }
; __device__ __forceinline__ float bflo(unsigned u) { return __uint_as_float(u << 16); }
; __device__ __forceinline__ float bfhi(unsigned u) { return __uint_as_float(u & 0xffff0000u); }
; #define PG8_WAIT_V(n) asm volatile("s_waitcnt vmcnt(" #n ")" ::: "memory")
; #define PG8_BAR __builtin_amdgcn_s_barrier()
; template <class Epi, class Sched>
; __device__ __forceinline__ void gemm_phase(const int wv, LAS unsigned char* lds, const Gemm g, const Sched& S, const Epi& E) {
;     ...
;     PG8_WAIT_V(0);
;     if (wr == 0) PG8_BAR;
;     PG8_BAR;
;     __device__ __forceinline__ void operator()(const f32x4 (&acc)[2][2][4][2], const Unit& u, int wr, int wc, int fr, int fq) const {
;     ...
;             for (int m = 0; m < 4; ++m)
; #pragma unroll
;                 for (int bj = 0; bj < 2; ++bj) {
;                     const int row = row0 + ai * 128 + m * 16, col = col0 + bj * 128;
;                     const u32x4 g = gv[m][bj];
;                     const f32x4 a0 = acc[ai][bj][m][0], a1 = acc[ai][bj][m][1];
;                     float r[8] = {a0[0] * bflo(g.x), a0[1] * bfhi(g.x), a0[2] * bflo(g.y), a0[3] * bfhi(g.y), a1[0] * bflo(g.z), a1[1] * bfhi(g.z), a1[2] * bflo(g.w), a1[3] * bfhi(g.w)};
;                     if (SECOND) { const u32x4 y = yv[m][bj];
;                         r[0] += bflo(y.x); r[1] += bfhi(y.x); r[2] += bflo(y.y); r[3] += bfhi(y.y); r[4] += bflo(y.z); r[5] += bfhi(y.z); r[6] += bflo(y.w); r[7] += bfhi(y.w); }
;                     u32x4 w; w.x = cvt_pk_bf16(r[0], r[1]); w.y = cvt_pk_bf16(r[2], r[3]); w.z = cvt_pk_bf16(r[4], r[5]); w.w = cvt_pk_bf16(r[6], r[7]);
;                     *(u32x4*)(Y + (size_t)row * 1024 + col) = w;
;                 }
	v_lshlrev_b32_e32 v104, 16, v64
	v_and_b32_e32 v64, 0xffff0000, v64
	v_mul_f32_e32 v61, v61, v64
	v_lshlrev_b32_e32 v64, 16, v65
	v_mul_f32_e32 v62, v62, v64
	v_and_b32_e32 v64, 0xffff0000, v65
	v_mul_f32_e32 v63, v63, v64
	v_lshlrev_b32_e32 v64, 16, v66
	v_mul_f32_e32 v64, v56, v64
	v_and_b32_e32 v56, 0xffff0000, v66
	v_mul_f32_e32 v65, v57, v56
	v_lshlrev_b32_e32 v56, 16, v67
	v_mul_f32_e32 v60, v60, v104
	v_mul_f32_e32 v66, v58, v56
	v_and_b32_e32 v56, 0xffff0000, v67
	v_mul_f32_e32 v59, v59, v56
	v_cvt_pk_bf16_f32 v56, v60, v61
	v_lshl_add_u64 v[60:61], s[2:3], 0, v[96:97]
	v_lshl_add_u64 v[60:61], v[60:61], 0, v[144:145]
	v_cvt_pk_bf16_f32 v57, v62, v63
	v_cvt_pk_bf16_f32 v58, v64, v65
	v_cvt_pk_bf16_f32 v59, v66, v59
	global_store_dwordx4 v[60:61], v[56:59], off
	s_nop 1
	v_lshlrev_b32_e32 v56, 16, v68
	v_mul_f32_e32 v52, v52, v56
	v_and_b32_e32 v56, 0xffff0000, v68
	v_mul_f32_e32 v53, v53, v56
	v_lshlrev_b32_e32 v56, 16, v69
	v_mul_f32_e32 v54, v54, v56
	v_and_b32_e32 v56, 0xffff0000, v69
	v_mul_f32_e32 v55, v55, v56
	v_lshlrev_b32_e32 v56, 16, v70
	v_mul_f32_e32 v56, v44, v56
	v_and_b32_e32 v44, 0xffff0000, v70
	v_mul_f32_e32 v57, v45, v44
	v_lshlrev_b32_e32 v44, 16, v71
	v_mul_f32_e32 v58, v46, v44
	v_and_b32_e32 v44, 0xffff0000, v71
	v_mul_f32_e32 v47, v47, v44
	v_cvt_pk_bf16_f32 v44, v52, v53
	v_cvt_pk_bf16_f32 v45, v54, v55
	v_cvt_pk_bf16_f32 v46, v56, v57
	v_cvt_pk_bf16_f32 v47, v58, v47
	global_store_dwordx4 v[60:61], v[44:47], off offset:256
	s_nop 1
	v_lshlrev_b32_e32 v46, 16, v72
	v_mul_f32_e32 v46, v48, v46
	v_lshlrev_b32_e32 v48, 16, v73
	v_and_b32_e32 v47, 0xffff0000, v72
	v_mul_f32_e32 v48, v50, v48
	v_lshlrev_b32_e32 v50, 16, v74
	v_mul_f32_e32 v47, v49, v47
	v_and_b32_e32 v49, 0xffff0000, v73
	v_mul_f32_e32 v50, v40, v50
	v_and_b32_e32 v40, 0xffff0000, v74
	v_lshlrev_b64 v[44:45], 11, v[98:99]
	v_mul_f32_e32 v49, v51, v49
	v_mul_f32_e32 v51, v41, v40
	v_lshlrev_b32_e32 v40, 16, v75
	v_mul_f32_e32 v52, v42, v40
	v_and_b32_e32 v40, 0xffff0000, v75
	v_lshl_add_u64 v[44:45], s[2:3], 0, v[44:45]
	v_mul_f32_e32 v43, v43, v40
	v_cvt_pk_bf16_f32 v40, v46, v47
	v_lshl_add_u64 v[44:45], v[44:45], 0, v[144:145]
	v_cvt_pk_bf16_f32 v41, v48, v49
	v_cvt_pk_bf16_f32 v42, v50, v51
	v_cvt_pk_bf16_f32 v43, v52, v43
	global_store_dwordx4 v[44:45], v[40:43], off
	s_nop 1
	v_lshlrev_b32_e32 v40, 16, v76
	v_mul_f32_e32 v36, v36, v40
	v_and_b32_e32 v40, 0xffff0000, v76
	v_mul_f32_e32 v37, v37, v40
	v_lshlrev_b32_e32 v40, 16, v77
	v_mul_f32_e32 v38, v38, v40
	v_and_b32_e32 v40, 0xffff0000, v77
	v_mul_f32_e32 v39, v39, v40
	v_lshlrev_b32_e32 v40, 16, v78
	v_mul_f32_e32 v40, v28, v40
	v_and_b32_e32 v28, 0xffff0000, v78
	v_mul_f32_e32 v41, v29, v28
	v_lshlrev_b32_e32 v28, 16, v79
	v_mul_f32_e32 v42, v30, v28
	v_and_b32_e32 v28, 0xffff0000, v79
	v_mul_f32_e32 v31, v31, v28
	v_cvt_pk_bf16_f32 v28, v36, v37
	v_cvt_pk_bf16_f32 v29, v38, v39
	v_cvt_pk_bf16_f32 v30, v40, v41
	v_cvt_pk_bf16_f32 v31, v42, v31
	global_store_dwordx4 v[44:45], v[28:31], off offset:256
	s_nop 1
	v_lshlrev_b32_e32 v30, 16, v80
	v_mul_f32_e32 v30, v32, v30
	v_lshlrev_b32_e32 v32, 16, v81
	v_and_b32_e32 v31, 0xffff0000, v80
	v_mul_f32_e32 v32, v34, v32
	v_lshlrev_b32_e32 v34, 16, v82
	v_mul_f32_e32 v31, v33, v31
	v_and_b32_e32 v33, 0xffff0000, v81
	v_mul_f32_e32 v34, v24, v34
	v_and_b32_e32 v24, 0xffff0000, v82
	v_lshlrev_b64 v[28:29], 11, v[100:101]
	v_mul_f32_e32 v33, v35, v33
	v_mul_f32_e32 v35, v25, v24
	v_lshlrev_b32_e32 v24, 16, v83
	v_mul_f32_e32 v36, v26, v24
	v_and_b32_e32 v24, 0xffff0000, v83
	v_lshl_add_u64 v[28:29], s[2:3], 0, v[28:29]
	v_mul_f32_e32 v27, v27, v24
	v_cvt_pk_bf16_f32 v24, v30, v31
	v_lshl_add_u64 v[28:29], v[28:29], 0, v[144:145]
	v_cvt_pk_bf16_f32 v25, v32, v33
	v_cvt_pk_bf16_f32 v26, v34, v35
	v_cvt_pk_bf16_f32 v27, v36, v27
	global_store_dwordx4 v[28:29], v[24:27], off
	s_nop 1
	v_lshlrev_b32_e32 v24, 16, v84
	v_mul_f32_e32 v20, v20, v24
	v_and_b32_e32 v24, 0xffff0000, v84
	v_mul_f32_e32 v21, v21, v24
	v_lshlrev_b32_e32 v24, 16, v85
	v_mul_f32_e32 v22, v22, v24
	v_and_b32_e32 v24, 0xffff0000, v85
	v_mul_f32_e32 v23, v23, v24
	v_lshlrev_b32_e32 v24, 16, v86
	v_mul_f32_e32 v24, v12, v24
	v_and_b32_e32 v12, 0xffff0000, v86
	v_mul_f32_e32 v25, v13, v12
	v_lshlrev_b32_e32 v12, 16, v87
	v_mul_f32_e32 v26, v14, v12
	v_and_b32_e32 v12, 0xffff0000, v87
	v_mul_f32_e32 v15, v15, v12
	v_cvt_pk_bf16_f32 v12, v20, v21
	v_cvt_pk_bf16_f32 v13, v22, v23
	v_cvt_pk_bf16_f32 v14, v24, v25
	v_cvt_pk_bf16_f32 v15, v26, v15
	global_store_dwordx4 v[28:29], v[12:15], off offset:256
	s_nop 1
	v_lshlrev_b32_e32 v14, 16, v88
	v_mul_f32_e32 v14, v16, v14
	v_lshlrev_b32_e32 v16, 16, v89
	v_and_b32_e32 v15, 0xffff0000, v88
	v_mul_f32_e32 v16, v18, v16
	v_lshlrev_b32_e32 v18, 16, v90
	v_mul_f32_e32 v15, v17, v15
	v_and_b32_e32 v17, 0xffff0000, v89
	v_mul_f32_e32 v18, v8, v18
	v_and_b32_e32 v8, 0xffff0000, v90
	v_lshlrev_b64 v[12:13], 11, v[102:103]
	v_mul_f32_e32 v17, v19, v17
	v_mul_f32_e32 v19, v9, v8
	v_lshlrev_b32_e32 v8, 16, v91
	v_mul_f32_e32 v20, v10, v8
	v_and_b32_e32 v8, 0xffff0000, v91
	v_lshl_add_u64 v[12:13], s[2:3], 0, v[12:13]
	v_mul_f32_e32 v11, v11, v8
	v_cvt_pk_bf16_f32 v8, v14, v15
	v_lshl_add_u64 v[12:13], v[12:13], 0, v[144:145]
	v_cvt_pk_bf16_f32 v9, v16, v17
	v_cvt_pk_bf16_f32 v10, v18, v19
	v_cvt_pk_bf16_f32 v11, v20, v11
	global_store_dwordx4 v[12:13], v[8:11], off
	s_nop 1
	v_lshlrev_b32_e32 v8, 16, v92
	v_mul_f32_e32 v4, v4, v8
	v_and_b32_e32 v8, 0xffff0000, v92
	v_mul_f32_e32 v5, v5, v8
	v_lshlrev_b32_e32 v8, 16, v93
	v_mul_f32_e32 v6, v6, v8
	v_and_b32_e32 v8, 0xffff0000, v93
	v_mul_f32_e32 v7, v7, v8
	v_lshlrev_b32_e32 v8, 16, v94
	v_mul_f32_e32 v8, v0, v8
	v_and_b32_e32 v0, 0xffff0000, v94
	v_mul_f32_e32 v9, v1, v0
	v_lshlrev_b32_e32 v0, 16, v95
	v_mul_f32_e32 v10, v2, v0
	v_and_b32_e32 v0, 0xffff0000, v95
	v_mul_f32_e32 v3, v3, v0
	v_cvt_pk_bf16_f32 v0, v4, v5
	v_cvt_pk_bf16_f32 v1, v6, v7
	v_cvt_pk_bf16_f32 v2, v8, v9
	v_cvt_pk_bf16_f32 v3, v10, v3
	global_store_dwordx4 v[12:13], v[0:3], off offset:256
	s_cbranch_vccz .LBB0_570
	s_waitcnt vmcnt(0)
	s_cmpk_gt_u32 s26, 0xff
	s_cbranch_scc1 .LBB0_581
	s_barrier

; #define PG8_STAGE(bufoff, gbase, voff) do { _Pragma("unroll") for (int _i = 0; _i < 2; ++_i) \
;         __builtin_amdgcn_global_load_lds((const unsigned*)((const char*)(gbase) + (voff)[_i]), (LAS unsigned*)(lds + (bufoff) + ldsw + _i * 8192), 16, 0, 0); } while (0)
; #define PG8_LDA(dst, b, h) do { _Pragma("unroll") for (int m = 0; m < 4; ++m) _Pragma("unroll") for (int k = 0; k < 2; ++k) dst[m][k] = *(const LAS bf16x8*)(lds + PG8_SA(b, h) + aoff + m * 2048 + k * 1024); } while (0)
; #define PG8_WAIT_V(n) asm volatile("s_waitcnt vmcnt(" #n ")" ::: "memory")
; template <class Epi, class Sched>
; __device__ __forceinline__ void gemm_phase(const int wv, LAS unsigned char* lds, const Gemm g, const Sched& S, const Epi& E) {
;     ...
;         for (int t = 0; t < nt; t += 2) {
;             const bool last = (t == nt - 2);
;             const char* a1 = cA + (size_t)(t + 1) * kstepA;
;             const char* a2 = last ? nA : cA + (size_t)(t + 2) * kstepA; const char* b2 = last ? nB : cB + (size_t)(t + 2) * kstep;
;             const char* a3 = a2 + kstepA; const char* b3 = b2 + kstep;
;             if (last && has_next) S.a_ready(nxt);
;             PG8_LDB(B0, 0, 0); PG8_SCHED; PG8_LDA(At, 0, 0); PG8_STAGE(PG8_SA(1, 1), a1 + hstepA, voffA);
;             PG8_WAIT_L(8); PG8_BAR; PG8_WAIT_L(0); PG8_MMA(0, 0, At, B0); PG8_BAR; PG8_SCHED;
;             PG8_LDB(B1, 0, 1); PG8_STAGE(PG8_SB(0, 0), b2, voffB);
;             PG8_BAR; PG8_WAIT_L(0); PG8_MMA(0, 1, At, B1); PG8_BAR;
;             PG8_LDA(At, 0, 1); PG8_STAGE(PG8_SA(0, 0), a2, voffA);
;             PG8_BAR; PG8_WAIT_L(0); PG8_MMA(1, 0, At, B0); PG8_BAR; PG8_SCHED;
;             PG8_STAGE(PG8_SB(0, 1), b2 + hstepB, voffB);
;             PG8_WAIT_V(6); PG8_BAR; PG8_MMA(1, 1, At, B1); PG8_BAR;
;             PG8_LDB(B0, 1, 0); PG8_SCHED; PG8_LDA(At, 1, 0); PG8_STAGE(PG8_SA(0, 1), a2 + hstepA, voffA);
;             PG8_WAIT_L(8); PG8_BAR; PG8_WAIT_L(0); PG8_MMA(0, 0, At, B0); PG8_BAR; PG8_SCHED;
;             PG8_LDB(B1, 1, 1); PG8_STAGE(PG8_SB(1, 0), b3, voffB);
;             PG8_BAR; PG8_WAIT_L(0); PG8_MMA(0, 1, At, B1); PG8_BAR;
;             PG8_LDA(At, 1, 1); PG8_STAGE(PG8_SA(1, 0), a3, voffA);
;             PG8_BAR; PG8_WAIT_L(0); PG8_MMA(1, 0, At, B0); PG8_BAR; PG8_SCHED;
;             PG8_STAGE(PG8_SB(1, 1), b3 + hstepB, voffB);
;             PG8_WAIT_V(6); PG8_BAR; PG8_MMA(1, 1, At, B1); PG8_BAR;
.LBB0_597:
	ds_read_b128 v[128:131], v175
	ds_read_b128 v[132:135], v175 offset:1024
	ds_read_b128 v[136:139], v175 offset:2048
	ds_read_b128 v[140:143], v175 offset:3072
	s_add_u32 s20, s18, 0xfff80080
	s_addc_u32 s21, s19, -1
	s_cmp_eq_u32 s44, 28
	s_cselect_b32 s23, s11, s21
	s_cselect_b32 s22, s40, s20
	s_cselect_b32 s21, s9, s43
	s_cselect_b32 s20, s41, s42
	v_lshl_add_u64 v[200:201], s[18:19], 0, v[156:157]
	s_add_i32 m0, s17, 0xc000
	ds_read_b128 v[144:147], v176
	ds_read_b128 v[164:167], v176 offset:1024
	ds_read_b128 v[168:171], v176 offset:2048
	ds_read_b128 v[180:183], v176 offset:3072
	ds_read_b128 v[184:187], v176 offset:4096
	ds_read_b128 v[188:191], v176 offset:5120
	ds_read_b128 v[192:195], v176 offset:6144
	ds_read_b128 v[196:199], v176 offset:7168
	global_load_lds_dwordx4 v[200:201], off
	s_add_i32 m0, s17, 0xe000
	v_lshl_add_u64 v[200:201], s[18:19], 0, v[158:159]
	global_load_lds_dwordx4 v[200:201], off
	s_waitcnt lgkmcnt(8)
	s_barrier
	s_waitcnt lgkmcnt(0)
	v_mfma_f32_16x16x32_bf16 v[124:127], v[128:131], v[144:147], v[124:127]
	v_mfma_f32_16x16x32_bf16 v[120:123], v[136:139], v[144:147], v[120:123]
	v_mfma_f32_16x16x32_bf16 v[108:111], v[128:131], v[168:171], v[108:111]
	v_mfma_f32_16x16x32_bf16 v[104:107], v[136:139], v[168:171], v[104:107]
	v_mfma_f32_16x16x32_bf16 v[92:95], v[128:131], v[184:187], v[92:95]
	v_mfma_f32_16x16x32_bf16 v[88:91], v[136:139], v[184:187], v[88:91]
	v_mfma_f32_16x16x32_bf16 v[76:79], v[128:131], v[192:195], v[76:79]
	v_mfma_f32_16x16x32_bf16 v[72:75], v[136:139], v[192:195], v[72:75]
	v_mfma_f32_16x16x32_bf16 v[124:127], v[132:135], v[164:167], v[124:127]
	v_mfma_f32_16x16x32_bf16 v[120:123], v[140:143], v[164:167], v[120:123]
	v_mfma_f32_16x16x32_bf16 v[108:111], v[132:135], v[180:183], v[108:111]
	v_mfma_f32_16x16x32_bf16 v[104:107], v[140:143], v[180:183], v[104:107]
	v_mfma_f32_16x16x32_bf16 v[92:95], v[132:135], v[188:191], v[92:95]
	v_mfma_f32_16x16x32_bf16 v[88:91], v[140:143], v[188:191], v[88:91]
	v_mfma_f32_16x16x32_bf16 v[76:79], v[132:135], v[196:199], v[76:79]
	v_mfma_f32_16x16x32_bf16 v[72:75], v[140:143], v[196:199], v[72:75]
	s_barrier
	s_add_i32 s45, s37, s29
	v_lshl_add_u64 v[216:217], s[20:21], 0, v[150:151]
	s_mov_b32 m0, s45
	ds_read_b128 v[200:203], v177
	ds_read_b128 v[204:207], v177 offset:1024
	ds_read_b128 v[208:211], v177 offset:2048
	ds_read_b128 v[212:215], v177 offset:3072
	global_load_lds_dwordx4 v[216:217], off
	s_add_i32 m0, s45, 0x2000
	v_lshl_add_u64 v[218:219], s[20:21], 0, v[154:155]
	global_load_lds_dwordx4 v[218:219], off
	s_barrier
	s_waitcnt lgkmcnt(0)
	v_mfma_f32_16x16x32_bf16 v[116:119], v[200:203], v[144:147], v[116:119]
	v_mfma_f32_16x16x32_bf16 v[112:115], v[208:211], v[144:147], v[112:115]
	v_mfma_f32_16x16x32_bf16 v[100:103], v[200:203], v[168:171], v[100:103]
	v_mfma_f32_16x16x32_bf16 v[96:99], v[208:211], v[168:171], v[96:99]
	v_mfma_f32_16x16x32_bf16 v[84:87], v[200:203], v[184:187], v[84:87]
	v_mfma_f32_16x16x32_bf16 v[80:83], v[208:211], v[184:187], v[80:83]
	v_mfma_f32_16x16x32_bf16 v[68:71], v[200:203], v[192:195], v[68:71]
	v_mfma_f32_16x16x32_bf16 v[64:67], v[208:211], v[192:195], v[64:67]
	v_mfma_f32_16x16x32_bf16 v[116:119], v[204:207], v[164:167], v[116:119]
	v_mfma_f32_16x16x32_bf16 v[112:115], v[212:215], v[164:167], v[112:115]
	v_mfma_f32_16x16x32_bf16 v[100:103], v[204:207], v[180:183], v[100:103]
	v_mfma_f32_16x16x32_bf16 v[96:99], v[212:215], v[180:183], v[96:99]
	v_mfma_f32_16x16x32_bf16 v[84:87], v[204:207], v[188:191], v[84:87]
	v_mfma_f32_16x16x32_bf16 v[80:83], v[212:215], v[188:191], v[80:83]
	v_mfma_f32_16x16x32_bf16 v[68:71], v[204:207], v[196:199], v[68:71]
	v_mfma_f32_16x16x32_bf16 v[64:67], v[212:215], v[196:199], v[64:67]
	s_mov_b32 m0, s17
	v_lshl_add_u64 v[220:221], s[22:23], 0, v[148:149]
	s_barrier
	ds_read_b128 v[144:147], v176 offset:16384
	ds_read_b128 v[164:167], v176 offset:17408
	ds_read_b128 v[168:171], v176 offset:18432
	ds_read_b128 v[180:183], v176 offset:19456
	ds_read_b128 v[184:187], v176 offset:20480
	ds_read_b128 v[188:191], v176 offset:21504
	ds_read_b128 v[192:195], v176 offset:22528
	ds_read_b128 v[196:199], v176 offset:23552
	global_load_lds_dwordx4 v[220:221], off
	s_mov_b32 m0, s30
	v_lshl_add_u64 v[222:223], s[22:23], 0, v[152:153]
	global_load_lds_dwordx4 v[222:223], off
	s_barrier
	s_waitcnt lgkmcnt(0)
	v_mfma_f32_16x16x32_bf16 v[60:63], v[128:131], v[144:147], v[60:63]
	v_mfma_f32_16x16x32_bf16 v[56:59], v[136:139], v[144:147], v[56:59]
	v_mfma_f32_16x16x32_bf16 v[44:47], v[128:131], v[168:171], v[44:47]
	v_mfma_f32_16x16x32_bf16 v[40:43], v[136:139], v[168:171], v[40:43]
	v_mfma_f32_16x16x32_bf16 v[28:31], v[128:131], v[184:187], v[28:31]
	v_mfma_f32_16x16x32_bf16 v[24:27], v[136:139], v[184:187], v[24:27]
	v_mfma_f32_16x16x32_bf16 v[12:15], v[128:131], v[192:195], v[12:15]
	v_mfma_f32_16x16x32_bf16 v[8:11], v[136:139], v[192:195], v[8:11]
	v_mfma_f32_16x16x32_bf16 v[60:63], v[132:135], v[164:167], v[60:63]
	v_mfma_f32_16x16x32_bf16 v[56:59], v[140:143], v[164:167], v[56:59]
	v_mfma_f32_16x16x32_bf16 v[44:47], v[132:135], v[180:183], v[44:47]
	v_mfma_f32_16x16x32_bf16 v[40:43], v[140:143], v[180:183], v[40:43]
	v_mfma_f32_16x16x32_bf16 v[28:31], v[132:135], v[188:191], v[28:31]
	v_mfma_f32_16x16x32_bf16 v[24:27], v[140:143], v[188:191], v[24:27]
	v_mfma_f32_16x16x32_bf16 v[12:15], v[132:135], v[196:199], v[12:15]
	v_mfma_f32_16x16x32_bf16 v[8:11], v[140:143], v[196:199], v[8:11]
	s_barrier
	s_add_u32 s46, s20, 0x80000
	s_addc_u32 s47, s21, 0
	s_add_i32 s45, s38, s29
	s_mov_b32 m0, s45
	v_lshl_add_u64 v[128:129], s[46:47], 0, v[150:151]
	global_load_lds_dwordx4 v[128:129], off
	s_add_i32 m0, s45, 0x2000
	v_lshl_add_u64 v[128:129], s[46:47], 0, v[154:155]
	global_load_lds_dwordx4 v[128:129], off
	s_waitcnt vmcnt(6)
	s_barrier
; #define PG8_STAGE(bufoff, gbase, voff) do { _Pragma("unroll") for (int _i = 0; _i < 2; ++_i) \
;         __builtin_amdgcn_global_load_lds((const unsigned*)((const char*)(gbase) + (voff)[_i]), (LAS unsigned*)(lds + (bufoff) + ldsw + _i * 8192), 16, 0, 0); } while (0)
; #define PG8_LDA(dst, b, h) do { _Pragma("unroll") for (int m = 0; m < 4; ++m) _Pragma("unroll") for (int k = 0; k < 2; ++k) dst[m][k] = *(const LAS bf16x8*)(lds + PG8_SA(b, h) + aoff + m * 2048 + k * 1024); } while (0)
; #define PG8_WAIT_V(n) asm volatile("s_waitcnt vmcnt(" #n ")" ::: "memory")
; template <class Epi, class Sched>
; __device__ __forceinline__ void gemm_phase(const int wv, LAS unsigned char* lds, const Gemm g, const Sched& S, const Epi& E) {
;     ...
;         for (int t = 0; t < nt; t += 2) {
;             const bool last = (t == nt - 2);
;             const char* a1 = cA + (size_t)(t + 1) * kstepA;
;             const char* a2 = last ? nA : cA + (size_t)(t + 2) * kstepA; const char* b2 = last ? nB : cB + (size_t)(t + 2) * kstep;
;             const char* a3 = a2 + kstepA; const char* b3 = b2 + kstep;
;             if (last && has_next) S.a_ready(nxt);
;             PG8_LDB(B0, 0, 0); PG8_SCHED; PG8_LDA(At, 0, 0); PG8_STAGE(PG8_SA(1, 1), a1 + hstepA, voffA);
;             PG8_WAIT_L(8); PG8_BAR; PG8_WAIT_L(0); PG8_MMA(0, 0, At, B0); PG8_BAR; PG8_SCHED;
;             PG8_LDB(B1, 0, 1); PG8_STAGE(PG8_SB(0, 0), b2, voffB);
;             PG8_BAR; PG8_WAIT_L(0); PG8_MMA(0, 1, At, B1); PG8_BAR;
;             PG8_LDA(At, 0, 1); PG8_STAGE(PG8_SA(0, 0), a2, voffA);
;             PG8_BAR; PG8_WAIT_L(0); PG8_MMA(1, 0, At, B0); PG8_BAR; PG8_SCHED;
;             PG8_STAGE(PG8_SB(0, 1), b2 + hstepB, voffB);
;             PG8_WAIT_V(6); PG8_BAR; PG8_MMA(1, 1, At, B1); PG8_BAR;
;             PG8_LDB(B0, 1, 0); PG8_SCHED; PG8_LDA(At, 1, 0); PG8_STAGE(PG8_SA(0, 1), a2 + hstepA, voffA);
;             PG8_WAIT_L(8); PG8_BAR; PG8_WAIT_L(0); PG8_MMA(0, 0, At, B0); PG8_BAR; PG8_SCHED;
;             PG8_LDB(B1, 1, 1); PG8_STAGE(PG8_SB(1, 0), b3, voffB);
;             PG8_BAR; PG8_WAIT_L(0); PG8_MMA(0, 1, At, B1); PG8_BAR;
;             PG8_LDA(At, 1, 1); PG8_STAGE(PG8_SA(1, 0), a3, voffA);
;             PG8_BAR; PG8_WAIT_L(0); PG8_MMA(1, 0, At, B0); PG8_BAR; PG8_SCHED;
;             PG8_STAGE(PG8_SB(1, 1), b3 + hstepB, voffB);
;             PG8_WAIT_V(6); PG8_BAR; PG8_MMA(1, 1, At, B1); PG8_BAR;
	v_mfma_f32_16x16x32_bf16 v[52:55], v[200:203], v[144:147], v[52:55]
	v_mfma_f32_16x16x32_bf16 v[48:51], v[208:211], v[144:147], v[48:51]
	v_mfma_f32_16x16x32_bf16 v[36:39], v[200:203], v[168:171], v[36:39]
	v_mfma_f32_16x16x32_bf16 v[32:35], v[208:211], v[168:171], v[32:35]
	v_mfma_f32_16x16x32_bf16 v[20:23], v[200:203], v[184:187], v[20:23]
	v_mfma_f32_16x16x32_bf16 v[16:19], v[208:211], v[184:187], v[16:19]
	v_mfma_f32_16x16x32_bf16 v[4:7], v[200:203], v[192:195], v[4:7]
	v_mfma_f32_16x16x32_bf16 v[0:3], v[208:211], v[192:195], v[0:3]
	v_mfma_f32_16x16x32_bf16 v[52:55], v[204:207], v[164:167], v[52:55]
	v_mfma_f32_16x16x32_bf16 v[48:51], v[212:215], v[164:167], v[48:51]
	v_mfma_f32_16x16x32_bf16 v[36:39], v[204:207], v[180:183], v[36:39]
	v_mfma_f32_16x16x32_bf16 v[32:35], v[212:215], v[180:183], v[32:35]
	v_mfma_f32_16x16x32_bf16 v[20:23], v[204:207], v[188:191], v[20:23]
	v_mfma_f32_16x16x32_bf16 v[16:19], v[212:215], v[188:191], v[16:19]
	v_mfma_f32_16x16x32_bf16 v[4:7], v[204:207], v[196:199], v[4:7]
	v_mfma_f32_16x16x32_bf16 v[0:3], v[212:215], v[196:199], v[0:3]
	s_add_i32 s45, 0, 0x18000
	v_add_u32_e32 v140, s45, v173
	s_barrier
	ds_read_b128 v[128:131], v140
	ds_read_b128 v[132:135], v140 offset:1024
	ds_read_b128 v[136:139], v140 offset:2048
	ds_read_b128 v[140:143], v140 offset:3072
	s_add_u32 s22, s22, 0x80000
	s_addc_u32 s23, s23, 0
	s_mov_b32 m0, s31
	v_lshl_add_u64 v[200:201], s[22:23], 0, v[148:149]
	ds_read_b128 v[144:147], v176 offset:32768
	ds_read_b128 v[164:167], v176 offset:33792
	ds_read_b128 v[168:171], v176 offset:34816
	ds_read_b128 v[180:183], v176 offset:35840
	ds_read_b128 v[184:187], v176 offset:36864
	ds_read_b128 v[188:191], v176 offset:37888
	ds_read_b128 v[192:195], v176 offset:38912
	ds_read_b128 v[196:199], v176 offset:39936
	global_load_lds_dwordx4 v[200:201], off
	s_mov_b32 m0, s33
	v_lshl_add_u64 v[200:201], s[22:23], 0, v[152:153]
	global_load_lds_dwordx4 v[200:201], off
	s_waitcnt lgkmcnt(8)
	s_barrier
	s_waitcnt lgkmcnt(0)
	v_mfma_f32_16x16x32_bf16 v[124:127], v[128:131], v[144:147], v[124:127]
	v_mfma_f32_16x16x32_bf16 v[120:123], v[136:139], v[144:147], v[120:123]
	v_mfma_f32_16x16x32_bf16 v[108:111], v[128:131], v[168:171], v[108:111]
	v_mfma_f32_16x16x32_bf16 v[104:107], v[136:139], v[168:171], v[104:107]
	v_mfma_f32_16x16x32_bf16 v[92:95], v[128:131], v[184:187], v[92:95]
	v_mfma_f32_16x16x32_bf16 v[88:91], v[136:139], v[184:187], v[88:91]
	v_mfma_f32_16x16x32_bf16 v[76:79], v[128:131], v[192:195], v[76:79]
	v_mfma_f32_16x16x32_bf16 v[72:75], v[136:139], v[192:195], v[72:75]
	v_mfma_f32_16x16x32_bf16 v[124:127], v[132:135], v[164:167], v[124:127]
	v_mfma_f32_16x16x32_bf16 v[120:123], v[140:143], v[164:167], v[120:123]
	v_mfma_f32_16x16x32_bf16 v[108:111], v[132:135], v[180:183], v[108:111]
	v_mfma_f32_16x16x32_bf16 v[104:107], v[140:143], v[180:183], v[104:107]
	v_mfma_f32_16x16x32_bf16 v[92:95], v[132:135], v[188:191], v[92:95]
	v_mfma_f32_16x16x32_bf16 v[88:91], v[140:143], v[188:191], v[88:91]
	v_mfma_f32_16x16x32_bf16 v[76:79], v[132:135], v[196:199], v[76:79]
	v_mfma_f32_16x16x32_bf16 v[72:75], v[140:143], v[196:199], v[72:75]
	s_barrier
	s_add_i32 s22, 0, 0x1c000
	s_add_i32 s23, s45, s29
	v_add_u32_e32 v212, s22, v173
	v_lshl_add_u64 v[216:217], v[216:217], 0, s[6:7]
	s_mov_b32 m0, s23
	ds_read_b128 v[200:203], v212
	ds_read_b128 v[204:207], v212 offset:1024
	ds_read_b128 v[208:211], v212 offset:2048
	ds_read_b128 v[212:215], v212 offset:3072
	global_load_lds_dwordx4 v[216:217], off
	s_add_i32 m0, s23, 0x2000
	v_lshl_add_u64 v[216:217], v[218:219], 0, s[6:7]
	global_load_lds_dwordx4 v[216:217], off
	s_barrier
	s_waitcnt lgkmcnt(0)
	v_mfma_f32_16x16x32_bf16 v[116:119], v[200:203], v[144:147], v[116:119]
	v_mfma_f32_16x16x32_bf16 v[112:115], v[208:211], v[144:147], v[112:115]
	v_mfma_f32_16x16x32_bf16 v[100:103], v[200:203], v[168:171], v[100:103]
	v_mfma_f32_16x16x32_bf16 v[96:99], v[208:211], v[168:171], v[96:99]
	v_mfma_f32_16x16x32_bf16 v[84:87], v[200:203], v[184:187], v[84:87]
	v_mfma_f32_16x16x32_bf16 v[80:83], v[208:211], v[184:187], v[80:83]
	v_mfma_f32_16x16x32_bf16 v[68:71], v[200:203], v[192:195], v[68:71]
	v_mfma_f32_16x16x32_bf16 v[64:67], v[208:211], v[192:195], v[64:67]
	v_mfma_f32_16x16x32_bf16 v[116:119], v[204:207], v[164:167], v[116:119]
	v_mfma_f32_16x16x32_bf16 v[112:115], v[212:215], v[164:167], v[112:115]
	v_mfma_f32_16x16x32_bf16 v[100:103], v[204:207], v[180:183], v[100:103]
	v_mfma_f32_16x16x32_bf16 v[96:99], v[212:215], v[180:183], v[96:99]
	v_mfma_f32_16x16x32_bf16 v[84:87], v[204:207], v[188:191], v[84:87]
	v_mfma_f32_16x16x32_bf16 v[80:83], v[212:215], v[188:191], v[80:83]
	v_mfma_f32_16x16x32_bf16 v[68:71], v[204:207], v[196:199], v[68:71]
	v_mfma_f32_16x16x32_bf16 v[64:67], v[212:215], v[196:199], v[64:67]
	s_mov_b32 m0, s35
	v_lshl_add_u64 v[216:217], v[220:221], 0, s[6:7]
	s_barrier
	ds_read_b128 v[144:147], v176 offset:49152
	ds_read_b128 v[164:167], v176 offset:50176
	ds_read_b128 v[168:171], v176 offset:51200
	ds_read_b128 v[180:183], v176 offset:52224
	ds_read_b128 v[184:187], v176 offset:53248
	ds_read_b128 v[188:191], v176 offset:54272
	ds_read_b128 v[192:195], v176 offset:55296
	ds_read_b128 v[196:199], v176 offset:56320
	global_load_lds_dwordx4 v[216:217], off
	s_mov_b32 m0, s36
	v_lshl_add_u64 v[216:217], v[222:223], 0, s[6:7]
	global_load_lds_dwordx4 v[216:217], off
	s_barrier
; template <class Epi, class Sched>
; __device__ __forceinline__ void gemm_phase(const int wv, LAS unsigned char* lds, const Gemm g, const Sched& S, const Epi& E) {
;     ...
;         for (int t = 0; t < nt; t += 2) {
;             const bool last = (t == nt - 2);
;             const char* a1 = cA + (size_t)(t + 1) * kstepA;
;             const char* a2 = last ? nA : cA + (size_t)(t + 2) * kstepA; const char* b2 = last ? nB : cB + (size_t)(t + 2) * kstep;
;             const char* a3 = a2 + kstepA; const char* b3 = b2 + kstep;
;             if (last && has_next) S.a_ready(nxt);
;             PG8_LDB(B0, 0, 0); PG8_SCHED; PG8_LDA(At, 0, 0); PG8_STAGE(PG8_SA(1, 1), a1 + hstepA, voffA);
;             PG8_WAIT_L(8); PG8_BAR; PG8_WAIT_L(0); PG8_MMA(0, 0, At, B0); PG8_BAR; PG8_SCHED;
;             PG8_LDB(B1, 0, 1); PG8_STAGE(PG8_SB(0, 0), b2, voffB);
;             PG8_BAR; PG8_WAIT_L(0); PG8_MMA(0, 1, At, B1); PG8_BAR;
;             PG8_LDA(At, 0, 1); PG8_STAGE(PG8_SA(0, 0), a2, voffA);
;             PG8_BAR; PG8_WAIT_L(0); PG8_MMA(1, 0, At, B0); PG8_BAR; PG8_SCHED;
;             PG8_STAGE(PG8_SB(0, 1), b2 + hstepB, voffB);
;             PG8_WAIT_V(6); PG8_BAR; PG8_MMA(1, 1, At, B1); PG8_BAR;
;             PG8_LDB(B0, 1, 0); PG8_SCHED; PG8_LDA(At, 1, 0); PG8_STAGE(PG8_SA(0, 1), a2 + hstepA, voffA);
;             PG8_WAIT_L(8); PG8_BAR; PG8_WAIT_L(0); PG8_MMA(0, 0, At, B0); PG8_BAR; PG8_SCHED;
;             PG8_LDB(B1, 1, 1); PG8_STAGE(PG8_SB(1, 0), b3, voffB);
;             PG8_BAR; PG8_WAIT_L(0); PG8_MMA(0, 1, At, B1); PG8_BAR;
;             PG8_LDA(At, 1, 1); PG8_STAGE(PG8_SA(1, 0), a3, voffA);
;             PG8_BAR; PG8_WAIT_L(0); PG8_MMA(1, 0, At, B0); PG8_BAR; PG8_SCHED;
;             PG8_STAGE(PG8_SB(1, 1), b3 + hstepB, voffB);
;             PG8_WAIT_V(6); PG8_BAR; PG8_MMA(1, 1, At, B1); PG8_BAR;
;     __device__ __forceinline__ void operator()(const f32x4 (&acc)[2][2][4][2], const Unit& u, int wr, int wc, int fr, int fq) const {
;         const int row0 = u.pm * 256 + wr * 64 + fr; const int col0 = u.pn * 256 + wc * 32 + 8 * fq;
; #pragma unroll
;         for (int ai = 0; ai < 2; ++ai) {
;             u32x4 gv[4][2], yv[4][2];
; #pragma unroll
;             for (int m = 0; m < 4; ++m)
; #pragma unroll
;                 for (int bj = 0; bj < 2; ++bj) {
;                     const int row = row0 + ai * 128 + m * 16, col = col0 + bj * 128;
	s_waitcnt lgkmcnt(0)
	v_mfma_f32_16x16x32_bf16 v[60:63], v[128:131], v[144:147], v[60:63]
	v_mfma_f32_16x16x32_bf16 v[56:59], v[136:139], v[144:147], v[56:59]
	v_mfma_f32_16x16x32_bf16 v[44:47], v[128:131], v[168:171], v[44:47]
	v_mfma_f32_16x16x32_bf16 v[40:43], v[136:139], v[168:171], v[40:43]
	v_mfma_f32_16x16x32_bf16 v[28:31], v[128:131], v[184:187], v[28:31]
	v_mfma_f32_16x16x32_bf16 v[24:27], v[136:139], v[184:187], v[24:27]
	v_mfma_f32_16x16x32_bf16 v[12:15], v[128:131], v[192:195], v[12:15]
	v_mfma_f32_16x16x32_bf16 v[8:11], v[136:139], v[192:195], v[8:11]
	v_mfma_f32_16x16x32_bf16 v[60:63], v[132:135], v[164:167], v[60:63]
	v_mfma_f32_16x16x32_bf16 v[56:59], v[140:143], v[164:167], v[56:59]
	v_mfma_f32_16x16x32_bf16 v[44:47], v[132:135], v[180:183], v[44:47]
	v_mfma_f32_16x16x32_bf16 v[40:43], v[140:143], v[180:183], v[40:43]
	v_mfma_f32_16x16x32_bf16 v[28:31], v[132:135], v[188:191], v[28:31]
	v_mfma_f32_16x16x32_bf16 v[24:27], v[140:143], v[188:191], v[24:27]
	v_mfma_f32_16x16x32_bf16 v[12:15], v[132:135], v[196:199], v[12:15]
	v_mfma_f32_16x16x32_bf16 v[8:11], v[140:143], v[196:199], v[8:11]
	s_barrier
	s_add_u32 s20, s20, 0x80080
	s_addc_u32 s21, s21, 0
	s_add_i32 s22, s22, s29
	s_mov_b32 m0, s22
	v_lshl_add_u64 v[128:129], s[20:21], 0, v[150:151]
	global_load_lds_dwordx4 v[128:129], off
	s_add_i32 m0, s22, 0x2000
	v_lshl_add_u64 v[128:129], s[20:21], 0, v[154:155]
	global_load_lds_dwordx4 v[128:129], off
	s_waitcnt vmcnt(6)
	s_barrier
	v_mfma_f32_16x16x32_bf16 v[52:55], v[200:203], v[144:147], v[52:55]
	v_mfma_f32_16x16x32_bf16 v[48:51], v[208:211], v[144:147], v[48:51]
	v_mfma_f32_16x16x32_bf16 v[36:39], v[200:203], v[168:171], v[36:39]
	v_mfma_f32_16x16x32_bf16 v[32:35], v[208:211], v[168:171], v[32:35]
	v_mfma_f32_16x16x32_bf16 v[20:23], v[200:203], v[184:187], v[20:23]
	v_mfma_f32_16x16x32_bf16 v[16:19], v[208:211], v[184:187], v[16:19]
	v_mfma_f32_16x16x32_bf16 v[4:7], v[200:203], v[192:195], v[4:7]
	v_mfma_f32_16x16x32_bf16 v[0:3], v[208:211], v[192:195], v[0:3]
	v_mfma_f32_16x16x32_bf16 v[52:55], v[204:207], v[164:167], v[52:55]
	v_mfma_f32_16x16x32_bf16 v[48:51], v[212:215], v[164:167], v[48:51]
	v_mfma_f32_16x16x32_bf16 v[36:39], v[204:207], v[180:183], v[36:39]
	v_mfma_f32_16x16x32_bf16 v[32:35], v[212:215], v[180:183], v[32:35]
	v_mfma_f32_16x16x32_bf16 v[20:23], v[204:207], v[188:191], v[20:23]
	v_mfma_f32_16x16x32_bf16 v[16:19], v[212:215], v[188:191], v[16:19]
	v_mfma_f32_16x16x32_bf16 v[4:7], v[204:207], v[196:199], v[4:7]
	v_mfma_f32_16x16x32_bf16 v[0:3], v[212:215], v[196:199], v[0:3]
	s_add_i32 s44, s44, 2
	s_add_u32 s18, s18, 0x100
	s_addc_u32 s19, s19, 0
	s_add_u32 s42, s42, 0x100
	s_addc_u32 s43, s43, 0
	s_cmp_gt_u32 s44, 29
	s_barrier
	s_cbranch_scc0 .LBB0_597
	v_lshl_add_u32 v164, s16, 8, v172
	v_lshl_or_b32 v128, s39, 8, v174
	v_ashrrev_i32_e32 v165, 31, v164
	v_ashrrev_i32_e32 v129, 31, v128
	v_lshlrev_b64 v[130:131], 12, v[164:165]
	v_lshl_add_u64 v[130:131], s[4:5], 0, v[130:131]
	v_lshlrev_b64 v[166:167], 1, v[128:129]
	v_lshl_add_u64 v[128:129], v[130:131], 0, v[166:167]
	v_lshlrev_b64 v[130:131], 11, v[164:165]
	v_lshl_add_u64 v[130:131], s[2:3], 0, v[130:131]
	v_lshl_add_u64 v[224:225], v[130:131], 0, v[166:167]
	global_load_dwordx4 v[180:183], v[128:129], off offset:2048
	global_load_dwordx4 v[184:187], v[224:225], off
	global_load_dwordx4 v[188:191], v[128:129], off offset:2304
	global_load_dwordx4 v[192:195], v[224:225], off offset:256
	v_or_b32_e32 v128, 16, v164
	v_ashrrev_i32_e32 v129, 31, v128
	v_lshlrev_b64 v[134:135], 12, v[128:129]
	v_lshlrev_b64 v[128:129], 11, v[128:129]
	v_lshl_add_u64 v[134:135], s[4:5], 0, v[134:135]
	v_lshl_add_u64 v[128:129], s[2:3], 0, v[128:129]
	v_lshl_add_u64 v[134:135], v[134:135], 0, v[166:167]
	v_lshl_add_u64 v[226:227], v[128:129], 0, v[166:167]
	global_load_dwordx4 v[196:199], v[134:135], off offset:2048
	global_load_dwordx4 v[200:203], v[226:227], off
	v_or_b32_e32 v130, 32, v164
	v_or_b32_e32 v132, 48, v164
	v_ashrrev_i32_e32 v131, 31, v130
	v_ashrrev_i32_e32 v133, 31, v132
	v_lshlrev_b64 v[136:137], 12, v[130:131]
	v_lshlrev_b64 v[130:131], 11, v[130:131]
	v_lshlrev_b64 v[138:139], 12, v[132:133]
	v_lshlrev_b64 v[132:133], 11, v[132:133]
	v_lshl_add_u64 v[136:137], s[4:5], 0, v[136:137]
	v_lshl_add_u64 v[130:131], s[2:3], 0, v[130:131]
	v_lshl_add_u64 v[138:139], s[4:5], 0, v[138:139]
	v_lshl_add_u64 v[132:133], s[2:3], 0, v[132:133]
	v_lshl_add_u64 v[128:129], v[136:137], 0, v[166:167]
	v_lshl_add_u64 v[170:171], v[130:131], 0, v[166:167]
	v_lshl_add_u64 v[130:131], v[138:139], 0, v[166:167]
	v_lshl_add_u64 v[168:169], v[132:133], 0, v[166:167]
	global_load_dwordx4 v[204:207], v[134:135], off offset:2304
	global_load_dwordx4 v[208:211], v[226:227], off offset:256
	global_load_dwordx4 v[212:215], v[128:129], off offset:2048
	global_load_dwordx4 v[216:219], v[128:129], off offset:2304
	global_load_dwordx4 v[220:223], v[170:171], off
	global_load_dwordx4 v[144:147], v[170:171], off offset:256
	global_load_dwordx4 v[140:143], v[130:131], off offset:2048
	global_load_dwordx4 v[132:135], v[130:131], off offset:2304
	global_load_dwordx4 v[136:139], v[168:169], off
	s_nop 0
	global_load_dwordx4 v[128:131], v[168:169], off offset:256
	s_and_b64 vcc, exec, s[0:1]
	s_mov_b32 s39, s8
	s_mov_b32 s16, s10
	s_mov_b64 s[20:21], s[14:15]
	s_mov_b64 s[18:19], s[12:13]
	s_waitcnt vmcnt(0)
; __device__ __forceinline__ unsigned cvt_pk_bf16(float lo, float hi) { unsigned r; asm volatile("v_cvt_pk_bf16_f32 %0, %1, %2" : "=v"(r) : "v"(lo), "v"(hi)); return r; }
; __device__ __forceinline__ float bflo(unsigned u) { return __uint_as_float(u << 16); }
; __device__ __forceinline__ float bfhi(unsigned u) { return __uint_as_float(u & 0xffff0000u); }
;     __device__ __forceinline__ void operator()(const f32x4 (&acc)[2][2][4][2], const Unit& u, int wr, int wc, int fr, int fq) const {
;     ...
;             for (int m = 0; m < 4; ++m)
; #pragma unroll
;                 for (int bj = 0; bj < 2; ++bj) {
;                     const int row = row0 + ai * 128 + m * 16, col = col0 + bj * 128;
;                     const u32x4 g = gv[m][bj];
;                     const f32x4 a0 = acc[ai][bj][m][0], a1 = acc[ai][bj][m][1];
;                     float r[8] = {a0[0] * bflo(g.x), a0[1] * bfhi(g.x), a0[2] * bflo(g.y), a0[3] * bfhi(g.y), a1[0] * bflo(g.z), a1[1] * bfhi(g.z), a1[2] * bflo(g.w), a1[3] * bfhi(g.w)};
;                     if (SECOND) { const u32x4 y = yv[m][bj];
;                         r[0] += bflo(y.x); r[1] += bfhi(y.x); r[2] += bflo(y.y); r[3] += bfhi(y.y); r[4] += bflo(y.z); r[5] += bfhi(y.z); r[6] += bflo(y.w); r[7] += bfhi(y.w); }
;                     u32x4 w; w.x = cvt_pk_bf16(r[0], r[1]); w.y = cvt_pk_bf16(r[2], r[3]); w.z = cvt_pk_bf16(r[4], r[5]); w.w = cvt_pk_bf16(r[6], r[7]);
;                     *(u32x4*)(Y + (size_t)row * 1024 + col) = w;
;                 }
	v_lshlrev_b32_e32 v231, 16, v184
	v_lshlrev_b32_e32 v235, 16, v188
	v_lshlrev_b32_e32 v239, 16, v192
	v_and_b32_e32 v188, 0xffff0000, v188
	v_fmac_f32_e32 v239, v116, v235
	v_and_b32_e32 v116, 0xffff0000, v192
	v_lshlrev_b32_e32 v165, 16, v180
	v_and_b32_e32 v180, 0xffff0000, v180
	v_lshlrev_b32_e32 v229, 16, v182
	v_and_b32_e32 v184, 0xffff0000, v184
	v_lshlrev_b32_e32 v233, 16, v186
	v_lshlrev_b32_e32 v236, 16, v189
	v_fmac_f32_e32 v116, v117, v188
	v_lshlrev_b32_e32 v117, 16, v193
	v_lshlrev_b32_e32 v228, 16, v181
	v_and_b32_e32 v181, 0xffff0000, v181
	v_and_b32_e32 v182, 0xffff0000, v182
	v_lshlrev_b32_e32 v230, 16, v183
	v_and_b32_e32 v183, 0xffff0000, v183
	v_lshlrev_b32_e32 v232, 16, v185
	v_and_b32_e32 v185, 0xffff0000, v185
	v_and_b32_e32 v186, 0xffff0000, v186
	v_lshlrev_b32_e32 v234, 16, v187
	v_and_b32_e32 v187, 0xffff0000, v187
	v_and_b32_e32 v189, 0xffff0000, v189
	v_fmac_f32_e32 v231, v124, v165
	v_fmac_f32_e32 v184, v125, v180
	v_fmac_f32_e32 v233, v120, v229
	v_cvt_pk_bf16_f32 v120, v231, v184
	v_fmac_f32_e32 v117, v118, v236
	v_and_b32_e32 v118, 0xffff0000, v193
	v_lshlrev_b32_e32 v237, 16, v190
	v_and_b32_e32 v190, 0xffff0000, v190
	v_fmac_f32_e32 v232, v126, v228
	v_fmac_f32_e32 v185, v127, v181
	v_fmac_f32_e32 v186, v121, v182
	v_fmac_f32_e32 v234, v122, v230
	v_fmac_f32_e32 v187, v123, v183
	v_cvt_pk_bf16_f32 v121, v232, v185
	v_cvt_pk_bf16_f32 v122, v233, v186
	v_cvt_pk_bf16_f32 v123, v234, v187
	global_store_dwordx4 v[224:225], v[120:123], off
	v_fmac_f32_e32 v118, v119, v189
	v_lshlrev_b32_e32 v119, 16, v194
	v_and_b32_e32 v120, 0xffff0000, v194
	v_lshlrev_b32_e32 v238, 16, v191
	v_and_b32_e32 v191, 0xffff0000, v191
	v_fmac_f32_e32 v119, v112, v237
	v_fmac_f32_e32 v120, v113, v190
	v_lshlrev_b32_e32 v121, 16, v195
	v_and_b32_e32 v122, 0xffff0000, v195
	v_cvt_pk_bf16_f32 v112, v239, v116
	v_fmac_f32_e32 v121, v114, v238
	v_fmac_f32_e32 v122, v115, v191
	v_cvt_pk_bf16_f32 v113, v117, v118
	v_cvt_pk_bf16_f32 v114, v119, v120
	v_cvt_pk_bf16_f32 v115, v121, v122
	global_store_dwordx4 v[224:225], v[112:115], off offset:256
	v_lshlrev_b32_e32 v120, 16, v200
	v_lshlrev_b32_e32 v116, 16, v198
	v_lshlrev_b32_e32 v112, 16, v196
	v_and_b32_e32 v113, 0xffff0000, v196
	v_fmac_f32_e32 v120, v108, v112
	v_and_b32_e32 v108, 0xffff0000, v200
	v_lshlrev_b32_e32 v114, 16, v197
	v_fmac_f32_e32 v108, v109, v113
	v_lshlrev_b32_e32 v109, 16, v201
	v_and_b32_e32 v115, 0xffff0000, v197
	v_fmac_f32_e32 v109, v110, v114
	v_and_b32_e32 v110, 0xffff0000, v201
	v_and_b32_e32 v117, 0xffff0000, v198
	v_fmac_f32_e32 v110, v111, v115
	v_lshlrev_b32_e32 v111, 16, v202
	v_and_b32_e32 v112, 0xffff0000, v202
	v_lshlrev_b32_e32 v118, 16, v199
	v_and_b32_e32 v119, 0xffff0000, v199
	v_fmac_f32_e32 v111, v104, v116
	v_fmac_f32_e32 v112, v105, v117
	v_lshlrev_b32_e32 v113, 16, v203
	v_and_b32_e32 v114, 0xffff0000, v203
	v_cvt_pk_bf16_f32 v104, v120, v108
	v_fmac_f32_e32 v113, v106, v118
	v_fmac_f32_e32 v114, v107, v119
	v_cvt_pk_bf16_f32 v105, v109, v110
	v_cvt_pk_bf16_f32 v106, v111, v112
	v_cvt_pk_bf16_f32 v107, v113, v114
	global_store_dwordx4 v[226:227], v[104:107], off
	v_lshlrev_b32_e32 v112, 16, v208
	v_lshlrev_b32_e32 v108, 16, v206
	v_lshlrev_b32_e32 v104, 16, v204
	v_and_b32_e32 v105, 0xffff0000, v204
	v_fmac_f32_e32 v112, v100, v104
	v_and_b32_e32 v100, 0xffff0000, v208
	v_lshlrev_b32_e32 v106, 16, v205
	v_fmac_f32_e32 v100, v101, v105
	v_lshlrev_b32_e32 v101, 16, v209
	v_and_b32_e32 v107, 0xffff0000, v205
	v_fmac_f32_e32 v101, v102, v106
	v_and_b32_e32 v102, 0xffff0000, v209
	v_and_b32_e32 v109, 0xffff0000, v206
	v_fmac_f32_e32 v102, v103, v107
	v_lshlrev_b32_e32 v103, 16, v210
	v_and_b32_e32 v104, 0xffff0000, v210
	v_lshlrev_b32_e32 v110, 16, v207
	v_and_b32_e32 v111, 0xffff0000, v207
	v_fmac_f32_e32 v103, v96, v108
	v_fmac_f32_e32 v104, v97, v109
	v_lshlrev_b32_e32 v105, 16, v211
	v_and_b32_e32 v106, 0xffff0000, v211
	v_cvt_pk_bf16_f32 v96, v112, v100
	v_fmac_f32_e32 v105, v98, v110
	v_fmac_f32_e32 v106, v99, v111
	v_cvt_pk_bf16_f32 v97, v101, v102
	v_cvt_pk_bf16_f32 v98, v103, v104
	v_cvt_pk_bf16_f32 v99, v105, v106
	global_store_dwordx4 v[226:227], v[96:99], off offset:256
	v_lshlrev_b32_e32 v104, 16, v220
	v_lshlrev_b32_e32 v100, 16, v214
	v_lshlrev_b32_e32 v96, 16, v212
	v_and_b32_e32 v97, 0xffff0000, v212
	v_fmac_f32_e32 v104, v92, v96
	v_and_b32_e32 v92, 0xffff0000, v220
	v_lshlrev_b32_e32 v98, 16, v213
	v_fmac_f32_e32 v92, v93, v97
	v_lshlrev_b32_e32 v93, 16, v221
	v_and_b32_e32 v99, 0xffff0000, v213
	v_fmac_f32_e32 v93, v94, v98
	v_and_b32_e32 v94, 0xffff0000, v221
	v_and_b32_e32 v101, 0xffff0000, v214
	v_fmac_f32_e32 v94, v95, v99
	v_lshlrev_b32_e32 v95, 16, v222
	v_and_b32_e32 v96, 0xffff0000, v222
	v_lshlrev_b32_e32 v102, 16, v215
	v_and_b32_e32 v103, 0xffff0000, v215
	v_fmac_f32_e32 v95, v88, v100
	v_fmac_f32_e32 v96, v89, v101
	v_lshlrev_b32_e32 v97, 16, v223
	v_and_b32_e32 v98, 0xffff0000, v223
	v_cvt_pk_bf16_f32 v88, v104, v92
	v_fmac_f32_e32 v97, v90, v102
	v_fmac_f32_e32 v98, v91, v103
	v_cvt_pk_bf16_f32 v89, v93, v94
	v_cvt_pk_bf16_f32 v90, v95, v96
	v_cvt_pk_bf16_f32 v91, v97, v98
	global_store_dwordx4 v[170:171], v[88:91], off
	v_lshlrev_b32_e32 v96, 16, v144
	v_lshlrev_b32_e32 v92, 16, v218
	v_lshlrev_b32_e32 v88, 16, v216
	v_and_b32_e32 v89, 0xffff0000, v216
	v_fmac_f32_e32 v96, v84, v88
	v_and_b32_e32 v84, 0xffff0000, v144
	v_lshlrev_b32_e32 v90, 16, v217
	v_fmac_f32_e32 v84, v85, v89
	v_lshlrev_b32_e32 v85, 16, v145
	v_and_b32_e32 v91, 0xffff0000, v217
	v_fmac_f32_e32 v85, v86, v90
	v_and_b32_e32 v86, 0xffff0000, v145
	v_and_b32_e32 v93, 0xffff0000, v218
	v_fmac_f32_e32 v86, v87, v91
	v_lshlrev_b32_e32 v87, 16, v146
; __device__ __forceinline__ unsigned cvt_pk_bf16(float lo, float hi) { unsigned r; asm volatile("v_cvt_pk_bf16_f32 %0, %1, %2" : "=v"(r) : "v"(lo), "v"(hi)); return r; }
; __device__ __forceinline__ float bflo(unsigned u) { return __uint_as_float(u << 16); }
; __device__ __forceinline__ float bfhi(unsigned u) { return __uint_as_float(u & 0xffff0000u); }
;     __device__ __forceinline__ void operator()(const f32x4 (&acc)[2][2][4][2], const Unit& u, int wr, int wc, int fr, int fq) const {
;     ...
;         for (int ai = 0; ai < 2; ++ai) {
;             u32x4 gv[4][2], yv[4][2];
; #pragma unroll
;             for (int m = 0; m < 4; ++m)
; #pragma unroll
;                 for (int bj = 0; bj < 2; ++bj) {
;                     const int row = row0 + ai * 128 + m * 16, col = col0 + bj * 128;
;                     gv[m][bj] = *(const u32x4*)(gates + (size_t)row * 2048 + SECOND * 1024 + col);
;                     if (SECOND) yv[m][bj] = *(const u32x4*)(Y + (size_t)row * 1024 + col);
;                 }
;     ...
;             for (int m = 0; m < 4; ++m)
; #pragma unroll
;                 for (int bj = 0; bj < 2; ++bj) {
;                     const int row = row0 + ai * 128 + m * 16, col = col0 + bj * 128;
;                     const u32x4 g = gv[m][bj];
;                     const f32x4 a0 = acc[ai][bj][m][0], a1 = acc[ai][bj][m][1];
;                     float r[8] = {a0[0] * bflo(g.x), a0[1] * bfhi(g.x), a0[2] * bflo(g.y), a0[3] * bfhi(g.y), a1[0] * bflo(g.z), a1[1] * bfhi(g.z), a1[2] * bflo(g.w), a1[3] * bfhi(g.w)};
;                     if (SECOND) { const u32x4 y = yv[m][bj];
;                         r[0] += bflo(y.x); r[1] += bfhi(y.x); r[2] += bflo(y.y); r[3] += bfhi(y.y); r[4] += bflo(y.z); r[5] += bfhi(y.z); r[6] += bflo(y.w); r[7] += bfhi(y.w); }
;                     u32x4 w; w.x = cvt_pk_bf16(r[0], r[1]); w.y = cvt_pk_bf16(r[2], r[3]); w.z = cvt_pk_bf16(r[4], r[5]); w.w = cvt_pk_bf16(r[6], r[7]);
;                     *(u32x4*)(Y + (size_t)row * 1024 + col) = w;
;                 }
	v_and_b32_e32 v88, 0xffff0000, v146
	v_lshlrev_b32_e32 v94, 16, v219
	v_and_b32_e32 v95, 0xffff0000, v219
	v_fmac_f32_e32 v87, v80, v92
	v_fmac_f32_e32 v88, v81, v93
	v_lshlrev_b32_e32 v89, 16, v147
	v_and_b32_e32 v90, 0xffff0000, v147
	v_cvt_pk_bf16_f32 v80, v96, v84
	v_fmac_f32_e32 v89, v82, v94
	v_fmac_f32_e32 v90, v83, v95
	v_cvt_pk_bf16_f32 v81, v85, v86
	v_cvt_pk_bf16_f32 v82, v87, v88
	v_cvt_pk_bf16_f32 v83, v89, v90
	global_store_dwordx4 v[170:171], v[80:83], off offset:256
	v_lshlrev_b32_e32 v88, 16, v136
	v_lshlrev_b32_e32 v84, 16, v142
	v_lshlrev_b32_e32 v80, 16, v140
	v_and_b32_e32 v81, 0xffff0000, v140
	v_fmac_f32_e32 v88, v76, v80
	v_and_b32_e32 v76, 0xffff0000, v136
	v_lshlrev_b32_e32 v82, 16, v141
	v_fmac_f32_e32 v76, v77, v81
	v_lshlrev_b32_e32 v77, 16, v137
	v_and_b32_e32 v83, 0xffff0000, v141
	v_fmac_f32_e32 v77, v78, v82
	v_and_b32_e32 v78, 0xffff0000, v137
	v_and_b32_e32 v85, 0xffff0000, v142
	v_fmac_f32_e32 v78, v79, v83
	v_lshlrev_b32_e32 v79, 16, v138
	v_and_b32_e32 v80, 0xffff0000, v138
	v_lshlrev_b32_e32 v86, 16, v143
	v_and_b32_e32 v87, 0xffff0000, v143
	v_fmac_f32_e32 v79, v72, v84
	v_fmac_f32_e32 v80, v73, v85
	v_lshlrev_b32_e32 v81, 16, v139
	v_and_b32_e32 v82, 0xffff0000, v139
	v_cvt_pk_bf16_f32 v72, v88, v76
	v_fmac_f32_e32 v81, v74, v86
	v_fmac_f32_e32 v82, v75, v87
	v_cvt_pk_bf16_f32 v73, v77, v78
	v_cvt_pk_bf16_f32 v74, v79, v80
	v_cvt_pk_bf16_f32 v75, v81, v82
	global_store_dwordx4 v[168:169], v[72:75], off
	v_lshlrev_b32_e32 v80, 16, v128
	v_lshlrev_b32_e32 v76, 16, v134
	v_lshlrev_b32_e32 v72, 16, v132
	v_and_b32_e32 v73, 0xffff0000, v132
	v_fmac_f32_e32 v80, v68, v72
	v_and_b32_e32 v68, 0xffff0000, v128
	v_lshlrev_b32_e32 v74, 16, v133
	v_fmac_f32_e32 v68, v69, v73
	v_lshlrev_b32_e32 v69, 16, v129
	v_and_b32_e32 v75, 0xffff0000, v133
	v_fmac_f32_e32 v69, v70, v74
	v_and_b32_e32 v70, 0xffff0000, v129
	v_fmac_f32_e32 v70, v71, v75
	v_lshlrev_b32_e32 v71, 16, v130
	v_and_b32_e32 v77, 0xffff0000, v134
	v_lshlrev_b32_e32 v78, 16, v135
	v_and_b32_e32 v79, 0xffff0000, v135
	v_fmac_f32_e32 v71, v64, v76
	v_and_b32_e32 v72, 0xffff0000, v130
	v_lshlrev_b32_e32 v73, 16, v131
	v_and_b32_e32 v74, 0xffff0000, v131
	v_cvt_pk_bf16_f32 v64, v80, v68
	v_fmac_f32_e32 v72, v65, v77
	v_fmac_f32_e32 v73, v66, v78
	v_fmac_f32_e32 v74, v67, v79
	v_cvt_pk_bf16_f32 v65, v69, v70
	v_cvt_pk_bf16_f32 v66, v71, v72
	v_cvt_pk_bf16_f32 v67, v73, v74
	global_store_dwordx4 v[168:169], v[64:67], off offset:256
	s_nop 1
	v_add_u32_e32 v64, 0x80, v164
	v_ashrrev_i32_e32 v65, 31, v64
	v_lshlrev_b64 v[66:67], 12, v[64:65]
	v_lshl_add_u64 v[66:67], s[4:5], 0, v[66:67]
	v_lshl_add_u64 v[66:67], v[66:67], 0, v[166:167]
	v_lshlrev_b64 v[64:65], 11, v[64:65]
	global_load_dwordx4 v[88:91], v[66:67], off offset:2048
	v_lshl_add_u64 v[64:65], s[2:3], 0, v[64:65]
	v_lshl_add_u64 v[132:133], v[64:65], 0, v[166:167]
	global_load_dwordx4 v[92:95], v[132:133], off
	global_load_dwordx4 v[96:99], v[66:67], off offset:2304
	global_load_dwordx4 v[100:103], v[132:133], off offset:256
	v_add_u32_e32 v64, 0x90, v164
	v_ashrrev_i32_e32 v65, 31, v64
	v_lshlrev_b64 v[66:67], 12, v[64:65]
	v_lshl_add_u64 v[66:67], s[4:5], 0, v[66:67]
	v_lshlrev_b64 v[64:65], 11, v[64:65]
	v_lshl_add_u64 v[64:65], s[2:3], 0, v[64:65]
	v_lshl_add_u64 v[66:67], v[66:67], 0, v[166:167]
	v_lshl_add_u64 v[134:135], v[64:65], 0, v[166:167]
	global_load_dwordx4 v[104:107], v[66:67], off offset:2048
	global_load_dwordx4 v[108:111], v[66:67], off offset:2304
	global_load_dwordx4 v[112:115], v[134:135], off
	global_load_dwordx4 v[116:119], v[134:135], off offset:256
	v_add_u32_e32 v64, 0xa0, v164
	v_ashrrev_i32_e32 v65, 31, v64
	v_lshlrev_b64 v[66:67], 12, v[64:65]
	v_lshl_add_u64 v[66:67], s[4:5], 0, v[66:67]
	v_lshlrev_b64 v[64:65], 11, v[64:65]
	v_lshl_add_u64 v[64:65], s[2:3], 0, v[64:65]
	v_lshl_add_u64 v[66:67], v[66:67], 0, v[166:167]
	v_lshl_add_u64 v[86:87], v[64:65], 0, v[166:167]
	global_load_dwordx4 v[120:123], v[66:67], off offset:2048
	global_load_dwordx4 v[124:127], v[66:67], off offset:2304
	global_load_dwordx4 v[128:131], v[86:87], off
	global_load_dwordx4 v[80:83], v[86:87], off offset:256
	v_add_u32_e32 v64, 0xb0, v164
	v_ashrrev_i32_e32 v65, 31, v64
	v_lshlrev_b64 v[66:67], 12, v[64:65]
	v_lshl_add_u64 v[66:67], s[4:5], 0, v[66:67]
	v_lshlrev_b64 v[64:65], 11, v[64:65]
	v_lshl_add_u64 v[64:65], s[2:3], 0, v[64:65]
	v_lshl_add_u64 v[66:67], v[66:67], 0, v[166:167]
	v_lshl_add_u64 v[84:85], v[64:65], 0, v[166:167]
	global_load_dwordx4 v[76:79], v[66:67], off offset:2048
	global_load_dwordx4 v[68:71], v[66:67], off offset:2304
	global_load_dwordx4 v[72:75], v[84:85], off
	s_nop 0
	global_load_dwordx4 v[64:67], v[84:85], off offset:256
	s_waitcnt vmcnt(0)
; __device__ __forceinline__ unsigned cvt_pk_bf16(float lo, float hi) { unsigned r; asm volatile("v_cvt_pk_bf16_f32 %0, %1, %2" : "=v"(r) : "v"(lo), "v"(hi)); return r; }
; __device__ __forceinline__ float bflo(unsigned u) { return __uint_as_float(u << 16); }
; __device__ __forceinline__ float bfhi(unsigned u) { return __uint_as_float(u & 0xffff0000u); }
;     __device__ __forceinline__ void operator()(const f32x4 (&acc)[2][2][4][2], const Unit& u, int wr, int wc, int fr, int fq) const {
;     ...
;             for (int m = 0; m < 4; ++m)
; #pragma unroll
;                 for (int bj = 0; bj < 2; ++bj) {
;                     const int row = row0 + ai * 128 + m * 16, col = col0 + bj * 128;
;                     const u32x4 g = gv[m][bj];
;                     const f32x4 a0 = acc[ai][bj][m][0], a1 = acc[ai][bj][m][1];
;                     float r[8] = {a0[0] * bflo(g.x), a0[1] * bfhi(g.x), a0[2] * bflo(g.y), a0[3] * bfhi(g.y), a1[0] * bflo(g.z), a1[1] * bfhi(g.z), a1[2] * bflo(g.w), a1[3] * bfhi(g.w)};
;                     if (SECOND) { const u32x4 y = yv[m][bj];
;                         r[0] += bflo(y.x); r[1] += bfhi(y.x); r[2] += bflo(y.y); r[3] += bfhi(y.y); r[4] += bflo(y.z); r[5] += bfhi(y.z); r[6] += bflo(y.w); r[7] += bfhi(y.w); }
;                     u32x4 w; w.x = cvt_pk_bf16(r[0], r[1]); w.y = cvt_pk_bf16(r[2], r[3]); w.z = cvt_pk_bf16(r[4], r[5]); w.w = cvt_pk_bf16(r[6], r[7]);
;                     *(u32x4*)(Y + (size_t)row * 1024 + col) = w;
;                 }
	v_lshlrev_b32_e32 v136, 16, v88
	v_lshlrev_b32_e32 v140, 16, v92
	v_and_b32_e32 v88, 0xffff0000, v88
	v_fmac_f32_e32 v140, v60, v136
	v_and_b32_e32 v60, 0xffff0000, v92
	v_lshlrev_b32_e32 v137, 16, v89
	v_fmac_f32_e32 v60, v61, v88
	v_lshlrev_b32_e32 v61, 16, v93
	v_and_b32_e32 v89, 0xffff0000, v89
	v_fmac_f32_e32 v61, v62, v137
	v_and_b32_e32 v62, 0xffff0000, v93
	v_lshlrev_b32_e32 v138, 16, v90
	v_and_b32_e32 v90, 0xffff0000, v90
	v_fmac_f32_e32 v62, v63, v89
	v_lshlrev_b32_e32 v63, 16, v94
	v_and_b32_e32 v88, 0xffff0000, v94
	v_lshlrev_b32_e32 v139, 16, v91
	v_and_b32_e32 v91, 0xffff0000, v91
	v_fmac_f32_e32 v63, v56, v138
	v_fmac_f32_e32 v88, v57, v90
	v_lshlrev_b32_e32 v89, 16, v95
	v_and_b32_e32 v90, 0xffff0000, v95
	v_cvt_pk_bf16_f32 v56, v140, v60
	v_fmac_f32_e32 v89, v58, v139
	v_fmac_f32_e32 v90, v59, v91
	v_cvt_pk_bf16_f32 v57, v61, v62
	v_cvt_pk_bf16_f32 v58, v63, v88
	v_cvt_pk_bf16_f32 v59, v89, v90
	global_store_dwordx4 v[132:133], v[56:59], off
	v_lshlrev_b32_e32 v88, 16, v100
	v_lshlrev_b32_e32 v60, 16, v98
	v_lshlrev_b32_e32 v56, 16, v96
	v_and_b32_e32 v57, 0xffff0000, v96
	v_fmac_f32_e32 v88, v52, v56
	v_and_b32_e32 v52, 0xffff0000, v100
	v_lshlrev_b32_e32 v58, 16, v97
	v_fmac_f32_e32 v52, v53, v57
	v_lshlrev_b32_e32 v53, 16, v101
	v_and_b32_e32 v59, 0xffff0000, v97
	v_fmac_f32_e32 v53, v54, v58
	v_and_b32_e32 v54, 0xffff0000, v101
	v_and_b32_e32 v61, 0xffff0000, v98
	v_fmac_f32_e32 v54, v55, v59
	v_lshlrev_b32_e32 v55, 16, v102
	v_and_b32_e32 v56, 0xffff0000, v102
	v_lshlrev_b32_e32 v62, 16, v99
	v_and_b32_e32 v63, 0xffff0000, v99
	v_fmac_f32_e32 v55, v48, v60
	v_fmac_f32_e32 v56, v49, v61
	v_lshlrev_b32_e32 v57, 16, v103
	v_and_b32_e32 v58, 0xffff0000, v103
	v_cvt_pk_bf16_f32 v48, v88, v52
	v_fmac_f32_e32 v57, v50, v62
	v_fmac_f32_e32 v58, v51, v63
	v_cvt_pk_bf16_f32 v49, v53, v54
	v_cvt_pk_bf16_f32 v50, v55, v56
	v_cvt_pk_bf16_f32 v51, v57, v58
	global_store_dwordx4 v[132:133], v[48:51], off offset:256
	v_lshlrev_b32_e32 v56, 16, v112
	v_lshlrev_b32_e32 v52, 16, v106
	v_lshlrev_b32_e32 v48, 16, v104
	v_and_b32_e32 v49, 0xffff0000, v104
	v_fmac_f32_e32 v56, v44, v48
	v_and_b32_e32 v44, 0xffff0000, v112
	v_lshlrev_b32_e32 v50, 16, v105
	v_fmac_f32_e32 v44, v45, v49
	v_lshlrev_b32_e32 v45, 16, v113
	v_and_b32_e32 v51, 0xffff0000, v105
	v_fmac_f32_e32 v45, v46, v50
	v_and_b32_e32 v46, 0xffff0000, v113
	v_and_b32_e32 v53, 0xffff0000, v106
	v_fmac_f32_e32 v46, v47, v51
	v_lshlrev_b32_e32 v47, 16, v114
	v_and_b32_e32 v48, 0xffff0000, v114
	v_lshlrev_b32_e32 v54, 16, v107
	v_and_b32_e32 v55, 0xffff0000, v107
	v_fmac_f32_e32 v47, v40, v52
	v_fmac_f32_e32 v48, v41, v53
	v_lshlrev_b32_e32 v49, 16, v115
	v_and_b32_e32 v50, 0xffff0000, v115
	v_cvt_pk_bf16_f32 v40, v56, v44
	v_fmac_f32_e32 v49, v42, v54
	v_fmac_f32_e32 v50, v43, v55
	v_cvt_pk_bf16_f32 v41, v45, v46
	v_cvt_pk_bf16_f32 v42, v47, v48
	v_cvt_pk_bf16_f32 v43, v49, v50
	global_store_dwordx4 v[134:135], v[40:43], off
	v_lshlrev_b32_e32 v48, 16, v116
	v_lshlrev_b32_e32 v44, 16, v110
	v_lshlrev_b32_e32 v40, 16, v108
	v_and_b32_e32 v41, 0xffff0000, v108
	v_fmac_f32_e32 v48, v36, v40
	v_and_b32_e32 v36, 0xffff0000, v116
	v_lshlrev_b32_e32 v42, 16, v109
	v_fmac_f32_e32 v36, v37, v41
	v_lshlrev_b32_e32 v37, 16, v117
	v_and_b32_e32 v43, 0xffff0000, v109
	v_fmac_f32_e32 v37, v38, v42
	v_and_b32_e32 v38, 0xffff0000, v117
	v_and_b32_e32 v45, 0xffff0000, v110
	v_fmac_f32_e32 v38, v39, v43
	v_lshlrev_b32_e32 v39, 16, v118
	v_and_b32_e32 v40, 0xffff0000, v118
	v_lshlrev_b32_e32 v46, 16, v111
	v_and_b32_e32 v47, 0xffff0000, v111
	v_fmac_f32_e32 v39, v32, v44
	v_fmac_f32_e32 v40, v33, v45
	v_lshlrev_b32_e32 v41, 16, v119
	v_and_b32_e32 v42, 0xffff0000, v119
	v_cvt_pk_bf16_f32 v32, v48, v36
	v_fmac_f32_e32 v41, v34, v46
	v_fmac_f32_e32 v42, v35, v47
	v_cvt_pk_bf16_f32 v33, v37, v38
	v_cvt_pk_bf16_f32 v34, v39, v40
	v_cvt_pk_bf16_f32 v35, v41, v42
	global_store_dwordx4 v[134:135], v[32:35], off offset:256
; __device__ __forceinline__ unsigned cvt_pk_bf16(float lo, float hi) { unsigned r; asm volatile("v_cvt_pk_bf16_f32 %0, %1, %2" : "=v"(r) : "v"(lo), "v"(hi)); return r; }
; __device__ __forceinline__ float bflo(unsigned u) { return __uint_as_float(u << 16); }
; __device__ __forceinline__ float bfhi(unsigned u) { return __uint_as_float(u & 0xffff0000u); }
; #define PG8_WAIT_V(n) asm volatile("s_waitcnt vmcnt(" #n ")" ::: "memory")
; #define PG8_BAR __builtin_amdgcn_s_barrier()
; template <class Epi, class Sched>
; __device__ __forceinline__ void gemm_phase(const int wv, LAS unsigned char* lds, const Gemm g, const Sched& S, const Epi& E) {
;     ...
;     PG8_WAIT_V(0);
;     if (wr == 0) PG8_BAR;
;     PG8_BAR;
;     __device__ __forceinline__ void operator()(const f32x4 (&acc)[2][2][4][2], const Unit& u, int wr, int wc, int fr, int fq) const {
;     ...
;             for (int m = 0; m < 4; ++m)
; #pragma unroll
;                 for (int bj = 0; bj < 2; ++bj) {
;                     const int row = row0 + ai * 128 + m * 16, col = col0 + bj * 128;
;                     const u32x4 g = gv[m][bj];
;                     const f32x4 a0 = acc[ai][bj][m][0], a1 = acc[ai][bj][m][1];
;                     float r[8] = {a0[0] * bflo(g.x), a0[1] * bfhi(g.x), a0[2] * bflo(g.y), a0[3] * bfhi(g.y), a1[0] * bflo(g.z), a1[1] * bfhi(g.z), a1[2] * bflo(g.w), a1[3] * bfhi(g.w)};
;                     if (SECOND) { const u32x4 y = yv[m][bj];
;                         r[0] += bflo(y.x); r[1] += bfhi(y.x); r[2] += bflo(y.y); r[3] += bfhi(y.y); r[4] += bflo(y.z); r[5] += bfhi(y.z); r[6] += bflo(y.w); r[7] += bfhi(y.w); }
;                     u32x4 w; w.x = cvt_pk_bf16(r[0], r[1]); w.y = cvt_pk_bf16(r[2], r[3]); w.z = cvt_pk_bf16(r[4], r[5]); w.w = cvt_pk_bf16(r[6], r[7]);
;                     *(u32x4*)(Y + (size_t)row * 1024 + col) = w;
;                 }
	v_lshlrev_b32_e32 v40, 16, v128
	v_lshlrev_b32_e32 v36, 16, v122
	v_lshlrev_b32_e32 v32, 16, v120
	v_and_b32_e32 v33, 0xffff0000, v120
	v_fmac_f32_e32 v40, v28, v32
	v_and_b32_e32 v28, 0xffff0000, v128
	v_lshlrev_b32_e32 v34, 16, v121
	v_fmac_f32_e32 v28, v29, v33
	v_lshlrev_b32_e32 v29, 16, v129
	v_and_b32_e32 v35, 0xffff0000, v121
	v_fmac_f32_e32 v29, v30, v34
	v_and_b32_e32 v30, 0xffff0000, v129
	v_and_b32_e32 v37, 0xffff0000, v122
	v_fmac_f32_e32 v30, v31, v35
	v_lshlrev_b32_e32 v31, 16, v130
	v_and_b32_e32 v32, 0xffff0000, v130
	v_lshlrev_b32_e32 v38, 16, v123
	v_and_b32_e32 v39, 0xffff0000, v123
	v_fmac_f32_e32 v31, v24, v36
	v_fmac_f32_e32 v32, v25, v37
	v_lshlrev_b32_e32 v33, 16, v131
	v_and_b32_e32 v34, 0xffff0000, v131
	v_cvt_pk_bf16_f32 v24, v40, v28
	v_fmac_f32_e32 v33, v26, v38
	v_fmac_f32_e32 v34, v27, v39
	v_cvt_pk_bf16_f32 v25, v29, v30
	v_cvt_pk_bf16_f32 v26, v31, v32
	v_cvt_pk_bf16_f32 v27, v33, v34
	global_store_dwordx4 v[86:87], v[24:27], off
	v_lshlrev_b32_e32 v32, 16, v80
	v_lshlrev_b32_e32 v28, 16, v126
	v_lshlrev_b32_e32 v24, 16, v124
	v_and_b32_e32 v25, 0xffff0000, v124
	v_fmac_f32_e32 v32, v20, v24
	v_and_b32_e32 v20, 0xffff0000, v80
	v_lshlrev_b32_e32 v26, 16, v125
	v_fmac_f32_e32 v20, v21, v25
	v_lshlrev_b32_e32 v21, 16, v81
	v_and_b32_e32 v27, 0xffff0000, v125
	v_fmac_f32_e32 v21, v22, v26
	v_and_b32_e32 v22, 0xffff0000, v81
	v_and_b32_e32 v29, 0xffff0000, v126
	v_fmac_f32_e32 v22, v23, v27
	v_lshlrev_b32_e32 v23, 16, v82
	v_and_b32_e32 v24, 0xffff0000, v82
	v_lshlrev_b32_e32 v30, 16, v127
	v_and_b32_e32 v31, 0xffff0000, v127
	v_fmac_f32_e32 v23, v16, v28
	v_fmac_f32_e32 v24, v17, v29
	v_lshlrev_b32_e32 v25, 16, v83
	v_and_b32_e32 v26, 0xffff0000, v83
	v_cvt_pk_bf16_f32 v16, v32, v20
	v_fmac_f32_e32 v25, v18, v30
	v_fmac_f32_e32 v26, v19, v31
	v_cvt_pk_bf16_f32 v17, v21, v22
	v_cvt_pk_bf16_f32 v18, v23, v24
	v_cvt_pk_bf16_f32 v19, v25, v26
	global_store_dwordx4 v[86:87], v[16:19], off offset:256
	v_lshlrev_b32_e32 v24, 16, v72
	v_lshlrev_b32_e32 v20, 16, v78
	v_lshlrev_b32_e32 v16, 16, v76
	v_and_b32_e32 v17, 0xffff0000, v76
	v_fmac_f32_e32 v24, v12, v16
	v_and_b32_e32 v12, 0xffff0000, v72
	v_lshlrev_b32_e32 v18, 16, v77
	v_fmac_f32_e32 v12, v13, v17
	v_lshlrev_b32_e32 v13, 16, v73
	v_and_b32_e32 v19, 0xffff0000, v77
	v_fmac_f32_e32 v13, v14, v18
	v_and_b32_e32 v14, 0xffff0000, v73
	v_and_b32_e32 v21, 0xffff0000, v78
	v_fmac_f32_e32 v14, v15, v19
	v_lshlrev_b32_e32 v15, 16, v74
	v_and_b32_e32 v16, 0xffff0000, v74
	v_lshlrev_b32_e32 v22, 16, v79
	v_and_b32_e32 v23, 0xffff0000, v79
	v_fmac_f32_e32 v15, v8, v20
	v_fmac_f32_e32 v16, v9, v21
	v_lshlrev_b32_e32 v17, 16, v75
	v_and_b32_e32 v18, 0xffff0000, v75
	v_cvt_pk_bf16_f32 v8, v24, v12
	v_fmac_f32_e32 v17, v10, v22
	v_fmac_f32_e32 v18, v11, v23
	v_cvt_pk_bf16_f32 v9, v13, v14
	v_cvt_pk_bf16_f32 v10, v15, v16
	v_cvt_pk_bf16_f32 v11, v17, v18
	global_store_dwordx4 v[84:85], v[8:11], off
	v_lshlrev_b32_e32 v16, 16, v64
	v_lshlrev_b32_e32 v12, 16, v70
	v_lshlrev_b32_e32 v8, 16, v68
	v_and_b32_e32 v9, 0xffff0000, v68
	v_fmac_f32_e32 v16, v4, v8
	v_and_b32_e32 v4, 0xffff0000, v64
	v_lshlrev_b32_e32 v10, 16, v69
	v_fmac_f32_e32 v4, v5, v9
	v_lshlrev_b32_e32 v5, 16, v65
	v_and_b32_e32 v11, 0xffff0000, v69
	v_fmac_f32_e32 v5, v6, v10
	v_and_b32_e32 v6, 0xffff0000, v65
	v_and_b32_e32 v13, 0xffff0000, v70
	v_lshlrev_b32_e32 v14, 16, v71
	v_and_b32_e32 v15, 0xffff0000, v71
	v_fmac_f32_e32 v6, v7, v11
	v_lshlrev_b32_e32 v7, 16, v66
	v_and_b32_e32 v8, 0xffff0000, v66
	v_lshlrev_b32_e32 v9, 16, v67
	v_and_b32_e32 v10, 0xffff0000, v67
	v_fmac_f32_e32 v7, v0, v12
	v_fmac_f32_e32 v8, v1, v13
	v_fmac_f32_e32 v9, v2, v14
	v_fmac_f32_e32 v10, v3, v15
	v_cvt_pk_bf16_f32 v0, v16, v4
	v_cvt_pk_bf16_f32 v1, v5, v6
	v_cvt_pk_bf16_f32 v2, v7, v8
	v_cvt_pk_bf16_f32 v3, v9, v10
	global_store_dwordx4 v[84:85], v[0:3], off offset:256
	s_cbranch_vccz .LBB0_590
	s_waitcnt vmcnt(0)
	s_cmpk_gt_u32 s24, 0xff
	s_cbranch_scc1 .LBB0_601
	s_barrier

; #define PG8_STAGE(bufoff, gbase, voff) do { _Pragma("unroll") for (int _i = 0; _i < 2; ++_i) \
;         __builtin_amdgcn_global_load_lds((const unsigned*)((const char*)(gbase) + (voff)[_i]), (LAS unsigned*)(lds + (bufoff) + ldsw + _i * 8192), 16, 0, 0); } while (0)
; #define PG8_LDA(dst, b, h) do { _Pragma("unroll") for (int m = 0; m < 4; ++m) _Pragma("unroll") for (int k = 0; k < 2; ++k) dst[m][k] = *(const LAS bf16x8*)(lds + PG8_SA(b, h) + aoff + m * 2048 + k * 1024); } while (0)
; #define PG8_WAIT_V(n) asm volatile("s_waitcnt vmcnt(" #n ")" ::: "memory")
; template <class Epi, class Sched>
; __device__ __forceinline__ void gemm_phase(const int wv, LAS unsigned char* lds, const Gemm g, const Sched& S, const Epi& E) {
;     ...
;         for (int t = 0; t < nt; t += 2) {
;             const bool last = (t == nt - 2);
;             const char* a1 = cA + (size_t)(t + 1) * kstepA;
;             const char* a2 = last ? nA : cA + (size_t)(t + 2) * kstepA; const char* b2 = last ? nB : cB + (size_t)(t + 2) * kstep;
;             const char* a3 = a2 + kstepA; const char* b3 = b2 + kstep;
;             if (last && has_next) S.a_ready(nxt);
;             PG8_LDB(B0, 0, 0); PG8_SCHED; PG8_LDA(At, 0, 0); PG8_STAGE(PG8_SA(1, 1), a1 + hstepA, voffA);
;             PG8_WAIT_L(8); PG8_BAR; PG8_WAIT_L(0); PG8_MMA(0, 0, At, B0); PG8_BAR; PG8_SCHED;
;             PG8_LDB(B1, 0, 1); PG8_STAGE(PG8_SB(0, 0), b2, voffB);
;             PG8_BAR; PG8_WAIT_L(0); PG8_MMA(0, 1, At, B1); PG8_BAR;
;             PG8_LDA(At, 0, 1); PG8_STAGE(PG8_SA(0, 0), a2, voffA);
;             PG8_BAR; PG8_WAIT_L(0); PG8_MMA(1, 0, At, B0); PG8_BAR; PG8_SCHED;
;             PG8_STAGE(PG8_SB(0, 1), b2 + hstepB, voffB);
;             PG8_WAIT_V(6); PG8_BAR; PG8_MMA(1, 1, At, B1); PG8_BAR;
;             PG8_LDB(B0, 1, 0); PG8_SCHED; PG8_LDA(At, 1, 0); PG8_STAGE(PG8_SA(0, 1), a2 + hstepA, voffA);
;             PG8_WAIT_L(8); PG8_BAR; PG8_WAIT_L(0); PG8_MMA(0, 0, At, B0); PG8_BAR; PG8_SCHED;
;             PG8_LDB(B1, 1, 1); PG8_STAGE(PG8_SB(1, 0), b3, voffB);
;             PG8_BAR; PG8_WAIT_L(0); PG8_MMA(0, 1, At, B1); PG8_BAR;
;             PG8_LDA(At, 1, 1); PG8_STAGE(PG8_SA(1, 0), a3, voffA);
;             PG8_BAR; PG8_WAIT_L(0); PG8_MMA(1, 0, At, B0); PG8_BAR; PG8_SCHED;
;             PG8_STAGE(PG8_SB(1, 1), b3 + hstepB, voffB);
;             PG8_WAIT_V(6); PG8_BAR; PG8_MMA(1, 1, At, B1); PG8_BAR;
.LBB0_661:
	ds_read_b128 v[128:131], v177
	ds_read_b128 v[132:135], v177 offset:1024
	ds_read_b128 v[136:139], v177 offset:2048
	ds_read_b128 v[140:143], v177 offset:3072
	s_add_u32 s24, s22, 0xfffc0080
	s_addc_u32 s25, s23, -1
	s_cmp_eq_u32 s48, 12
	s_cselect_b32 s27, s15, s25
	s_cselect_b32 s26, s44, s24
	s_cselect_b32 s25, s13, s47
	s_cselect_b32 s24, s45, s46
	v_lshl_add_u64 v[202:203], s[22:23], 0, v[152:153]
	s_add_i32 m0, s35, 0xc000
	ds_read_b128 v[160:163], v180
	ds_read_b128 v[164:167], v180 offset:1024
	ds_read_b128 v[168:171], v180 offset:2048
	ds_read_b128 v[182:185], v180 offset:3072
	ds_read_b128 v[186:189], v180 offset:4096
	ds_read_b128 v[190:193], v180 offset:5120
	ds_read_b128 v[194:197], v180 offset:6144
	ds_read_b128 v[198:201], v180 offset:7168
	global_load_lds_dwordx4 v[202:203], off
	s_add_i32 m0, s35, 0xe000
	v_lshl_add_u64 v[202:203], s[22:23], 0, v[154:155]
	global_load_lds_dwordx4 v[202:203], off
	s_waitcnt lgkmcnt(8)
	s_barrier
	s_waitcnt lgkmcnt(0)
	v_mfma_f32_16x16x32_bf16 v[124:127], v[128:131], v[160:163], v[124:127]
	v_mfma_f32_16x16x32_bf16 v[120:123], v[136:139], v[160:163], v[120:123]
	v_mfma_f32_16x16x32_bf16 v[116:119], v[128:131], v[168:171], v[116:119]
	v_mfma_f32_16x16x32_bf16 v[104:107], v[136:139], v[168:171], v[104:107]
	v_mfma_f32_16x16x32_bf16 v[92:95], v[128:131], v[186:189], v[92:95]
	v_mfma_f32_16x16x32_bf16 v[88:91], v[136:139], v[186:189], v[88:91]
	v_mfma_f32_16x16x32_bf16 v[76:79], v[128:131], v[194:197], v[76:79]
	v_mfma_f32_16x16x32_bf16 v[72:75], v[136:139], v[194:197], v[72:75]
	v_mfma_f32_16x16x32_bf16 v[124:127], v[132:135], v[164:167], v[124:127]
	v_mfma_f32_16x16x32_bf16 v[120:123], v[140:143], v[164:167], v[120:123]
	v_mfma_f32_16x16x32_bf16 v[116:119], v[132:135], v[182:185], v[116:119]
	v_mfma_f32_16x16x32_bf16 v[104:107], v[140:143], v[182:185], v[104:107]
	v_mfma_f32_16x16x32_bf16 v[92:95], v[132:135], v[190:193], v[92:95]
	v_mfma_f32_16x16x32_bf16 v[88:91], v[140:143], v[190:193], v[88:91]
	v_mfma_f32_16x16x32_bf16 v[76:79], v[132:135], v[198:201], v[76:79]
	v_mfma_f32_16x16x32_bf16 v[72:75], v[140:143], v[198:201], v[72:75]
	s_barrier
	s_add_i32 s49, s41, s34
	v_lshl_add_u64 v[218:219], s[24:25], 0, v[146:147]
	s_mov_b32 m0, s49
	ds_read_b128 v[202:205], v181
	ds_read_b128 v[206:209], v181 offset:1024
	ds_read_b128 v[210:213], v181 offset:2048
	ds_read_b128 v[214:217], v181 offset:3072
	global_load_lds_dwordx4 v[218:219], off
	s_add_i32 m0, s49, 0x2000
	v_lshl_add_u64 v[220:221], s[24:25], 0, v[150:151]
	global_load_lds_dwordx4 v[220:221], off
	s_barrier
	s_waitcnt lgkmcnt(0)
	v_mfma_f32_16x16x32_bf16 v[112:115], v[202:205], v[160:163], v[112:115]
	v_mfma_f32_16x16x32_bf16 v[108:111], v[210:213], v[160:163], v[108:111]
	v_mfma_f32_16x16x32_bf16 v[100:103], v[202:205], v[168:171], v[100:103]
	v_mfma_f32_16x16x32_bf16 v[96:99], v[210:213], v[168:171], v[96:99]
	v_mfma_f32_16x16x32_bf16 v[84:87], v[202:205], v[186:189], v[84:87]
	v_mfma_f32_16x16x32_bf16 v[80:83], v[210:213], v[186:189], v[80:83]
	v_mfma_f32_16x16x32_bf16 v[68:71], v[202:205], v[194:197], v[68:71]
	v_mfma_f32_16x16x32_bf16 v[64:67], v[210:213], v[194:197], v[64:67]
	v_mfma_f32_16x16x32_bf16 v[112:115], v[206:209], v[164:167], v[112:115]
	v_mfma_f32_16x16x32_bf16 v[108:111], v[214:217], v[164:167], v[108:111]
	v_mfma_f32_16x16x32_bf16 v[100:103], v[206:209], v[182:185], v[100:103]
	v_mfma_f32_16x16x32_bf16 v[96:99], v[214:217], v[182:185], v[96:99]
	v_mfma_f32_16x16x32_bf16 v[84:87], v[206:209], v[190:193], v[84:87]
	v_mfma_f32_16x16x32_bf16 v[80:83], v[214:217], v[190:193], v[80:83]
	v_mfma_f32_16x16x32_bf16 v[68:71], v[206:209], v[198:201], v[68:71]
	v_mfma_f32_16x16x32_bf16 v[64:67], v[214:217], v[198:201], v[64:67]
	s_mov_b32 m0, s35
	v_lshl_add_u64 v[222:223], s[26:27], 0, v[144:145]
	s_barrier
	ds_read_b128 v[160:163], v180 offset:16384
	ds_read_b128 v[164:167], v180 offset:17408
	ds_read_b128 v[168:171], v180 offset:18432
	ds_read_b128 v[182:185], v180 offset:19456
	ds_read_b128 v[186:189], v180 offset:20480
	ds_read_b128 v[190:193], v180 offset:21504
	ds_read_b128 v[194:197], v180 offset:22528
	ds_read_b128 v[198:201], v180 offset:23552
	global_load_lds_dwordx4 v[222:223], off
	s_mov_b32 m0, s36
	v_lshl_add_u64 v[224:225], s[26:27], 0, v[148:149]
	global_load_lds_dwordx4 v[224:225], off
	s_barrier
	s_waitcnt lgkmcnt(0)
	v_mfma_f32_16x16x32_bf16 v[60:63], v[128:131], v[160:163], v[60:63]
	v_mfma_f32_16x16x32_bf16 v[56:59], v[136:139], v[160:163], v[56:59]
	v_mfma_f32_16x16x32_bf16 v[44:47], v[128:131], v[168:171], v[44:47]
	v_mfma_f32_16x16x32_bf16 v[40:43], v[136:139], v[168:171], v[40:43]
	v_mfma_f32_16x16x32_bf16 v[28:31], v[128:131], v[186:189], v[28:31]
	v_mfma_f32_16x16x32_bf16 v[24:27], v[136:139], v[186:189], v[24:27]
	v_mfma_f32_16x16x32_bf16 v[12:15], v[128:131], v[194:197], v[12:15]
	v_mfma_f32_16x16x32_bf16 v[8:11], v[136:139], v[194:197], v[8:11]
	v_mfma_f32_16x16x32_bf16 v[60:63], v[132:135], v[164:167], v[60:63]
	v_mfma_f32_16x16x32_bf16 v[56:59], v[140:143], v[164:167], v[56:59]
	v_mfma_f32_16x16x32_bf16 v[44:47], v[132:135], v[182:185], v[44:47]
	v_mfma_f32_16x16x32_bf16 v[40:43], v[140:143], v[182:185], v[40:43]
	v_mfma_f32_16x16x32_bf16 v[28:31], v[132:135], v[190:193], v[28:31]
	v_mfma_f32_16x16x32_bf16 v[24:27], v[140:143], v[190:193], v[24:27]
	v_mfma_f32_16x16x32_bf16 v[12:15], v[132:135], v[198:201], v[12:15]
	v_mfma_f32_16x16x32_bf16 v[8:11], v[140:143], v[198:201], v[8:11]
	s_barrier
	s_add_u32 s50, s24, 0x40000
	s_addc_u32 s51, s25, 0
	s_add_i32 s49, s42, s34
	s_mov_b32 m0, s49
	v_lshl_add_u64 v[128:129], s[50:51], 0, v[146:147]
	global_load_lds_dwordx4 v[128:129], off
	s_add_i32 m0, s49, 0x2000
	v_lshl_add_u64 v[128:129], s[50:51], 0, v[150:151]
	global_load_lds_dwordx4 v[128:129], off
	s_waitcnt vmcnt(6)
	s_barrier
; #define PG8_STAGE(bufoff, gbase, voff) do { _Pragma("unroll") for (int _i = 0; _i < 2; ++_i) \
;         __builtin_amdgcn_global_load_lds((const unsigned*)((const char*)(gbase) + (voff)[_i]), (LAS unsigned*)(lds + (bufoff) + ldsw + _i * 8192), 16, 0, 0); } while (0)
; #define PG8_LDA(dst, b, h) do { _Pragma("unroll") for (int m = 0; m < 4; ++m) _Pragma("unroll") for (int k = 0; k < 2; ++k) dst[m][k] = *(const LAS bf16x8*)(lds + PG8_SA(b, h) + aoff + m * 2048 + k * 1024); } while (0)
; #define PG8_WAIT_V(n) asm volatile("s_waitcnt vmcnt(" #n ")" ::: "memory")
; template <class Epi, class Sched>
; __device__ __forceinline__ void gemm_phase(const int wv, LAS unsigned char* lds, const Gemm g, const Sched& S, const Epi& E) {
;     ...
;         for (int t = 0; t < nt; t += 2) {
;             const bool last = (t == nt - 2);
;             const char* a1 = cA + (size_t)(t + 1) * kstepA;
;             const char* a2 = last ? nA : cA + (size_t)(t + 2) * kstepA; const char* b2 = last ? nB : cB + (size_t)(t + 2) * kstep;
;             const char* a3 = a2 + kstepA; const char* b3 = b2 + kstep;
;             if (last && has_next) S.a_ready(nxt);
;             PG8_LDB(B0, 0, 0); PG8_SCHED; PG8_LDA(At, 0, 0); PG8_STAGE(PG8_SA(1, 1), a1 + hstepA, voffA);
;             PG8_WAIT_L(8); PG8_BAR; PG8_WAIT_L(0); PG8_MMA(0, 0, At, B0); PG8_BAR; PG8_SCHED;
;             PG8_LDB(B1, 0, 1); PG8_STAGE(PG8_SB(0, 0), b2, voffB);
;             PG8_BAR; PG8_WAIT_L(0); PG8_MMA(0, 1, At, B1); PG8_BAR;
;             PG8_LDA(At, 0, 1); PG8_STAGE(PG8_SA(0, 0), a2, voffA);
;             PG8_BAR; PG8_WAIT_L(0); PG8_MMA(1, 0, At, B0); PG8_BAR; PG8_SCHED;
;             PG8_STAGE(PG8_SB(0, 1), b2 + hstepB, voffB);
;             PG8_WAIT_V(6); PG8_BAR; PG8_MMA(1, 1, At, B1); PG8_BAR;
;             PG8_LDB(B0, 1, 0); PG8_SCHED; PG8_LDA(At, 1, 0); PG8_STAGE(PG8_SA(0, 1), a2 + hstepA, voffA);
;             PG8_WAIT_L(8); PG8_BAR; PG8_WAIT_L(0); PG8_MMA(0, 0, At, B0); PG8_BAR; PG8_SCHED;
;             PG8_LDB(B1, 1, 1); PG8_STAGE(PG8_SB(1, 0), b3, voffB);
;             PG8_BAR; PG8_WAIT_L(0); PG8_MMA(0, 1, At, B1); PG8_BAR;
;             PG8_LDA(At, 1, 1); PG8_STAGE(PG8_SA(1, 0), a3, voffA);
;             PG8_BAR; PG8_WAIT_L(0); PG8_MMA(1, 0, At, B0); PG8_BAR; PG8_SCHED;
;             PG8_STAGE(PG8_SB(1, 1), b3 + hstepB, voffB);
;             PG8_WAIT_V(6); PG8_BAR; PG8_MMA(1, 1, At, B1); PG8_BAR;
	v_mfma_f32_16x16x32_bf16 v[52:55], v[202:205], v[160:163], v[52:55]
	v_mfma_f32_16x16x32_bf16 v[48:51], v[210:213], v[160:163], v[48:51]
	v_mfma_f32_16x16x32_bf16 v[36:39], v[202:205], v[168:171], v[36:39]
	v_mfma_f32_16x16x32_bf16 v[32:35], v[210:213], v[168:171], v[32:35]
	v_mfma_f32_16x16x32_bf16 v[20:23], v[202:205], v[186:189], v[20:23]
	v_mfma_f32_16x16x32_bf16 v[16:19], v[210:213], v[186:189], v[16:19]
	v_mfma_f32_16x16x32_bf16 v[4:7], v[202:205], v[194:197], v[4:7]
	v_mfma_f32_16x16x32_bf16 v[0:3], v[210:213], v[194:197], v[0:3]
	v_mfma_f32_16x16x32_bf16 v[52:55], v[206:209], v[164:167], v[52:55]
	v_mfma_f32_16x16x32_bf16 v[48:51], v[214:217], v[164:167], v[48:51]
	v_mfma_f32_16x16x32_bf16 v[36:39], v[206:209], v[182:185], v[36:39]
	v_mfma_f32_16x16x32_bf16 v[32:35], v[214:217], v[182:185], v[32:35]
	v_mfma_f32_16x16x32_bf16 v[20:23], v[206:209], v[190:193], v[20:23]
	v_mfma_f32_16x16x32_bf16 v[16:19], v[214:217], v[190:193], v[16:19]
	v_mfma_f32_16x16x32_bf16 v[4:7], v[206:209], v[198:201], v[4:7]
	v_mfma_f32_16x16x32_bf16 v[0:3], v[214:217], v[198:201], v[0:3]
	s_add_i32 s49, 0, 0x18000
	v_add_u32_e32 v140, s49, v173
	s_barrier
	ds_read_b128 v[128:131], v140
	ds_read_b128 v[132:135], v140 offset:1024
	ds_read_b128 v[136:139], v140 offset:2048
	ds_read_b128 v[140:143], v140 offset:3072
	s_add_u32 s26, s26, 0x40000
	s_addc_u32 s27, s27, 0
	s_mov_b32 m0, s37
	v_lshl_add_u64 v[202:203], s[26:27], 0, v[144:145]
	ds_read_b128 v[160:163], v180 offset:32768
	ds_read_b128 v[164:167], v180 offset:33792
	ds_read_b128 v[168:171], v180 offset:34816
	ds_read_b128 v[182:185], v180 offset:35840
	ds_read_b128 v[186:189], v180 offset:36864
	ds_read_b128 v[190:193], v180 offset:37888
	ds_read_b128 v[194:197], v180 offset:38912
	ds_read_b128 v[198:201], v180 offset:39936
	global_load_lds_dwordx4 v[202:203], off
	s_mov_b32 m0, s38
	v_lshl_add_u64 v[202:203], s[26:27], 0, v[148:149]
	global_load_lds_dwordx4 v[202:203], off
	s_waitcnt lgkmcnt(8)
	s_barrier
	s_waitcnt lgkmcnt(0)
	v_mfma_f32_16x16x32_bf16 v[124:127], v[128:131], v[160:163], v[124:127]
	v_mfma_f32_16x16x32_bf16 v[120:123], v[136:139], v[160:163], v[120:123]
	v_mfma_f32_16x16x32_bf16 v[116:119], v[128:131], v[168:171], v[116:119]
	v_mfma_f32_16x16x32_bf16 v[104:107], v[136:139], v[168:171], v[104:107]
	v_mfma_f32_16x16x32_bf16 v[92:95], v[128:131], v[186:189], v[92:95]
	v_mfma_f32_16x16x32_bf16 v[88:91], v[136:139], v[186:189], v[88:91]
	v_mfma_f32_16x16x32_bf16 v[76:79], v[128:131], v[194:197], v[76:79]
	v_mfma_f32_16x16x32_bf16 v[72:75], v[136:139], v[194:197], v[72:75]
	v_mfma_f32_16x16x32_bf16 v[124:127], v[132:135], v[164:167], v[124:127]
	v_mfma_f32_16x16x32_bf16 v[120:123], v[140:143], v[164:167], v[120:123]
	v_mfma_f32_16x16x32_bf16 v[116:119], v[132:135], v[182:185], v[116:119]
	v_mfma_f32_16x16x32_bf16 v[104:107], v[140:143], v[182:185], v[104:107]
	v_mfma_f32_16x16x32_bf16 v[92:95], v[132:135], v[190:193], v[92:95]
	v_mfma_f32_16x16x32_bf16 v[88:91], v[140:143], v[190:193], v[88:91]
	v_mfma_f32_16x16x32_bf16 v[76:79], v[132:135], v[198:201], v[76:79]
	v_mfma_f32_16x16x32_bf16 v[72:75], v[140:143], v[198:201], v[72:75]
	s_barrier
	s_add_i32 s26, 0, 0x1c000
	s_add_i32 s27, s49, s34
	v_add_u32_e32 v214, s26, v173
	v_lshl_add_u64 v[218:219], v[218:219], 0, s[10:11]
	s_mov_b32 m0, s27
	ds_read_b128 v[202:205], v214
	ds_read_b128 v[206:209], v214 offset:1024
	ds_read_b128 v[210:213], v214 offset:2048
	ds_read_b128 v[214:217], v214 offset:3072
	global_load_lds_dwordx4 v[218:219], off
	s_add_i32 m0, s27, 0x2000
	v_lshl_add_u64 v[218:219], v[220:221], 0, s[10:11]
	global_load_lds_dwordx4 v[218:219], off
	s_barrier
	s_waitcnt lgkmcnt(0)
	v_mfma_f32_16x16x32_bf16 v[112:115], v[202:205], v[160:163], v[112:115]
	v_mfma_f32_16x16x32_bf16 v[108:111], v[210:213], v[160:163], v[108:111]
	v_mfma_f32_16x16x32_bf16 v[100:103], v[202:205], v[168:171], v[100:103]
	v_mfma_f32_16x16x32_bf16 v[96:99], v[210:213], v[168:171], v[96:99]
	v_mfma_f32_16x16x32_bf16 v[84:87], v[202:205], v[186:189], v[84:87]
	v_mfma_f32_16x16x32_bf16 v[80:83], v[210:213], v[186:189], v[80:83]
	v_mfma_f32_16x16x32_bf16 v[68:71], v[202:205], v[194:197], v[68:71]
	v_mfma_f32_16x16x32_bf16 v[64:67], v[210:213], v[194:197], v[64:67]
	v_mfma_f32_16x16x32_bf16 v[112:115], v[206:209], v[164:167], v[112:115]
	v_mfma_f32_16x16x32_bf16 v[108:111], v[214:217], v[164:167], v[108:111]
	v_mfma_f32_16x16x32_bf16 v[100:103], v[206:209], v[182:185], v[100:103]
	v_mfma_f32_16x16x32_bf16 v[96:99], v[214:217], v[182:185], v[96:99]
	v_mfma_f32_16x16x32_bf16 v[84:87], v[206:209], v[190:193], v[84:87]
	v_mfma_f32_16x16x32_bf16 v[80:83], v[214:217], v[190:193], v[80:83]
	v_mfma_f32_16x16x32_bf16 v[68:71], v[206:209], v[198:201], v[68:71]
	v_mfma_f32_16x16x32_bf16 v[64:67], v[214:217], v[198:201], v[64:67]
	s_mov_b32 m0, s39
	v_lshl_add_u64 v[218:219], v[222:223], 0, s[10:11]
	s_barrier
	ds_read_b128 v[160:163], v180 offset:49152
	ds_read_b128 v[164:167], v180 offset:50176
	ds_read_b128 v[168:171], v180 offset:51200
	ds_read_b128 v[182:185], v180 offset:52224
	ds_read_b128 v[186:189], v180 offset:53248
	ds_read_b128 v[190:193], v180 offset:54272
	ds_read_b128 v[194:197], v180 offset:55296
	ds_read_b128 v[198:201], v180 offset:56320
	global_load_lds_dwordx4 v[218:219], off
	s_mov_b32 m0, s40
	v_lshl_add_u64 v[218:219], v[224:225], 0, s[10:11]
	global_load_lds_dwordx4 v[218:219], off
	s_barrier
; template <class Epi, class Sched>
; __device__ __forceinline__ void gemm_phase(const int wv, LAS unsigned char* lds, const Gemm g, const Sched& S, const Epi& E) {
;     ...
;         for (int t = 0; t < nt; t += 2) {
;             const bool last = (t == nt - 2);
;             const char* a1 = cA + (size_t)(t + 1) * kstepA;
;             const char* a2 = last ? nA : cA + (size_t)(t + 2) * kstepA; const char* b2 = last ? nB : cB + (size_t)(t + 2) * kstep;
;             const char* a3 = a2 + kstepA; const char* b3 = b2 + kstep;
;             if (last && has_next) S.a_ready(nxt);
;             PG8_LDB(B0, 0, 0); PG8_SCHED; PG8_LDA(At, 0, 0); PG8_STAGE(PG8_SA(1, 1), a1 + hstepA, voffA);
;             PG8_WAIT_L(8); PG8_BAR; PG8_WAIT_L(0); PG8_MMA(0, 0, At, B0); PG8_BAR; PG8_SCHED;
;             PG8_LDB(B1, 0, 1); PG8_STAGE(PG8_SB(0, 0), b2, voffB);
;             PG8_BAR; PG8_WAIT_L(0); PG8_MMA(0, 1, At, B1); PG8_BAR;
;             PG8_LDA(At, 0, 1); PG8_STAGE(PG8_SA(0, 0), a2, voffA);
;             PG8_BAR; PG8_WAIT_L(0); PG8_MMA(1, 0, At, B0); PG8_BAR; PG8_SCHED;
;             PG8_STAGE(PG8_SB(0, 1), b2 + hstepB, voffB);
;             PG8_WAIT_V(6); PG8_BAR; PG8_MMA(1, 1, At, B1); PG8_BAR;
;             PG8_LDB(B0, 1, 0); PG8_SCHED; PG8_LDA(At, 1, 0); PG8_STAGE(PG8_SA(0, 1), a2 + hstepA, voffA);
;             PG8_WAIT_L(8); PG8_BAR; PG8_WAIT_L(0); PG8_MMA(0, 0, At, B0); PG8_BAR; PG8_SCHED;
;             PG8_LDB(B1, 1, 1); PG8_STAGE(PG8_SB(1, 0), b3, voffB);
;             PG8_BAR; PG8_WAIT_L(0); PG8_MMA(0, 1, At, B1); PG8_BAR;
;             PG8_LDA(At, 1, 1); PG8_STAGE(PG8_SA(1, 0), a3, voffA);
;             PG8_BAR; PG8_WAIT_L(0); PG8_MMA(1, 0, At, B0); PG8_BAR; PG8_SCHED;
;             PG8_STAGE(PG8_SB(1, 1), b3 + hstepB, voffB);
;             PG8_WAIT_V(6); PG8_BAR; PG8_MMA(1, 1, At, B1); PG8_BAR;
;     __device__ __forceinline__ void operator()(const f32x4 (&acc)[2][2][4][2], const Unit& u, int wr, int wc, int fr, int fq) const {
;         const int row0 = u.pm * 256 + wr * 64 + fr; const int col0 = u.pn * 256 + wc * 32 + 8 * fq;
; #pragma unroll
;         for (int ai = 0; ai < 2; ++ai) {
;             f32x4 xv[4][2][2];
; #pragma unroll
;             for (int m = 0; m < 4; ++m)
; #pragma unroll
;                 for (int bj = 0; bj < 2; ++bj) {
;                     const size_t o = (size_t)(row0 + ai * 128 + m * 16) * 1024 + col0 + bj * 128;
	s_waitcnt lgkmcnt(0)
	v_mfma_f32_16x16x32_bf16 v[60:63], v[128:131], v[160:163], v[60:63]
	v_mfma_f32_16x16x32_bf16 v[56:59], v[136:139], v[160:163], v[56:59]
	v_mfma_f32_16x16x32_bf16 v[44:47], v[128:131], v[168:171], v[44:47]
	v_mfma_f32_16x16x32_bf16 v[40:43], v[136:139], v[168:171], v[40:43]
	v_mfma_f32_16x16x32_bf16 v[28:31], v[128:131], v[186:189], v[28:31]
	v_mfma_f32_16x16x32_bf16 v[24:27], v[136:139], v[186:189], v[24:27]
	v_mfma_f32_16x16x32_bf16 v[12:15], v[128:131], v[194:197], v[12:15]
	v_mfma_f32_16x16x32_bf16 v[8:11], v[136:139], v[194:197], v[8:11]
	v_mfma_f32_16x16x32_bf16 v[60:63], v[132:135], v[164:167], v[60:63]
	v_mfma_f32_16x16x32_bf16 v[56:59], v[140:143], v[164:167], v[56:59]
	v_mfma_f32_16x16x32_bf16 v[44:47], v[132:135], v[182:185], v[44:47]
	v_mfma_f32_16x16x32_bf16 v[40:43], v[140:143], v[182:185], v[40:43]
	v_mfma_f32_16x16x32_bf16 v[28:31], v[132:135], v[190:193], v[28:31]
	v_mfma_f32_16x16x32_bf16 v[24:27], v[140:143], v[190:193], v[24:27]
	v_mfma_f32_16x16x32_bf16 v[12:15], v[132:135], v[198:201], v[12:15]
	v_mfma_f32_16x16x32_bf16 v[8:11], v[140:143], v[198:201], v[8:11]
	s_barrier
	s_add_u32 s24, s24, 0x40080
	s_addc_u32 s25, s25, 0
	s_add_i32 s26, s26, s34
	s_mov_b32 m0, s26
	v_lshl_add_u64 v[128:129], s[24:25], 0, v[146:147]
	global_load_lds_dwordx4 v[128:129], off
	s_add_i32 m0, s26, 0x2000
	v_lshl_add_u64 v[128:129], s[24:25], 0, v[150:151]
	global_load_lds_dwordx4 v[128:129], off
	s_waitcnt vmcnt(6)
	s_barrier
	v_mfma_f32_16x16x32_bf16 v[52:55], v[202:205], v[160:163], v[52:55]
	v_mfma_f32_16x16x32_bf16 v[48:51], v[210:213], v[160:163], v[48:51]
	v_mfma_f32_16x16x32_bf16 v[36:39], v[202:205], v[168:171], v[36:39]
	v_mfma_f32_16x16x32_bf16 v[32:35], v[210:213], v[168:171], v[32:35]
	v_mfma_f32_16x16x32_bf16 v[20:23], v[202:205], v[186:189], v[20:23]
	v_mfma_f32_16x16x32_bf16 v[16:19], v[210:213], v[186:189], v[16:19]
	v_mfma_f32_16x16x32_bf16 v[4:7], v[202:205], v[194:197], v[4:7]
	v_mfma_f32_16x16x32_bf16 v[0:3], v[210:213], v[194:197], v[0:3]
	v_mfma_f32_16x16x32_bf16 v[52:55], v[206:209], v[164:167], v[52:55]
	v_mfma_f32_16x16x32_bf16 v[48:51], v[214:217], v[164:167], v[48:51]
	v_mfma_f32_16x16x32_bf16 v[36:39], v[206:209], v[182:185], v[36:39]
	v_mfma_f32_16x16x32_bf16 v[32:35], v[214:217], v[182:185], v[32:35]
	v_mfma_f32_16x16x32_bf16 v[20:23], v[206:209], v[190:193], v[20:23]
	v_mfma_f32_16x16x32_bf16 v[16:19], v[214:217], v[190:193], v[16:19]
	v_mfma_f32_16x16x32_bf16 v[4:7], v[206:209], v[198:201], v[4:7]
	v_mfma_f32_16x16x32_bf16 v[0:3], v[214:217], v[198:201], v[0:3]
	s_add_i32 s48, s48, 2
	s_add_u32 s22, s22, 0x100
	s_addc_u32 s23, s23, 0
	s_add_u32 s46, s46, 0x100
	s_addc_u32 s47, s47, 0
	s_cmp_gt_u32 s48, 13
	s_barrier
	s_cbranch_scc0 .LBB0_661
	v_lshl_add_u32 v162, s20, 8, v172
	v_lshl_or_b32 v128, s21, 8, v174
	v_ashrrev_i32_e32 v129, 31, v128
	v_ashrrev_i32_e32 v163, 31, v162
	v_lshl_add_u64 v[164:165], v[128:129], 2, s[2:3]
	v_lshlrev_b64 v[130:131], 12, v[162:163]
	v_lshl_add_u64 v[130:131], v[164:165], 0, v[130:131]
	global_load_dwordx4 v[182:185], v[130:131], off
	global_load_dwordx4 v[186:189], v[130:131], off offset:16
	global_load_dwordx4 v[190:193], v[130:131], off offset:512
	global_load_dwordx4 v[194:197], v[130:131], off offset:528
	v_or_b32_e32 v170, 16, v162
	v_ashrrev_i32_e32 v171, 31, v170
	v_lshlrev_b64 v[130:131], 12, v[170:171]
	v_lshl_add_u64 v[130:131], v[164:165], 0, v[130:131]
	global_load_dwordx4 v[198:201], v[130:131], off
	global_load_dwordx4 v[202:205], v[130:131], off offset:16
	global_load_dwordx4 v[206:209], v[130:131], off offset:528
	global_load_dwordx4 v[210:213], v[130:131], off offset:512
	v_or_b32_e32 v168, 32, v162
	v_or_b32_e32 v166, 48, v162
	s_lshl_b32 s20, s21, 2
	v_ashrrev_i32_e32 v169, 31, v168
	v_ashrrev_i32_e32 v167, 31, v166
	s_ashr_i32 s21, s20, 31
	v_lshlrev_b64 v[132:133], 11, v[162:163]
	v_lshlrev_b64 v[160:161], 1, v[128:129]
	v_lshlrev_b64 v[128:129], 6, v[162:163]
	v_lshlrev_b64 v[134:135], 12, v[168:169]
	v_lshlrev_b64 v[136:137], 12, v[166:167]
	s_lshl_b64 s[20:21], s[20:21], 2
	v_lshl_add_u64 v[132:133], s[6:7], 0, v[132:133]
	v_lshl_add_u64 v[128:129], s[8:9], 0, v[128:129]
	v_lshl_add_u64 v[130:131], v[164:165], 0, v[134:135]
	v_lshl_add_u64 v[134:135], v[164:165], 0, v[136:137]
	v_lshl_add_u64 v[232:233], v[132:133], 0, v[160:161]
	v_lshl_add_u64 v[234:235], v[128:129], 0, s[20:21]
	global_load_dwordx4 v[214:217], v[130:131], off offset:16
	global_load_dwordx4 v[218:221], v[130:131], off
	global_load_dwordx4 v[222:225], v[130:131], off offset:528
	global_load_dwordx4 v[226:229], v[130:131], off offset:512
	global_load_dwordx4 v[136:139], v[134:135], off offset:16
	global_load_dwordx4 v[140:143], v[134:135], off
	s_nop 0
	global_load_dwordx4 v[128:131], v[134:135], off offset:528
	s_nop 0
	global_load_dwordx4 v[132:135], v[134:135], off offset:512
	v_lshl_add_u64 v[234:235], v[234:235], 0, s[4:5]
	v_lshlrev_b64 v[230:231], 11, v[170:171]
	s_and_b64 vcc, exec, s[0:1]
	s_mov_b64 s[24:25], s[18:19]
	s_mov_b64 s[22:23], s[16:17]
	s_waitcnt vmcnt(0)
; __device__ __forceinline__ float shx(float v, int lane, int mask) { return __int_as_float(__builtin_amdgcn_ds_bpermute((lane ^ mask) << 2, __float_as_int(v))); }
; __device__ __forceinline__ unsigned cvt_pk_bf16(float lo, float hi) { unsigned r; asm volatile("v_cvt_pk_bf16_f32 %0, %1, %2" : "=v"(r) : "v"(lo), "v"(hi)); return r; }
;     __device__ __forceinline__ void operator()(const f32x4 (&acc)[2][2][4][2], const Unit& u, int wr, int wc, int fr, int fq) const {
;     ...
; #pragma unroll
;             for (int m = 0; m < 4; ++m) {
;                 const int row = row0 + ai * 128 + m * 16; float ss = 0.f;
; #pragma unroll
;                 for (int bj = 0; bj < 2; ++bj) {
;                     const size_t o = (size_t)row * 1024 + col0 + bj * 128;
;                     const f32x4 v0 = xv[m][bj][0] + acc[ai][bj][m][0], v1 = xv[m][bj][1] + acc[ai][bj][m][1];
;                     ss += (v0[0] * v0[0] + v0[1] * v0[1]) + (v0[2] * v0[2] + v0[3] * v0[3]) + (v1[0] * v1[0] + v1[1] * v1[1]) + (v1[2] * v1[2] + v1[3] * v1[3]);
;                     u32x4 w; w.x = cvt_pk_bf16(v0[0], v0[1]); w.y = cvt_pk_bf16(v0[2], v0[3]); w.z = cvt_pk_bf16(v1[0], v1[1]); w.w = cvt_pk_bf16(v1[2], v1[3]);
;                     *(u32x4*)(x1b + o) = w;
;                 }
;                 ss += shx(ss, fq * 16 + fr, 16); ss += shx(ss, fq * 16 + fr, 32);
;                 ss2[(size_t)row * 16 + u.pn * 4 + wc] = ss;
;             }
	v_pk_add_f32 v[126:127], v[126:127], v[184:185]
	v_pk_add_f32 v[124:125], v[124:125], v[182:183]
	v_pk_add_f32 v[122:123], v[122:123], v[188:189]
	v_pk_add_f32 v[120:121], v[120:121], v[186:187]
	v_pk_add_f32 v[114:115], v[114:115], v[192:193]
	v_pk_add_f32 v[112:113], v[112:113], v[190:191]
	v_pk_add_f32 v[182:183], v[110:111], v[196:197]
	v_pk_add_f32 v[184:185], v[108:109], v[194:195]
	v_mul_f32_e32 v163, v125, v125
	v_mul_f32_e32 v190, v127, v127
	v_mul_f32_e32 v191, v121, v121
	v_mul_f32_e32 v192, v123, v123
	v_cvt_pk_bf16_f32 v108, v124, v125
	v_cvt_pk_bf16_f32 v109, v126, v127
	v_cvt_pk_bf16_f32 v110, v120, v121
	v_cvt_pk_bf16_f32 v111, v122, v123
	v_mul_f32_e32 v121, v113, v113
	v_mul_f32_e32 v123, v115, v115
	v_mul_f32_e32 v125, v185, v185
	v_fmac_f32_e32 v163, v124, v124
	v_fmac_f32_e32 v190, v126, v126
	v_fmac_f32_e32 v121, v112, v112
	v_fmac_f32_e32 v123, v114, v114
	v_mul_f32_e32 v127, v183, v183
	v_fmac_f32_e32 v191, v120, v120
	global_store_dwordx4 v[232:233], v[108:111], off
	v_fmac_f32_e32 v125, v184, v184
	v_fmac_f32_e32 v192, v122, v122
	v_add_f32_e32 v108, v163, v190
	v_add_f32_e32 v109, v121, v123
	v_fmac_f32_e32 v127, v182, v182
	v_add_f32_e32 v108, v108, v191
	v_add_f32_e32 v109, v109, v125
	v_add_f32_e32 v108, v192, v108
	v_add_f32_e32 v109, v127, v109
	v_add_f32_e32 v108, v108, v109
	ds_bpermute_b32 v109, v175, v108
	v_pk_add_f32 v[188:189], v[104:105], v[202:203]
	v_cvt_pk_bf16_f32 v104, v112, v113
	v_pk_add_f32 v[186:187], v[106:107], v[204:205]
	v_cvt_pk_bf16_f32 v105, v114, v115
	v_cvt_pk_bf16_f32 v106, v184, v185
	v_cvt_pk_bf16_f32 v107, v182, v183
	global_store_dwordx4 v[232:233], v[104:107], off offset:256
	v_pk_add_f32 v[102:103], v[102:103], v[212:213]
	v_pk_add_f32 v[100:101], v[100:101], v[210:211]
	s_waitcnt lgkmcnt(0)
	v_add_f32_e32 v104, v108, v109
	ds_bpermute_b32 v105, v176, v104
	v_pk_add_f32 v[108:109], v[98:99], v[208:209]
	v_pk_add_f32 v[98:99], v[96:97], v[206:207]
	v_mul_f32_e32 v96, v101, v101
	v_mul_f32_e32 v97, v103, v103
	v_pk_add_f32 v[118:119], v[118:119], v[200:201]
	v_pk_add_f32 v[116:117], v[116:117], v[198:199]
	v_fmac_f32_e32 v96, v100, v100
	v_fmac_f32_e32 v97, v102, v102
	v_mul_f32_e32 v110, v117, v117
	v_mul_f32_e32 v111, v119, v119
	v_add_f32_e32 v96, v96, v97
	v_mul_f32_e32 v97, v99, v99
	v_mul_f32_e32 v112, v189, v189
	v_fmac_f32_e32 v110, v116, v116
	v_fmac_f32_e32 v111, v118, v118
	v_fmac_f32_e32 v97, v98, v98
	v_fmac_f32_e32 v112, v188, v188
	v_add_f32_e32 v106, v110, v111
	s_waitcnt lgkmcnt(0)
	v_add_f32_e32 v104, v104, v105
	v_mul_f32_e32 v105, v187, v187
	v_add_f32_e32 v96, v96, v97
	v_mul_f32_e32 v97, v109, v109
	global_store_dword v[234:235], v104, off
	v_add_f32_e32 v104, v106, v112
	v_fmac_f32_e32 v105, v186, v186
	v_fmac_f32_e32 v97, v108, v108
	v_add_f32_e32 v110, v105, v104
	v_add_f32_e32 v96, v97, v96
	v_add_f32_e32 v112, v110, v96
	ds_bpermute_b32 v113, v175, v112
	v_lshl_add_u64 v[96:97], s[6:7], 0, v[230:231]
	v_lshl_add_u64 v[110:111], v[96:97], 0, v[160:161]
	v_cvt_pk_bf16_f32 v104, v116, v117
	v_cvt_pk_bf16_f32 v105, v118, v119
	v_cvt_pk_bf16_f32 v106, v188, v189
	v_cvt_pk_bf16_f32 v107, v186, v187
	global_store_dwordx4 v[110:111], v[104:107], off
	v_cvt_pk_bf16_f32 v96, v100, v101
	s_waitcnt lgkmcnt(0)
	v_add_f32_e32 v100, v112, v113
	ds_bpermute_b32 v101, v176, v100
	v_cvt_pk_bf16_f32 v97, v102, v103
	v_cvt_pk_bf16_f32 v98, v98, v99
	v_cvt_pk_bf16_f32 v99, v108, v109
	global_store_dwordx4 v[110:111], v[96:99], off offset:256
	v_pk_add_f32 v[94:95], v[94:95], v[220:221]
	v_pk_add_f32 v[92:93], v[92:93], v[218:219]
	v_lshlrev_b64 v[96:97], 6, v[170:171]
	v_lshl_add_u64 v[96:97], s[8:9], 0, v[96:97]
	v_lshl_add_u64 v[96:97], v[96:97], 0, s[20:21]
	s_waitcnt lgkmcnt(0)
	v_add_f32_e32 v98, v100, v101
	v_lshl_add_u64 v[96:97], v[96:97], 0, s[4:5]
	global_store_dword v[96:97], v98, off
	v_pk_add_f32 v[98:99], v[90:91], v[216:217]
	v_pk_add_f32 v[90:91], v[88:89], v[214:215]
	v_mul_f32_e32 v88, v93, v93
	v_mul_f32_e32 v89, v95, v95
	v_fmac_f32_e32 v88, v92, v92
	v_fmac_f32_e32 v89, v94, v94
	v_add_f32_e32 v88, v88, v89
	v_mul_f32_e32 v89, v91, v91
	v_fmac_f32_e32 v89, v90, v90
	v_add_f32_e32 v88, v88, v89
	v_mul_f32_e32 v89, v99, v99
	v_fmac_f32_e32 v89, v98, v98
	v_pk_add_f32 v[86:87], v[86:87], v[228:229]
	v_pk_add_f32 v[84:85], v[84:85], v[226:227]
	v_add_f32_e32 v100, v89, v88
	v_cvt_pk_bf16_f32 v88, v92, v93
	v_pk_add_f32 v[92:93], v[82:83], v[224:225]
	v_pk_add_f32 v[82:83], v[80:81], v[222:223]
	v_mul_f32_e32 v80, v85, v85
	v_mul_f32_e32 v81, v87, v87
	v_fmac_f32_e32 v80, v84, v84
	v_fmac_f32_e32 v81, v86, v86
	v_add_f32_e32 v80, v80, v81
	v_mul_f32_e32 v81, v83, v83
	v_fmac_f32_e32 v81, v82, v82
	v_add_f32_e32 v80, v80, v81
	v_mul_f32_e32 v81, v93, v93
	v_fmac_f32_e32 v81, v92, v92
	v_add_f32_e32 v80, v81, v80
	v_cvt_pk_bf16_f32 v89, v94, v95
	v_cvt_pk_bf16_f32 v90, v90, v91
	v_cvt_pk_bf16_f32 v91, v98, v99
	v_add_f32_e32 v98, v100, v80
	ds_bpermute_b32 v99, v175, v98
	v_lshlrev_b64 v[96:97], 11, v[168:169]
	v_lshl_add_u64 v[80:81], s[6:7], 0, v[96:97]
	v_lshl_add_u64 v[94:95], v[80:81], 0, v[160:161]
	global_store_dwordx4 v[94:95], v[88:91], off
	v_cvt_pk_bf16_f32 v80, v84, v85
	s_waitcnt lgkmcnt(0)
	v_add_f32_e32 v84, v98, v99
	ds_bpermute_b32 v85, v176, v84
	v_cvt_pk_bf16_f32 v81, v86, v87
	v_cvt_pk_bf16_f32 v82, v82, v83
	v_cvt_pk_bf16_f32 v83, v92, v93
	global_store_dwordx4 v[94:95], v[80:83], off offset:256
	v_pk_add_f32 v[78:79], v[78:79], v[142:143]
	v_pk_add_f32 v[76:77], v[76:77], v[140:141]
	v_lshlrev_b64 v[80:81], 6, v[168:169]
	v_lshl_add_u64 v[80:81], s[8:9], 0, v[80:81]
	v_lshl_add_u64 v[80:81], v[80:81], 0, s[20:21]
	s_waitcnt lgkmcnt(0)
; __device__ __forceinline__ float shx(float v, int lane, int mask) { return __int_as_float(__builtin_amdgcn_ds_bpermute((lane ^ mask) << 2, __float_as_int(v))); }
; __device__ __forceinline__ unsigned cvt_pk_bf16(float lo, float hi) { unsigned r; asm volatile("v_cvt_pk_bf16_f32 %0, %1, %2" : "=v"(r) : "v"(lo), "v"(hi)); return r; }
;     __device__ __forceinline__ void operator()(const f32x4 (&acc)[2][2][4][2], const Unit& u, int wr, int wc, int fr, int fq) const {
;     ...
;         for (int ai = 0; ai < 2; ++ai) {
;             f32x4 xv[4][2][2];
; #pragma unroll
;             for (int m = 0; m < 4; ++m)
; #pragma unroll
;                 for (int bj = 0; bj < 2; ++bj) {
;                     const size_t o = (size_t)(row0 + ai * 128 + m * 16) * 1024 + col0 + bj * 128;
;                     xv[m][bj][0] = *(const f32x4*)(x + o); xv[m][bj][1] = *(const f32x4*)(x + o + 4);
;                 }
; #pragma unroll
;             for (int m = 0; m < 4; ++m) {
;                 const int row = row0 + ai * 128 + m * 16; float ss = 0.f;
; #pragma unroll
;                 for (int bj = 0; bj < 2; ++bj) {
;                     const size_t o = (size_t)row * 1024 + col0 + bj * 128;
;                     const f32x4 v0 = xv[m][bj][0] + acc[ai][bj][m][0], v1 = xv[m][bj][1] + acc[ai][bj][m][1];
;                     ss += (v0[0] * v0[0] + v0[1] * v0[1]) + (v0[2] * v0[2] + v0[3] * v0[3]) + (v1[0] * v1[0] + v1[1] * v1[1]) + (v1[2] * v1[2] + v1[3] * v1[3]);
;                     u32x4 w; w.x = cvt_pk_bf16(v0[0], v0[1]); w.y = cvt_pk_bf16(v0[2], v0[3]); w.z = cvt_pk_bf16(v1[0], v1[1]); w.w = cvt_pk_bf16(v1[2], v1[3]);
;                     *(u32x4*)(x1b + o) = w;
;                 }
;                 ss += shx(ss, fq * 16 + fr, 16); ss += shx(ss, fq * 16 + fr, 32);
;                 ss2[(size_t)row * 16 + u.pn * 4 + wc] = ss;
;             }
	v_add_f32_e32 v82, v84, v85
	v_lshl_add_u64 v[80:81], v[80:81], 0, s[4:5]
	global_store_dword v[80:81], v82, off
	v_pk_add_f32 v[82:83], v[74:75], v[138:139]
	v_pk_add_f32 v[74:75], v[72:73], v[136:137]
	v_mul_f32_e32 v72, v77, v77
	v_mul_f32_e32 v73, v79, v79
	v_fmac_f32_e32 v72, v76, v76
	v_fmac_f32_e32 v73, v78, v78
	v_add_f32_e32 v72, v72, v73
	v_mul_f32_e32 v73, v75, v75
	v_fmac_f32_e32 v73, v74, v74
	v_add_f32_e32 v72, v72, v73
	v_mul_f32_e32 v73, v83, v83
	v_fmac_f32_e32 v73, v82, v82
	v_pk_add_f32 v[70:71], v[70:71], v[134:135]
	v_pk_add_f32 v[68:69], v[68:69], v[132:133]
	v_add_f32_e32 v84, v73, v72
	v_cvt_pk_bf16_f32 v72, v76, v77
	v_pk_add_f32 v[76:77], v[66:67], v[130:131]
	v_pk_add_f32 v[66:67], v[64:65], v[128:129]
	v_mul_f32_e32 v64, v69, v69
	v_mul_f32_e32 v65, v71, v71
	v_fmac_f32_e32 v64, v68, v68
	v_fmac_f32_e32 v65, v70, v70
	v_add_f32_e32 v64, v64, v65
	v_mul_f32_e32 v65, v67, v67
	v_fmac_f32_e32 v65, v66, v66
	v_add_f32_e32 v64, v64, v65
	v_mul_f32_e32 v65, v77, v77
	v_fmac_f32_e32 v65, v76, v76
	v_add_f32_e32 v64, v65, v64
	v_cvt_pk_bf16_f32 v73, v78, v79
	v_cvt_pk_bf16_f32 v74, v74, v75
	v_cvt_pk_bf16_f32 v75, v82, v83
	v_add_f32_e32 v82, v84, v64
	ds_bpermute_b32 v83, v175, v82
	v_lshlrev_b64 v[80:81], 11, v[166:167]
	v_lshl_add_u64 v[64:65], s[6:7], 0, v[80:81]
	v_lshl_add_u64 v[78:79], v[64:65], 0, v[160:161]
	global_store_dwordx4 v[78:79], v[72:75], off
	v_cvt_pk_bf16_f32 v64, v68, v69
	s_waitcnt lgkmcnt(0)
	v_add_f32_e32 v68, v82, v83
	ds_bpermute_b32 v69, v176, v68
	v_cvt_pk_bf16_f32 v65, v70, v71
	v_cvt_pk_bf16_f32 v66, v66, v67
	v_cvt_pk_bf16_f32 v67, v76, v77
	global_store_dwordx4 v[78:79], v[64:67], off offset:256
	v_add_u32_e32 v132, 0x80, v162
	v_ashrrev_i32_e32 v133, 31, v132
	v_lshlrev_b64 v[64:65], 6, v[166:167]
	v_lshl_add_u64 v[64:65], s[8:9], 0, v[64:65]
	v_lshl_add_u64 v[64:65], v[64:65], 0, s[20:21]
	s_waitcnt lgkmcnt(0)
	v_add_f32_e32 v66, v68, v69
	v_lshl_add_u64 v[64:65], v[64:65], 0, s[4:5]
	global_store_dword v[64:65], v66, off
	v_lshlrev_b64 v[64:65], 12, v[132:133]
	v_lshl_add_u64 v[64:65], v[164:165], 0, v[64:65]
	global_load_dwordx4 v[92:95], v[64:65], off
	global_load_dwordx4 v[96:99], v[64:65], off offset:16
	global_load_dwordx4 v[100:103], v[64:65], off offset:512
	global_load_dwordx4 v[104:107], v[64:65], off offset:528
	v_add_u32_e32 v134, 0x90, v162
	v_ashrrev_i32_e32 v135, 31, v134
	v_lshlrev_b64 v[64:65], 12, v[134:135]
	v_lshl_add_u64 v[64:65], v[164:165], 0, v[64:65]
	global_load_dwordx4 v[108:111], v[64:65], off
	global_load_dwordx4 v[112:115], v[64:65], off offset:16
	global_load_dwordx4 v[116:119], v[64:65], off offset:528
	global_load_dwordx4 v[120:123], v[64:65], off offset:512
	v_add_u32_e32 v90, 0xa0, v162
	v_ashrrev_i32_e32 v91, 31, v90
	v_lshlrev_b64 v[64:65], 12, v[90:91]
	v_lshl_add_u64 v[64:65], v[164:165], 0, v[64:65]
	global_load_dwordx4 v[124:127], v[64:65], off offset:16
	global_load_dwordx4 v[128:131], v[64:65], off
	global_load_dwordx4 v[80:83], v[64:65], off offset:528
	global_load_dwordx4 v[84:87], v[64:65], off offset:512
	v_add_u32_e32 v88, 0xb0, v162
	v_ashrrev_i32_e32 v89, 31, v88
	v_lshlrev_b64 v[64:65], 12, v[88:89]
	v_lshl_add_u64 v[68:69], v[164:165], 0, v[64:65]
	global_load_dwordx4 v[72:75], v[68:69], off offset:16
	global_load_dwordx4 v[76:79], v[68:69], off
	global_load_dwordx4 v[64:67], v[68:69], off offset:528
	s_nop 0
	global_load_dwordx4 v[68:71], v[68:69], off offset:512
	v_lshlrev_b64 v[136:137], 11, v[132:133]
	s_waitcnt vmcnt(15)
	v_pk_add_f32 v[62:63], v[62:63], v[94:95]
	v_pk_add_f32 v[60:61], v[60:61], v[92:93]
	s_waitcnt vmcnt(14)
	v_pk_add_f32 v[92:93], v[58:59], v[98:99]
	v_pk_add_f32 v[58:59], v[56:57], v[96:97]
	v_mul_f32_e32 v56, v61, v61
	v_mul_f32_e32 v57, v63, v63
	v_fmac_f32_e32 v56, v60, v60
	v_fmac_f32_e32 v57, v62, v62
	v_add_f32_e32 v56, v56, v57
	v_mul_f32_e32 v57, v59, v59
	v_fmac_f32_e32 v57, v58, v58
	v_add_f32_e32 v56, v56, v57
	v_mul_f32_e32 v57, v93, v93
	v_fmac_f32_e32 v57, v92, v92
	s_waitcnt vmcnt(13)
	v_pk_add_f32 v[54:55], v[54:55], v[102:103]
	v_pk_add_f32 v[52:53], v[52:53], v[100:101]
	v_add_f32_e32 v94, v57, v56
	v_cvt_pk_bf16_f32 v56, v60, v61
	s_waitcnt vmcnt(12)
	v_pk_add_f32 v[60:61], v[50:51], v[106:107]
	v_pk_add_f32 v[50:51], v[48:49], v[104:105]
	v_mul_f32_e32 v48, v53, v53
	v_mul_f32_e32 v49, v55, v55
	v_fmac_f32_e32 v48, v52, v52
	v_fmac_f32_e32 v49, v54, v54
	v_add_f32_e32 v48, v48, v49
	v_mul_f32_e32 v49, v51, v51
	v_fmac_f32_e32 v49, v50, v50
	v_add_f32_e32 v48, v48, v49
	v_mul_f32_e32 v49, v61, v61
	v_fmac_f32_e32 v49, v60, v60
	v_add_f32_e32 v48, v49, v48
	v_cvt_pk_bf16_f32 v57, v62, v63
	v_cvt_pk_bf16_f32 v58, v58, v59
	v_cvt_pk_bf16_f32 v59, v92, v93
	v_add_f32_e32 v92, v94, v48
	ds_bpermute_b32 v93, v175, v92
	v_lshl_add_u64 v[48:49], s[6:7], 0, v[136:137]
	v_lshl_add_u64 v[62:63], v[48:49], 0, v[160:161]
	global_store_dwordx4 v[62:63], v[56:59], off
	v_cvt_pk_bf16_f32 v48, v52, v53
	s_waitcnt lgkmcnt(0)
	v_add_f32_e32 v52, v92, v93
	ds_bpermute_b32 v53, v176, v52
	v_cvt_pk_bf16_f32 v49, v54, v55
	v_cvt_pk_bf16_f32 v50, v50, v51
	v_cvt_pk_bf16_f32 v51, v60, v61
	global_store_dwordx4 v[62:63], v[48:51], off offset:256
	s_waitcnt vmcnt(13)
	v_pk_add_f32 v[46:47], v[46:47], v[110:111]
	v_pk_add_f32 v[44:45], v[44:45], v[108:109]
	v_lshlrev_b64 v[48:49], 6, v[132:133]
	v_lshl_add_u64 v[48:49], s[8:9], 0, v[48:49]
	v_lshl_add_u64 v[48:49], v[48:49], 0, s[20:21]
	s_waitcnt lgkmcnt(0)
	v_add_f32_e32 v50, v52, v53
	v_lshl_add_u64 v[48:49], v[48:49], 0, s[4:5]
	global_store_dword v[48:49], v50, off
	s_waitcnt vmcnt(13)
; __device__ __forceinline__ float shx(float v, int lane, int mask) { return __int_as_float(__builtin_amdgcn_ds_bpermute((lane ^ mask) << 2, __float_as_int(v))); }
; __device__ __forceinline__ unsigned cvt_pk_bf16(float lo, float hi) { unsigned r; asm volatile("v_cvt_pk_bf16_f32 %0, %1, %2" : "=v"(r) : "v"(lo), "v"(hi)); return r; }
; #define PG8_WAIT_V(n) asm volatile("s_waitcnt vmcnt(" #n ")" ::: "memory")
; #define PG8_BAR __builtin_amdgcn_s_barrier()
; template <class Epi, class Sched>
; __device__ __forceinline__ void gemm_phase(const int wv, LAS unsigned char* lds, const Gemm g, const Sched& S, const Epi& E) {
;     ...
;     PG8_WAIT_V(0);
;     if (wr == 0) PG8_BAR;
;     PG8_BAR;
;     __device__ __forceinline__ void operator()(const f32x4 (&acc)[2][2][4][2], const Unit& u, int wr, int wc, int fr, int fq) const {
;     ...
; #pragma unroll
;             for (int m = 0; m < 4; ++m) {
;                 const int row = row0 + ai * 128 + m * 16; float ss = 0.f;
; #pragma unroll
;                 for (int bj = 0; bj < 2; ++bj) {
;                     const size_t o = (size_t)row * 1024 + col0 + bj * 128;
;                     const f32x4 v0 = xv[m][bj][0] + acc[ai][bj][m][0], v1 = xv[m][bj][1] + acc[ai][bj][m][1];
;                     ss += (v0[0] * v0[0] + v0[1] * v0[1]) + (v0[2] * v0[2] + v0[3] * v0[3]) + (v1[0] * v1[0] + v1[1] * v1[1]) + (v1[2] * v1[2] + v1[3] * v1[3]);
;                     u32x4 w; w.x = cvt_pk_bf16(v0[0], v0[1]); w.y = cvt_pk_bf16(v0[2], v0[3]); w.z = cvt_pk_bf16(v1[0], v1[1]); w.w = cvt_pk_bf16(v1[2], v1[3]);
;                     *(u32x4*)(x1b + o) = w;
;                 }
;                 ss += shx(ss, fq * 16 + fr, 16); ss += shx(ss, fq * 16 + fr, 32);
;                 ss2[(size_t)row * 16 + u.pn * 4 + wc] = ss;
;             }
	v_pk_add_f32 v[50:51], v[42:43], v[114:115]
	v_pk_add_f32 v[42:43], v[40:41], v[112:113]
	v_mul_f32_e32 v40, v45, v45
	v_mul_f32_e32 v41, v47, v47
	v_fmac_f32_e32 v40, v44, v44
	v_fmac_f32_e32 v41, v46, v46
	v_add_f32_e32 v40, v40, v41
	v_mul_f32_e32 v41, v43, v43
	v_fmac_f32_e32 v41, v42, v42
	v_add_f32_e32 v40, v40, v41
	v_mul_f32_e32 v41, v51, v51
	v_fmac_f32_e32 v41, v50, v50
	s_waitcnt vmcnt(11)
	v_pk_add_f32 v[38:39], v[38:39], v[122:123]
	v_pk_add_f32 v[36:37], v[36:37], v[120:121]
	v_add_f32_e32 v52, v41, v40
	v_cvt_pk_bf16_f32 v40, v44, v45
	v_pk_add_f32 v[44:45], v[34:35], v[118:119]
	v_pk_add_f32 v[34:35], v[32:33], v[116:117]
	v_mul_f32_e32 v32, v37, v37
	v_mul_f32_e32 v33, v39, v39
	v_fmac_f32_e32 v32, v36, v36
	v_fmac_f32_e32 v33, v38, v38
	v_add_f32_e32 v32, v32, v33
	v_mul_f32_e32 v33, v35, v35
	v_fmac_f32_e32 v33, v34, v34
	v_add_f32_e32 v32, v32, v33
	v_mul_f32_e32 v33, v45, v45
	v_fmac_f32_e32 v33, v44, v44
	v_add_f32_e32 v32, v33, v32
	v_cvt_pk_bf16_f32 v41, v46, v47
	v_cvt_pk_bf16_f32 v42, v42, v43
	v_cvt_pk_bf16_f32 v43, v50, v51
	v_add_f32_e32 v50, v52, v32
	ds_bpermute_b32 v51, v175, v50
	v_lshlrev_b64 v[48:49], 11, v[134:135]
	v_lshl_add_u64 v[32:33], s[6:7], 0, v[48:49]
	v_lshl_add_u64 v[46:47], v[32:33], 0, v[160:161]
	global_store_dwordx4 v[46:47], v[40:43], off
	v_cvt_pk_bf16_f32 v32, v36, v37
	s_waitcnt lgkmcnt(0)
	v_add_f32_e32 v36, v50, v51
	ds_bpermute_b32 v37, v176, v36
	v_cvt_pk_bf16_f32 v33, v38, v39
	v_cvt_pk_bf16_f32 v34, v34, v35
	v_cvt_pk_bf16_f32 v35, v44, v45
	global_store_dwordx4 v[46:47], v[32:35], off offset:256
	s_waitcnt vmcnt(11)
	v_pk_add_f32 v[30:31], v[30:31], v[130:131]
	v_pk_add_f32 v[28:29], v[28:29], v[128:129]
	v_lshlrev_b64 v[32:33], 6, v[134:135]
	v_lshl_add_u64 v[32:33], s[8:9], 0, v[32:33]
	v_lshl_add_u64 v[32:33], v[32:33], 0, s[20:21]
	s_waitcnt lgkmcnt(0)
	v_add_f32_e32 v34, v36, v37
	v_lshl_add_u64 v[32:33], v[32:33], 0, s[4:5]
	global_store_dword v[32:33], v34, off
	v_pk_add_f32 v[34:35], v[26:27], v[126:127]
	v_pk_add_f32 v[26:27], v[24:25], v[124:125]
	v_mul_f32_e32 v24, v29, v29
	v_mul_f32_e32 v25, v31, v31
	v_fmac_f32_e32 v24, v28, v28
	v_fmac_f32_e32 v25, v30, v30
	v_add_f32_e32 v24, v24, v25
	v_mul_f32_e32 v25, v27, v27
	v_fmac_f32_e32 v25, v26, v26
	v_add_f32_e32 v24, v24, v25
	v_mul_f32_e32 v25, v35, v35
	v_fmac_f32_e32 v25, v34, v34
	s_waitcnt vmcnt(10)
	v_pk_add_f32 v[22:23], v[22:23], v[86:87]
	v_pk_add_f32 v[20:21], v[20:21], v[84:85]
	v_add_f32_e32 v36, v25, v24
	v_cvt_pk_bf16_f32 v24, v28, v29
	v_pk_add_f32 v[28:29], v[18:19], v[82:83]
	v_pk_add_f32 v[18:19], v[16:17], v[80:81]
	v_mul_f32_e32 v16, v21, v21
	v_mul_f32_e32 v17, v23, v23
	v_fmac_f32_e32 v16, v20, v20
	v_fmac_f32_e32 v17, v22, v22
	v_add_f32_e32 v16, v16, v17
	v_mul_f32_e32 v17, v19, v19
	v_fmac_f32_e32 v17, v18, v18
	v_add_f32_e32 v16, v16, v17
	v_mul_f32_e32 v17, v29, v29
	v_fmac_f32_e32 v17, v28, v28
	v_add_f32_e32 v16, v17, v16
	v_cvt_pk_bf16_f32 v25, v30, v31
	v_cvt_pk_bf16_f32 v26, v26, v27
	v_cvt_pk_bf16_f32 v27, v34, v35
	v_add_f32_e32 v34, v36, v16
	ds_bpermute_b32 v35, v175, v34
	v_lshlrev_b64 v[32:33], 11, v[90:91]
	v_lshl_add_u64 v[16:17], s[6:7], 0, v[32:33]
	v_lshl_add_u64 v[30:31], v[16:17], 0, v[160:161]
	global_store_dwordx4 v[30:31], v[24:27], off
	v_cvt_pk_bf16_f32 v16, v20, v21
	s_waitcnt lgkmcnt(0)
	v_add_f32_e32 v20, v34, v35
	ds_bpermute_b32 v21, v176, v20
	v_cvt_pk_bf16_f32 v17, v22, v23
	v_cvt_pk_bf16_f32 v18, v18, v19
	v_cvt_pk_bf16_f32 v19, v28, v29
	global_store_dwordx4 v[30:31], v[16:19], off offset:256
	s_waitcnt vmcnt(10)
	v_pk_add_f32 v[14:15], v[14:15], v[78:79]
	v_pk_add_f32 v[12:13], v[12:13], v[76:77]
	v_lshlrev_b64 v[16:17], 6, v[90:91]
	v_lshl_add_u64 v[16:17], s[8:9], 0, v[16:17]
	v_lshl_add_u64 v[16:17], v[16:17], 0, s[20:21]
	s_waitcnt lgkmcnt(0)
	v_add_f32_e32 v18, v20, v21
	v_lshl_add_u64 v[16:17], v[16:17], 0, s[4:5]
	global_store_dword v[16:17], v18, off
	v_pk_add_f32 v[18:19], v[10:11], v[74:75]
	v_pk_add_f32 v[10:11], v[8:9], v[72:73]
	v_mul_f32_e32 v8, v13, v13
	v_mul_f32_e32 v9, v15, v15
	v_fmac_f32_e32 v8, v12, v12
	v_fmac_f32_e32 v9, v14, v14
	v_add_f32_e32 v8, v8, v9
	v_mul_f32_e32 v9, v11, v11
	v_fmac_f32_e32 v9, v10, v10
	v_add_f32_e32 v8, v8, v9
	v_mul_f32_e32 v9, v19, v19
	v_fmac_f32_e32 v9, v18, v18
	s_waitcnt vmcnt(9)
	v_pk_add_f32 v[6:7], v[6:7], v[70:71]
	v_pk_add_f32 v[4:5], v[4:5], v[68:69]
	v_add_f32_e32 v20, v9, v8
	v_cvt_pk_bf16_f32 v8, v12, v13
	v_pk_add_f32 v[12:13], v[2:3], v[66:67]
	v_pk_add_f32 v[2:3], v[0:1], v[64:65]
	v_mul_f32_e32 v0, v5, v5
	v_mul_f32_e32 v1, v7, v7
	v_fmac_f32_e32 v0, v4, v4
	v_fmac_f32_e32 v1, v6, v6
	v_add_f32_e32 v0, v0, v1
	v_mul_f32_e32 v1, v3, v3
	v_fmac_f32_e32 v1, v2, v2
	v_add_f32_e32 v0, v0, v1
	v_mul_f32_e32 v1, v13, v13
	v_fmac_f32_e32 v1, v12, v12
	v_add_f32_e32 v0, v1, v0
	v_cvt_pk_bf16_f32 v9, v14, v15
	v_cvt_pk_bf16_f32 v10, v10, v11
	v_cvt_pk_bf16_f32 v11, v18, v19
	v_add_f32_e32 v18, v20, v0
	ds_bpermute_b32 v19, v175, v18
	v_lshlrev_b64 v[16:17], 11, v[88:89]
	v_lshl_add_u64 v[0:1], s[6:7], 0, v[16:17]
	v_lshl_add_u64 v[14:15], v[0:1], 0, v[160:161]
	global_store_dwordx4 v[14:15], v[8:11], off
	v_cvt_pk_bf16_f32 v0, v4, v5
	s_waitcnt lgkmcnt(0)
	v_add_f32_e32 v4, v18, v19
	ds_bpermute_b32 v5, v176, v4
	v_cvt_pk_bf16_f32 v1, v6, v7
	v_cvt_pk_bf16_f32 v2, v2, v3
	v_cvt_pk_bf16_f32 v3, v12, v13
	global_store_dwordx4 v[14:15], v[0:3], off offset:256
	s_nop 1
	v_lshlrev_b64 v[0:1], 6, v[88:89]
	v_lshl_add_u64 v[0:1], s[8:9], 0, v[0:1]
	v_lshl_add_u64 v[0:1], v[0:1], 0, s[20:21]
	s_waitcnt lgkmcnt(0)
	v_add_f32_e32 v2, v4, v5
	v_lshl_add_u64 v[0:1], v[0:1], 0, s[4:5]
	s_mov_b32 s21, s12
	s_mov_b32 s20, s14
	global_store_dword v[0:1], v2, off
	s_cbranch_vccz .LBB0_654
	s_waitcnt vmcnt(0)
	s_cmpk_gt_u32 s28, 0xff
	s_cbranch_scc1 .LBB0_665
	s_barrier

; #define PG8_STAGE(bufoff, gbase, voff) do { _Pragma("unroll") for (int _i = 0; _i < 2; ++_i) \
;         __builtin_amdgcn_global_load_lds((const unsigned*)((const char*)(gbase) + (voff)[_i]), (LAS unsigned*)(lds + (bufoff) + ldsw + _i * 8192), 16, 0, 0); } while (0)
; #define PG8_LDA(dst, b, h) do { _Pragma("unroll") for (int m = 0; m < 4; ++m) _Pragma("unroll") for (int k = 0; k < 2; ++k) dst[m][k] = *(const LAS bf16x8*)(lds + PG8_SA(b, h) + aoff + m * 2048 + k * 1024); } while (0)
; #define PG8_WAIT_V(n) asm volatile("s_waitcnt vmcnt(" #n ")" ::: "memory")
; template <class Epi, class Sched>
; __device__ __forceinline__ void gemm_phase(const int wv, LAS unsigned char* lds, const Gemm g, const Sched& S, const Epi& E) {
;     ...
;         for (int t = 0; t < nt; t += 2) {
;             const bool last = (t == nt - 2);
;             const char* a1 = cA + (size_t)(t + 1) * kstepA;
;             const char* a2 = last ? nA : cA + (size_t)(t + 2) * kstepA; const char* b2 = last ? nB : cB + (size_t)(t + 2) * kstep;
;             const char* a3 = a2 + kstepA; const char* b3 = b2 + kstep;
;             if (last && has_next) S.a_ready(nxt);
;             PG8_LDB(B0, 0, 0); PG8_SCHED; PG8_LDA(At, 0, 0); PG8_STAGE(PG8_SA(1, 1), a1 + hstepA, voffA);
;             PG8_WAIT_L(8); PG8_BAR; PG8_WAIT_L(0); PG8_MMA(0, 0, At, B0); PG8_BAR; PG8_SCHED;
;             PG8_LDB(B1, 0, 1); PG8_STAGE(PG8_SB(0, 0), b2, voffB);
;             PG8_BAR; PG8_WAIT_L(0); PG8_MMA(0, 1, At, B1); PG8_BAR;
;             PG8_LDA(At, 0, 1); PG8_STAGE(PG8_SA(0, 0), a2, voffA);
;             PG8_BAR; PG8_WAIT_L(0); PG8_MMA(1, 0, At, B0); PG8_BAR; PG8_SCHED;
;             PG8_STAGE(PG8_SB(0, 1), b2 + hstepB, voffB);
;             PG8_WAIT_V(6); PG8_BAR; PG8_MMA(1, 1, At, B1); PG8_BAR;
;             PG8_LDB(B0, 1, 0); PG8_SCHED; PG8_LDA(At, 1, 0); PG8_STAGE(PG8_SA(0, 1), a2 + hstepA, voffA);
;             PG8_WAIT_L(8); PG8_BAR; PG8_WAIT_L(0); PG8_MMA(0, 0, At, B0); PG8_BAR; PG8_SCHED;
;             PG8_LDB(B1, 1, 1); PG8_STAGE(PG8_SB(1, 0), b3, voffB);
;             PG8_BAR; PG8_WAIT_L(0); PG8_MMA(0, 1, At, B1); PG8_BAR;
;             PG8_LDA(At, 1, 1); PG8_STAGE(PG8_SA(1, 0), a3, voffA);
;             PG8_BAR; PG8_WAIT_L(0); PG8_MMA(1, 0, At, B0); PG8_BAR; PG8_SCHED;
;             PG8_STAGE(PG8_SB(1, 1), b3 + hstepB, voffB);
;             PG8_WAIT_V(6); PG8_BAR; PG8_MMA(1, 1, At, B1); PG8_BAR;
.LBB0_725:
	ds_read_b128 v[128:131], v176
	ds_read_b128 v[132:135], v176 offset:1024
	ds_read_b128 v[136:139], v176 offset:2048
	ds_read_b128 v[140:143], v176 offset:3072
	s_add_u32 s18, s16, 0xfffc0080
	s_addc_u32 s19, s17, -1
	s_cmp_eq_u32 s46, 12
	s_cselect_b32 s21, s9, s19
	s_cselect_b32 s20, s42, s18
	s_cselect_b32 s19, s7, s45
	s_cselect_b32 s18, s43, s44
	v_lshl_add_u64 v[170:171], s[16:17], 0, v[160:161]
	s_add_i32 m0, s28, 0xc000
	ds_read_b128 v[144:147], v177
	ds_read_b128 v[182:185], v177 offset:1024
	ds_read_b128 v[186:189], v177 offset:2048
	ds_read_b128 v[190:193], v177 offset:3072
	ds_read_b128 v[194:197], v177 offset:4096
	ds_read_b128 v[198:201], v177 offset:5120
	ds_read_b128 v[202:205], v177 offset:6144
	ds_read_b128 v[206:209], v177 offset:7168
	global_load_lds_dwordx4 v[170:171], off
	s_add_i32 m0, s28, 0xe000
	v_lshl_add_u64 v[170:171], s[16:17], 0, v[162:163]
	global_load_lds_dwordx4 v[170:171], off
	s_waitcnt lgkmcnt(8)
	s_barrier
	s_waitcnt lgkmcnt(0)
	v_mfma_f32_16x16x32_bf16 v[124:127], v[128:131], v[144:147], v[124:127]
	v_mfma_f32_16x16x32_bf16 v[120:123], v[136:139], v[144:147], v[120:123]
	v_mfma_f32_16x16x32_bf16 v[108:111], v[128:131], v[186:189], v[108:111]
	v_mfma_f32_16x16x32_bf16 v[104:107], v[136:139], v[186:189], v[104:107]
	v_mfma_f32_16x16x32_bf16 v[92:95], v[128:131], v[194:197], v[92:95]
	v_mfma_f32_16x16x32_bf16 v[88:91], v[136:139], v[194:197], v[88:91]
	v_mfma_f32_16x16x32_bf16 v[76:79], v[128:131], v[202:205], v[76:79]
	v_mfma_f32_16x16x32_bf16 v[72:75], v[136:139], v[202:205], v[72:75]
	v_mfma_f32_16x16x32_bf16 v[124:127], v[132:135], v[182:185], v[124:127]
	v_mfma_f32_16x16x32_bf16 v[120:123], v[140:143], v[182:185], v[120:123]
	v_mfma_f32_16x16x32_bf16 v[108:111], v[132:135], v[190:193], v[108:111]
	v_mfma_f32_16x16x32_bf16 v[104:107], v[140:143], v[190:193], v[104:107]
	v_mfma_f32_16x16x32_bf16 v[92:95], v[132:135], v[198:201], v[92:95]
	v_mfma_f32_16x16x32_bf16 v[88:91], v[140:143], v[198:201], v[88:91]
	v_mfma_f32_16x16x32_bf16 v[76:79], v[132:135], v[206:209], v[76:79]
	v_mfma_f32_16x16x32_bf16 v[72:75], v[140:143], v[206:209], v[72:75]
	s_barrier
	s_add_i32 s47, s39, s27
	v_lshl_add_u64 v[170:171], s[18:19], 0, v[150:151]
	s_mov_b32 m0, s47
	ds_read_b128 v[210:213], v180
	ds_read_b128 v[214:217], v180 offset:1024
	ds_read_b128 v[218:221], v180 offset:2048
	ds_read_b128 v[222:225], v180 offset:3072
	global_load_lds_dwordx4 v[170:171], off
	s_add_i32 m0, s47, 0x2000
	v_lshl_add_u64 v[226:227], s[18:19], 0, v[154:155]
	global_load_lds_dwordx4 v[226:227], off
	s_barrier
	s_waitcnt lgkmcnt(0)
	v_mfma_f32_16x16x32_bf16 v[116:119], v[210:213], v[144:147], v[116:119]
	v_mfma_f32_16x16x32_bf16 v[112:115], v[218:221], v[144:147], v[112:115]
	v_mfma_f32_16x16x32_bf16 v[100:103], v[210:213], v[186:189], v[100:103]
	v_mfma_f32_16x16x32_bf16 v[96:99], v[218:221], v[186:189], v[96:99]
	v_mfma_f32_16x16x32_bf16 v[84:87], v[210:213], v[194:197], v[84:87]
	v_mfma_f32_16x16x32_bf16 v[80:83], v[218:221], v[194:197], v[80:83]
	v_mfma_f32_16x16x32_bf16 v[68:71], v[210:213], v[202:205], v[68:71]
	v_mfma_f32_16x16x32_bf16 v[64:67], v[218:221], v[202:205], v[64:67]
	v_mfma_f32_16x16x32_bf16 v[116:119], v[214:217], v[182:185], v[116:119]
	v_mfma_f32_16x16x32_bf16 v[112:115], v[222:225], v[182:185], v[112:115]
	v_mfma_f32_16x16x32_bf16 v[100:103], v[214:217], v[190:193], v[100:103]
	v_mfma_f32_16x16x32_bf16 v[96:99], v[222:225], v[190:193], v[96:99]
	v_mfma_f32_16x16x32_bf16 v[84:87], v[214:217], v[198:201], v[84:87]
	v_mfma_f32_16x16x32_bf16 v[80:83], v[222:225], v[198:201], v[80:83]
	v_mfma_f32_16x16x32_bf16 v[68:71], v[214:217], v[206:209], v[68:71]
	v_mfma_f32_16x16x32_bf16 v[64:67], v[222:225], v[206:209], v[64:67]
	s_mov_b32 m0, s28
	v_lshl_add_u64 v[228:229], s[20:21], 0, v[148:149]
	s_barrier
	ds_read_b128 v[144:147], v177 offset:16384
	ds_read_b128 v[182:185], v177 offset:17408
	ds_read_b128 v[186:189], v177 offset:18432
	ds_read_b128 v[190:193], v177 offset:19456
	ds_read_b128 v[194:197], v177 offset:20480
	ds_read_b128 v[198:201], v177 offset:21504
	ds_read_b128 v[202:205], v177 offset:22528
	ds_read_b128 v[206:209], v177 offset:23552
	global_load_lds_dwordx4 v[228:229], off
	s_mov_b32 m0, s29
	v_lshl_add_u64 v[230:231], s[20:21], 0, v[152:153]
	global_load_lds_dwordx4 v[230:231], off
	s_barrier
	s_waitcnt lgkmcnt(0)
	v_mfma_f32_16x16x32_bf16 v[60:63], v[128:131], v[144:147], v[60:63]
	v_mfma_f32_16x16x32_bf16 v[56:59], v[136:139], v[144:147], v[56:59]
	v_mfma_f32_16x16x32_bf16 v[44:47], v[128:131], v[186:189], v[44:47]
	v_mfma_f32_16x16x32_bf16 v[40:43], v[136:139], v[186:189], v[40:43]
	v_mfma_f32_16x16x32_bf16 v[28:31], v[128:131], v[194:197], v[28:31]
	v_mfma_f32_16x16x32_bf16 v[24:27], v[136:139], v[194:197], v[24:27]
	v_mfma_f32_16x16x32_bf16 v[12:15], v[128:131], v[202:205], v[12:15]
	v_mfma_f32_16x16x32_bf16 v[8:11], v[136:139], v[202:205], v[8:11]
	v_mfma_f32_16x16x32_bf16 v[60:63], v[132:135], v[182:185], v[60:63]
	v_mfma_f32_16x16x32_bf16 v[56:59], v[140:143], v[182:185], v[56:59]
	v_mfma_f32_16x16x32_bf16 v[44:47], v[132:135], v[190:193], v[44:47]
	v_mfma_f32_16x16x32_bf16 v[40:43], v[140:143], v[190:193], v[40:43]
	v_mfma_f32_16x16x32_bf16 v[28:31], v[132:135], v[198:201], v[28:31]
	v_mfma_f32_16x16x32_bf16 v[24:27], v[140:143], v[198:201], v[24:27]
	v_mfma_f32_16x16x32_bf16 v[12:15], v[132:135], v[206:209], v[12:15]
	v_mfma_f32_16x16x32_bf16 v[8:11], v[140:143], v[206:209], v[8:11]
	s_barrier
	s_add_u32 s48, s18, 0x40000
	s_addc_u32 s49, s19, 0
	s_add_i32 s47, s40, s27
	s_mov_b32 m0, s47
	v_lshl_add_u64 v[128:129], s[48:49], 0, v[150:151]
	global_load_lds_dwordx4 v[128:129], off
	s_add_i32 m0, s47, 0x2000
	v_lshl_add_u64 v[128:129], s[48:49], 0, v[154:155]
	global_load_lds_dwordx4 v[128:129], off
	s_waitcnt vmcnt(6)
	s_barrier
; #define PG8_STAGE(bufoff, gbase, voff) do { _Pragma("unroll") for (int _i = 0; _i < 2; ++_i) \
;         __builtin_amdgcn_global_load_lds((const unsigned*)((const char*)(gbase) + (voff)[_i]), (LAS unsigned*)(lds + (bufoff) + ldsw + _i * 8192), 16, 0, 0); } while (0)
; #define PG8_LDA(dst, b, h) do { _Pragma("unroll") for (int m = 0; m < 4; ++m) _Pragma("unroll") for (int k = 0; k < 2; ++k) dst[m][k] = *(const LAS bf16x8*)(lds + PG8_SA(b, h) + aoff + m * 2048 + k * 1024); } while (0)
; #define PG8_LDB(dst, b, h) do { _Pragma("unroll") for (int n = 0; n < 2; ++n) _Pragma("unroll") for (int k = 0; k < 2; ++k) dst[n][k] = *(const LAS bf16x8*)(lds + PG8_SB(b, h) + boff + n * 2048 + k * 1024); } while (0)
; #define PG8_WAIT_V(n) asm volatile("s_waitcnt vmcnt(" #n ")" ::: "memory")
; #define PG8_WAIT_L(n) asm volatile("s_waitcnt lgkmcnt(" #n ")" ::: "memory")
; #define PG8_BAR __builtin_amdgcn_s_barrier()
; #define PG8_SCHED __builtin_amdgcn_sched_barrier(0)
; template <class Epi, class Sched>
; __device__ __forceinline__ void gemm_phase(const int wv, LAS unsigned char* lds, const Gemm g, const Sched& S, const Epi& E) {
;     ...
;             PG8_LDB(B0, 0, 0); PG8_SCHED; PG8_LDA(At, 0, 0); PG8_STAGE(PG8_SA(1, 1), a1 + hstepA, voffA);
;             PG8_WAIT_L(8); PG8_BAR; PG8_WAIT_L(0); PG8_MMA(0, 0, At, B0); PG8_BAR; PG8_SCHED;
;             PG8_LDB(B1, 0, 1); PG8_STAGE(PG8_SB(0, 0), b2, voffB);
;             PG8_BAR; PG8_WAIT_L(0); PG8_MMA(0, 1, At, B1); PG8_BAR;
;             PG8_LDA(At, 0, 1); PG8_STAGE(PG8_SA(0, 0), a2, voffA);
;             PG8_BAR; PG8_WAIT_L(0); PG8_MMA(1, 0, At, B0); PG8_BAR; PG8_SCHED;
;             PG8_STAGE(PG8_SB(0, 1), b2 + hstepB, voffB);
;             PG8_WAIT_V(6); PG8_BAR; PG8_MMA(1, 1, At, B1); PG8_BAR;
;             PG8_LDB(B0, 1, 0); PG8_SCHED; PG8_LDA(At, 1, 0); PG8_STAGE(PG8_SA(0, 1), a2 + hstepA, voffA);
;             PG8_WAIT_L(8); PG8_BAR; PG8_WAIT_L(0); PG8_MMA(0, 0, At, B0); PG8_BAR; PG8_SCHED;
;             PG8_LDB(B1, 1, 1); PG8_STAGE(PG8_SB(1, 0), b3, voffB);
;             PG8_BAR; PG8_WAIT_L(0); PG8_MMA(0, 1, At, B1); PG8_BAR;
;             PG8_LDA(At, 1, 1); PG8_STAGE(PG8_SA(1, 0), a3, voffA);
;             PG8_BAR; PG8_WAIT_L(0); PG8_MMA(1, 0, At, B0); PG8_BAR; PG8_SCHED;
;             PG8_STAGE(PG8_SB(1, 1), b3 + hstepB, voffB);
;             PG8_WAIT_V(6); PG8_BAR; PG8_MMA(1, 1, At, B1); PG8_BAR;
	v_mfma_f32_16x16x32_bf16 v[52:55], v[210:213], v[144:147], v[52:55]
	v_mfma_f32_16x16x32_bf16 v[48:51], v[218:221], v[144:147], v[48:51]
	v_mfma_f32_16x16x32_bf16 v[36:39], v[210:213], v[186:189], v[36:39]
	v_mfma_f32_16x16x32_bf16 v[32:35], v[218:221], v[186:189], v[32:35]
	v_mfma_f32_16x16x32_bf16 v[20:23], v[210:213], v[194:197], v[20:23]
	v_mfma_f32_16x16x32_bf16 v[16:19], v[218:221], v[194:197], v[16:19]
	v_mfma_f32_16x16x32_bf16 v[4:7], v[210:213], v[202:205], v[4:7]
	v_mfma_f32_16x16x32_bf16 v[0:3], v[218:221], v[202:205], v[0:3]
	v_mfma_f32_16x16x32_bf16 v[52:55], v[214:217], v[182:185], v[52:55]
	v_mfma_f32_16x16x32_bf16 v[48:51], v[222:225], v[182:185], v[48:51]
	v_mfma_f32_16x16x32_bf16 v[36:39], v[214:217], v[190:193], v[36:39]
	v_mfma_f32_16x16x32_bf16 v[32:35], v[222:225], v[190:193], v[32:35]
	v_mfma_f32_16x16x32_bf16 v[20:23], v[214:217], v[198:201], v[20:23]
	v_mfma_f32_16x16x32_bf16 v[16:19], v[222:225], v[198:201], v[16:19]
	v_mfma_f32_16x16x32_bf16 v[4:7], v[214:217], v[206:209], v[4:7]
	v_mfma_f32_16x16x32_bf16 v[0:3], v[222:225], v[206:209], v[0:3]
	s_add_i32 s47, 0, 0x18000
	v_add_u32_e32 v140, s47, v173
	s_barrier
	ds_read_b128 v[128:131], v140
	ds_read_b128 v[132:135], v140 offset:1024
	ds_read_b128 v[136:139], v140 offset:2048
	ds_read_b128 v[140:143], v140 offset:3072
	s_add_u32 s20, s20, 0x40000
	s_addc_u32 s21, s21, 0
	s_mov_b32 m0, s30
	v_lshl_add_u64 v[210:211], s[20:21], 0, v[148:149]
	ds_read_b128 v[144:147], v177 offset:32768
	ds_read_b128 v[182:185], v177 offset:33792
	ds_read_b128 v[186:189], v177 offset:34816
	ds_read_b128 v[190:193], v177 offset:35840
	ds_read_b128 v[194:197], v177 offset:36864
	ds_read_b128 v[198:201], v177 offset:37888
	ds_read_b128 v[202:205], v177 offset:38912
	ds_read_b128 v[206:209], v177 offset:39936
	global_load_lds_dwordx4 v[210:211], off
	s_mov_b32 m0, s31
	v_lshl_add_u64 v[210:211], s[20:21], 0, v[152:153]
	global_load_lds_dwordx4 v[210:211], off
	s_waitcnt lgkmcnt(8)
	s_barrier
	s_waitcnt lgkmcnt(0)
	v_mfma_f32_16x16x32_bf16 v[124:127], v[128:131], v[144:147], v[124:127]
	v_mfma_f32_16x16x32_bf16 v[120:123], v[136:139], v[144:147], v[120:123]
	v_mfma_f32_16x16x32_bf16 v[108:111], v[128:131], v[186:189], v[108:111]
	v_mfma_f32_16x16x32_bf16 v[104:107], v[136:139], v[186:189], v[104:107]
	v_mfma_f32_16x16x32_bf16 v[92:95], v[128:131], v[194:197], v[92:95]
	v_mfma_f32_16x16x32_bf16 v[88:91], v[136:139], v[194:197], v[88:91]
	v_mfma_f32_16x16x32_bf16 v[76:79], v[128:131], v[202:205], v[76:79]
	v_mfma_f32_16x16x32_bf16 v[72:75], v[136:139], v[202:205], v[72:75]
	v_mfma_f32_16x16x32_bf16 v[124:127], v[132:135], v[182:185], v[124:127]
	v_mfma_f32_16x16x32_bf16 v[120:123], v[140:143], v[182:185], v[120:123]
	v_mfma_f32_16x16x32_bf16 v[108:111], v[132:135], v[190:193], v[108:111]
	v_mfma_f32_16x16x32_bf16 v[104:107], v[140:143], v[190:193], v[104:107]
	v_mfma_f32_16x16x32_bf16 v[92:95], v[132:135], v[198:201], v[92:95]
	v_mfma_f32_16x16x32_bf16 v[88:91], v[140:143], v[198:201], v[88:91]
	v_mfma_f32_16x16x32_bf16 v[76:79], v[132:135], v[206:209], v[76:79]
	v_mfma_f32_16x16x32_bf16 v[72:75], v[140:143], v[206:209], v[72:75]
	s_barrier
	s_add_i32 s20, 0, 0x1c000
	s_add_i32 s21, s47, s27
	v_add_u32_e32 v156, s20, v173
	v_lshl_add_u64 v[170:171], v[170:171], 0, s[4:5]
	s_mov_b32 m0, s21
	ds_read_b128 v[210:213], v156
	ds_read_b128 v[214:217], v156 offset:1024
	ds_read_b128 v[218:221], v156 offset:2048
	ds_read_b128 v[222:225], v156 offset:3072
	global_load_lds_dwordx4 v[170:171], off
	s_add_i32 m0, s21, 0x2000
	v_lshl_add_u64 v[170:171], v[226:227], 0, s[4:5]
	global_load_lds_dwordx4 v[170:171], off
	s_barrier
	s_waitcnt lgkmcnt(0)
	v_mfma_f32_16x16x32_bf16 v[116:119], v[210:213], v[144:147], v[116:119]
	v_mfma_f32_16x16x32_bf16 v[112:115], v[218:221], v[144:147], v[112:115]
	v_mfma_f32_16x16x32_bf16 v[100:103], v[210:213], v[186:189], v[100:103]
	v_mfma_f32_16x16x32_bf16 v[96:99], v[218:221], v[186:189], v[96:99]
	v_mfma_f32_16x16x32_bf16 v[84:87], v[210:213], v[194:197], v[84:87]
	v_mfma_f32_16x16x32_bf16 v[80:83], v[218:221], v[194:197], v[80:83]
	v_mfma_f32_16x16x32_bf16 v[68:71], v[210:213], v[202:205], v[68:71]
	v_mfma_f32_16x16x32_bf16 v[64:67], v[218:221], v[202:205], v[64:67]
	v_mfma_f32_16x16x32_bf16 v[116:119], v[214:217], v[182:185], v[116:119]
	v_mfma_f32_16x16x32_bf16 v[112:115], v[222:225], v[182:185], v[112:115]
	v_mfma_f32_16x16x32_bf16 v[100:103], v[214:217], v[190:193], v[100:103]
	v_mfma_f32_16x16x32_bf16 v[96:99], v[222:225], v[190:193], v[96:99]
	v_mfma_f32_16x16x32_bf16 v[84:87], v[214:217], v[198:201], v[84:87]
	v_mfma_f32_16x16x32_bf16 v[80:83], v[222:225], v[198:201], v[80:83]
	v_mfma_f32_16x16x32_bf16 v[68:71], v[214:217], v[206:209], v[68:71]
	v_mfma_f32_16x16x32_bf16 v[64:67], v[222:225], v[206:209], v[64:67]
	s_mov_b32 m0, s37
	v_lshl_add_u64 v[170:171], v[228:229], 0, s[4:5]
	s_barrier
	ds_read_b128 v[144:147], v177 offset:49152
	ds_read_b128 v[182:185], v177 offset:50176
	ds_read_b128 v[186:189], v177 offset:51200
	ds_read_b128 v[190:193], v177 offset:52224
	ds_read_b128 v[194:197], v177 offset:53248
	ds_read_b128 v[198:201], v177 offset:54272
	ds_read_b128 v[202:205], v177 offset:55296
	ds_read_b128 v[206:209], v177 offset:56320
	global_load_lds_dwordx4 v[170:171], off
	s_mov_b32 m0, s38
	v_lshl_add_u64 v[170:171], v[230:231], 0, s[4:5]
	global_load_lds_dwordx4 v[170:171], off
	s_barrier
; __device__ __forceinline__ float shx(float v, int lane, int mask) { return __int_as_float(__builtin_amdgcn_ds_bpermute((lane ^ mask) << 2, __float_as_int(v))); }
; #define PG8_STAGE(bufoff, gbase, voff) do { _Pragma("unroll") for (int _i = 0; _i < 2; ++_i) \
;         __builtin_amdgcn_global_load_lds((const unsigned*)((const char*)(gbase) + (voff)[_i]), (LAS unsigned*)(lds + (bufoff) + ldsw + _i * 8192), 16, 0, 0); } while (0)
; #define PG8_LDA(dst, b, h) do { _Pragma("unroll") for (int m = 0; m < 4; ++m) _Pragma("unroll") for (int k = 0; k < 2; ++k) dst[m][k] = *(const LAS bf16x8*)(lds + PG8_SA(b, h) + aoff + m * 2048 + k * 1024); } while (0)
; #define PG8_BAR __builtin_amdgcn_s_barrier()
; template <class Epi, class Sched>
; __device__ __forceinline__ void gemm_phase(const int wv, LAS unsigned char* lds, const Gemm g, const Sched& S, const Epi& E) {
;     ...
;             PG8_WAIT_V(6); PG8_BAR; PG8_MMA(1, 1, At, B1); PG8_BAR;
;             PG8_LDB(B0, 1, 0); PG8_SCHED; PG8_LDA(At, 1, 0); PG8_STAGE(PG8_SA(0, 1), a2 + hstepA, voffA);
;             PG8_WAIT_L(8); PG8_BAR; PG8_WAIT_L(0); PG8_MMA(0, 0, At, B0); PG8_BAR; PG8_SCHED;
;             PG8_LDB(B1, 1, 1); PG8_STAGE(PG8_SB(1, 0), b3, voffB);
;             PG8_BAR; PG8_WAIT_L(0); PG8_MMA(0, 1, At, B1); PG8_BAR;
;             PG8_LDA(At, 1, 1); PG8_STAGE(PG8_SA(1, 0), a3, voffA);
;             PG8_BAR; PG8_WAIT_L(0); PG8_MMA(1, 0, At, B0); PG8_BAR; PG8_SCHED;
;             PG8_STAGE(PG8_SB(1, 1), b3 + hstepB, voffB);
;             PG8_WAIT_V(6); PG8_BAR; PG8_MMA(1, 1, At, B1); PG8_BAR;
;         }
;     __device__ __forceinline__ void operator()(const f32x4 (&acc)[2][2][4][2], const Unit& u, int wr, int wc, int fr, int fq) const {
;         const int row0 = u.pm * 256 + wr * 64 + fr; const int col0 = u.pn * 256 + wc * 32 + 8 * fq;
;         f32x4 sq[2][4];
; #pragma unroll
;         for (int ai = 0; ai < 2; ++ai)
; #pragma unroll
;             for (int m = 0; m < 4; ++m) sq[ai][m] = *(const f32x4*)(ss2 + (size_t)(row0 + ai * 128 + m * 16) * 16 + 4 * fq);
; #pragma unroll
;         for (int ai = 0; ai < 2; ++ai)
; #pragma unroll
;             for (int m = 0; m < 4; ++m) {
;                 const int row = row0 + ai * 128 + m * 16;
;                 float ss = (sq[ai][m][0] + sq[ai][m][1]) + (sq[ai][m][2] + sq[ai][m][3]);
;                 ss += shx(ss, fq * 16 + fr, 16); ss += shx(ss, fq * 16 + fr, 32);
	s_waitcnt lgkmcnt(0)
	v_mfma_f32_16x16x32_bf16 v[60:63], v[128:131], v[144:147], v[60:63]
	v_mfma_f32_16x16x32_bf16 v[56:59], v[136:139], v[144:147], v[56:59]
	v_mfma_f32_16x16x32_bf16 v[44:47], v[128:131], v[186:189], v[44:47]
	v_mfma_f32_16x16x32_bf16 v[40:43], v[136:139], v[186:189], v[40:43]
	v_mfma_f32_16x16x32_bf16 v[28:31], v[128:131], v[194:197], v[28:31]
	v_mfma_f32_16x16x32_bf16 v[24:27], v[136:139], v[194:197], v[24:27]
	v_mfma_f32_16x16x32_bf16 v[12:15], v[128:131], v[202:205], v[12:15]
	v_mfma_f32_16x16x32_bf16 v[8:11], v[136:139], v[202:205], v[8:11]
	v_mfma_f32_16x16x32_bf16 v[60:63], v[132:135], v[182:185], v[60:63]
	v_mfma_f32_16x16x32_bf16 v[56:59], v[140:143], v[182:185], v[56:59]
	v_mfma_f32_16x16x32_bf16 v[44:47], v[132:135], v[190:193], v[44:47]
	v_mfma_f32_16x16x32_bf16 v[40:43], v[140:143], v[190:193], v[40:43]
	v_mfma_f32_16x16x32_bf16 v[28:31], v[132:135], v[198:201], v[28:31]
	v_mfma_f32_16x16x32_bf16 v[24:27], v[140:143], v[198:201], v[24:27]
	v_mfma_f32_16x16x32_bf16 v[12:15], v[132:135], v[206:209], v[12:15]
	v_mfma_f32_16x16x32_bf16 v[8:11], v[140:143], v[206:209], v[8:11]
	s_barrier
	s_add_u32 s18, s18, 0x40080
	s_addc_u32 s19, s19, 0
	s_add_i32 s20, s20, s27
	s_mov_b32 m0, s20
	v_lshl_add_u64 v[128:129], s[18:19], 0, v[150:151]
	global_load_lds_dwordx4 v[128:129], off
	s_add_i32 m0, s20, 0x2000
	v_lshl_add_u64 v[128:129], s[18:19], 0, v[154:155]
	global_load_lds_dwordx4 v[128:129], off
	s_waitcnt vmcnt(6)
	s_barrier
	v_mfma_f32_16x16x32_bf16 v[52:55], v[210:213], v[144:147], v[52:55]
	v_mfma_f32_16x16x32_bf16 v[48:51], v[218:221], v[144:147], v[48:51]
	v_mfma_f32_16x16x32_bf16 v[36:39], v[210:213], v[186:189], v[36:39]
	v_mfma_f32_16x16x32_bf16 v[32:35], v[218:221], v[186:189], v[32:35]
	v_mfma_f32_16x16x32_bf16 v[20:23], v[210:213], v[194:197], v[20:23]
	v_mfma_f32_16x16x32_bf16 v[16:19], v[218:221], v[194:197], v[16:19]
	v_mfma_f32_16x16x32_bf16 v[4:7], v[210:213], v[202:205], v[4:7]
	v_mfma_f32_16x16x32_bf16 v[0:3], v[218:221], v[202:205], v[0:3]
	v_mfma_f32_16x16x32_bf16 v[52:55], v[214:217], v[182:185], v[52:55]
	v_mfma_f32_16x16x32_bf16 v[48:51], v[222:225], v[182:185], v[48:51]
	v_mfma_f32_16x16x32_bf16 v[36:39], v[214:217], v[190:193], v[36:39]
	v_mfma_f32_16x16x32_bf16 v[32:35], v[222:225], v[190:193], v[32:35]
	v_mfma_f32_16x16x32_bf16 v[20:23], v[214:217], v[198:201], v[20:23]
	v_mfma_f32_16x16x32_bf16 v[16:19], v[222:225], v[198:201], v[16:19]
	v_mfma_f32_16x16x32_bf16 v[4:7], v[214:217], v[206:209], v[4:7]
	v_mfma_f32_16x16x32_bf16 v[0:3], v[222:225], v[206:209], v[0:3]
	s_add_i32 s46, s46, 2
	s_add_u32 s16, s16, 0x100
	s_addc_u32 s17, s17, 0
	s_add_u32 s44, s44, 0x100
	s_addc_u32 s45, s45, 0
	s_cmp_gt_u32 s46, 13
	s_barrier
	s_cbranch_scc0 .LBB0_725
	s_lshl_b32 s7, s14, 8
	s_add_i32 s7, s7, s35
	v_or_b32_e32 v132, s7, v172
	v_ashrrev_i32_e32 v133, 31, v132
	v_lshlrev_b64 v[128:129], 6, v[132:133]
	v_lshl_add_u64 v[134:135], v[158:159], 0, v[128:129]
	global_load_dwordx4 v[128:131], v[134:135], off
	v_or_b32_e32 v136, 16, v132
	v_ashrrev_i32_e32 v137, 31, v136
	v_lshlrev_b64 v[136:137], 6, v[136:137]
	v_lshl_add_u64 v[136:137], v[158:159], 0, v[136:137]
	global_load_dwordx4 v[182:185], v[136:137], off
	v_or_b32_e32 v136, 32, v132
	v_or_b32_e32 v138, 48, v132
	v_add_u32_e32 v170, 0x80, v132
	v_lshlrev_b32_e32 v132, 7, v132
	v_ashrrev_i32_e32 v137, 31, v136
	v_ashrrev_i32_e32 v139, 31, v138
	v_and_b32_e32 v156, 0x6780, v132
	v_lshlrev_b64 v[132:133], 6, v[136:137]
	v_lshlrev_b64 v[136:137], 6, v[138:139]
	v_lshl_add_u64 v[132:133], v[158:159], 0, v[132:133]
	v_lshl_add_u64 v[136:137], v[158:159], 0, v[136:137]
	global_load_dwordx4 v[186:189], v[132:133], off
	global_load_dwordx4 v[144:147], v[136:137], off
	v_ashrrev_i32_e32 v171, 31, v170
	v_lshlrev_b64 v[138:139], 6, v[170:171]
	v_add_co_u32_e32 v190, vcc, s33, v134
	s_lshl_b32 s9, s15, 8
	s_nop 0
	v_addc_co_u32_e32 v191, vcc, 0, v135, vcc
	s_or_b32 s9, s9, s36
	s_ashr_i32 s14, s7, 2
	s_ashr_i32 s7, s9, 6
	s_and_b32 s16, s14, 0xffffffc0
	s_add_i32 s14, s16, s7
	s_ashr_i32 s15, s14, 31
	s_lshl_b64 s[14:15], s[14:15], 15
	s_add_u32 s14, s2, s14
	v_lshl_add_u64 v[138:139], v[158:159], 0, v[138:139]
	s_addc_u32 s15, s3, s15
	v_mov_b32_e32 v169, v157
	s_or_b32 s9, s7, 2
	s_add_i32 s16, s16, s9
	s_ashr_i32 s17, s16, 31
	s_lshl_b64 s[16:17], s[16:17], 15
	s_add_u32 s16, s2, s16
	s_addc_u32 s17, s3, s17
	s_mov_b64 s[18:19], s[12:13]
	s_waitcnt vmcnt(0)
	v_mov_b32_e32 v132, v129
	v_mov_b32_e32 v133, v130
	v_mov_b32_e32 v129, v131
	v_pk_add_f32 v[128:129], v[132:133], v[128:129]
	v_mov_b32_e32 v193, v184
	v_add_f32_e32 v171, v128, v129
	ds_bpermute_b32 v192, v174, v171
	global_load_dwordx4 v[140:143], v[138:139], off
	s_nop 0
	global_load_dwordx4 v[136:139], v[190:191], off offset:1024
	global_load_dwordx4 v[132:135], v[190:191], off offset:2048
	global_load_dwordx4 v[128:131], v[190:191], off offset:3072
	v_lshl_add_u64 v[190:191], s[14:15], 0, v[156:157]
	v_lshl_add_u64 v[190:191], v[190:191], 0, v[168:169]
	s_waitcnt lgkmcnt(0)
	v_add_f32_e32 v171, v171, v192
	ds_bpermute_b32 v192, v175, v171
	s_waitcnt lgkmcnt(0)
; __device__ __forceinline__ float shx(float v, int lane, int mask) { return __int_as_float(__builtin_amdgcn_ds_bpermute((lane ^ mask) << 2, __float_as_int(v))); }
; __device__ __forceinline__ unsigned cvt_pk_bf16(float lo, float hi) { unsigned r; asm volatile("v_cvt_pk_bf16_f32 %0, %1, %2" : "=v"(r) : "v"(lo), "v"(hi)); return r; }
;     __device__ __forceinline__ void operator()(const f32x4 (&acc)[2][2][4][2], const Unit& u, int wr, int wc, int fr, int fq) const {
;     ...
; #pragma unroll
;         for (int ai = 0; ai < 2; ++ai)
; #pragma unroll
;             for (int m = 0; m < 4; ++m) {
;                 const int row = row0 + ai * 128 + m * 16;
;                 float ss = (sq[ai][m][0] + sq[ai][m][1]) + (sq[ai][m][2] + sq[ai][m][3]);
;                 ss += shx(ss, fq * 16 + fr, 16); ss += shx(ss, fq * 16 + fr, 32);
;                 const float rs = rsqrtf(ss * (1.0f / 1024.0f) + EPS);
; #pragma unroll
;                 for (int bj = 0; bj < 2; ++bj) {
;                     f32x4 v0 = acc[ai][bj][m][0] * rs, v1 = acc[ai][bj][m][1] * rs;
; #pragma unroll
;                     for (int j = 0; j < 4; ++j) { const float a = fmaxf(v0[j], 0.f), b = fmaxf(v1[j], 0.f); v0[j] = a * a; v1[j] = b * b; }
;                     u32x4 w; w.x = cvt_pk_bf16(v0[0], v0[1]); w.y = cvt_pk_bf16(v0[2], v0[3]); w.z = cvt_pk_bf16(v1[0], v1[1]); w.w = cvt_pk_bf16(v1[2], v1[3]);
;                     { const int col = col0 + bj * 128;
;                       *(u32x4*)(H + ((size_t)((row >> 8) * (DFF / 64) + (col >> 6)) * 256 + (row & 255)) * 64 + (col & 63)) = w; }
;                 }
	v_add_f32_e32 v171, v171, v192
	v_fmamk_f32 v171, v171, 0x3a800000, v181
	v_mul_f32_e32 v192, 0x4b800000, v171
	v_cmp_gt_f32_e32 vcc, s41, v171
	s_nop 1
	v_cndmask_b32_e32 v171, v171, v192, vcc
	v_rsq_f32_e32 v171, v171
	v_mov_b32_e32 v192, v183
	v_mov_b32_e32 v183, v185
	v_mul_f32_e32 v184, 0x45800000, v171
	v_cndmask_b32_e32 v184, v171, v184, vcc
	v_pk_mul_f32 v[126:127], v[126:127], v[184:185] op_sel_hi:[1,0]
	v_pk_mul_f32 v[124:125], v[124:125], v[184:185] op_sel_hi:[1,0]
	v_pk_mul_f32 v[122:123], v[122:123], v[184:185] op_sel_hi:[1,0]
	v_pk_mul_f32 v[120:121], v[120:121], v[184:185] op_sel_hi:[1,0]
	v_pk_mul_f32 v[114:115], v[114:115], v[184:185] op_sel_hi:[1,0]
	v_pk_mul_f32 v[112:113], v[112:113], v[184:185] op_sel_hi:[1,0]
	v_pk_mul_f32 v[116:117], v[116:117], v[184:185] op_sel_hi:[1,0]
	v_max_f32_e32 v124, 0, v124
	v_max_f32_e32 v120, 0, v120
	v_max_f32_e32 v125, 0, v125
	v_max_f32_e32 v121, 0, v121
	v_max_f32_e32 v126, 0, v126
	v_max_f32_e32 v122, 0, v122
	v_max_f32_e32 v127, 0, v127
	v_max_f32_e32 v123, 0, v123
	v_max_f32_e32 v112, 0, v112
	v_max_f32_e32 v113, 0, v113
	v_max_f32_e32 v114, 0, v114
	v_max_f32_e32 v115, 0, v115
	v_pk_mul_f32 v[118:119], v[118:119], v[184:185] op_sel_hi:[1,0]
	v_max_f32_e32 v116, 0, v116
	v_mul_f32_e32 v124, v124, v124
	v_mul_f32_e32 v120, v120, v120
	v_mul_f32_e32 v125, v125, v125
	v_mul_f32_e32 v121, v121, v121
	v_mul_f32_e32 v126, v126, v126
	v_mul_f32_e32 v122, v122, v122
	v_mul_f32_e32 v127, v127, v127
	v_mul_f32_e32 v123, v123, v123
	v_mul_f32_e32 v171, v112, v112
	v_mul_f32_e32 v184, v113, v113
	v_mul_f32_e32 v185, v114, v114
	v_mul_f32_e32 v194, v115, v115
	v_cvt_pk_bf16_f32 v112, v124, v125
	v_cvt_pk_bf16_f32 v113, v126, v127
	v_cvt_pk_bf16_f32 v114, v120, v121
	v_cvt_pk_bf16_f32 v115, v122, v123
	v_max_f32_e32 v117, 0, v117
	v_mul_f32_e32 v116, v116, v116
	global_store_dwordx4 v[190:191], v[112:115], off
	v_mul_f32_e32 v117, v117, v117
	v_max_f32_e32 v118, 0, v118
	v_pk_add_f32 v[114:115], v[192:193], v[182:183]
	v_cvt_pk_bf16_f32 v112, v116, v117
	v_max_f32_e32 v119, 0, v119
	v_add_f32_e32 v116, v114, v115
	ds_bpermute_b32 v117, v174, v116
	v_mul_f32_e32 v118, v118, v118
	v_mul_f32_e32 v119, v119, v119
	v_cvt_pk_bf16_f32 v113, v118, v119
	v_cvt_pk_bf16_f32 v114, v171, v184
	s_waitcnt lgkmcnt(0)
	v_add_f32_e32 v116, v116, v117
	ds_bpermute_b32 v117, v175, v116
	v_cvt_pk_bf16_f32 v115, v185, v194
	s_waitcnt lgkmcnt(0)
	v_add_f32_e32 v116, v116, v117
	v_fmamk_f32 v116, v116, 0x3a800000, v181
	v_mul_f32_e32 v117, 0x4b800000, v116
	v_cmp_gt_f32_e32 vcc, s41, v116
	s_nop 1
	v_cndmask_b32_e32 v116, v116, v117, vcc
	v_rsq_f32_e32 v118, v116
	v_lshl_add_u64 v[116:117], s[16:17], 0, v[156:157]
	v_lshl_add_u64 v[116:117], v[116:117], 0, v[168:169]
	global_store_dwordx4 v[116:117], v[112:115], off
	s_nop 1
	v_mul_f32_e32 v112, 0x45800000, v118
	v_cndmask_b32_e32 v112, v118, v112, vcc
	v_pk_mul_f32 v[104:105], v[104:105], v[112:113] op_sel_hi:[1,0]
	v_pk_mul_f32 v[108:109], v[108:109], v[112:113] op_sel_hi:[1,0]
	v_pk_mul_f32 v[106:107], v[106:107], v[112:113] op_sel_hi:[1,0]
	v_max_f32_e32 v104, 0, v104
	v_pk_mul_f32 v[110:111], v[110:111], v[112:113] op_sel_hi:[1,0]
	v_mul_f32_e32 v113, v104, v104
	v_max_f32_e32 v104, 0, v109
	v_max_f32_e32 v105, 0, v105
	v_max_f32_e32 v106, 0, v106
	v_max_f32_e32 v108, 0, v108
	v_mul_f32_e32 v104, v104, v104
	v_mul_f32_e32 v109, v105, v105
	v_max_f32_e32 v105, 0, v110
	v_mul_f32_e32 v110, v106, v106
	v_max_f32_e32 v106, 0, v111
	v_max_f32_e32 v107, 0, v107
	v_pk_mul_f32 v[96:97], v[96:97], v[112:113] op_sel_hi:[1,0]
	v_mul_f32_e32 v108, v108, v108
	v_mul_f32_e32 v105, v105, v105
	v_mul_f32_e32 v106, v106, v106
	v_mul_f32_e32 v107, v107, v107
	v_cvt_pk_bf16_f32 v104, v108, v104
	v_pk_mul_f32 v[100:101], v[100:101], v[112:113] op_sel_hi:[1,0]
	v_max_f32_e32 v96, 0, v96
	v_cvt_pk_bf16_f32 v105, v105, v106
	v_cvt_pk_bf16_f32 v106, v113, v109
	v_cvt_pk_bf16_f32 v107, v110, v107
	global_store_dwordx4 v[190:191], v[104:107], off offset:2048
	v_max_f32_e32 v97, 0, v97
	v_pk_mul_f32 v[98:99], v[98:99], v[112:113] op_sel_hi:[1,0]
	v_mul_f32_e32 v104, v96, v96
	v_max_f32_e32 v96, 0, v101
	v_mul_f32_e32 v101, v96, v96
	v_mul_f32_e32 v105, v97, v97
	v_mov_b32_e32 v96, v187
	v_mov_b32_e32 v97, v188
	v_mov_b32_e32 v187, v189
	v_pk_add_f32 v[96:97], v[96:97], v[186:187]
	v_pk_mul_f32 v[102:103], v[102:103], v[112:113] op_sel_hi:[1,0]
	v_add_f32_e32 v96, v96, v97
	ds_bpermute_b32 v97, v174, v96
	v_max_f32_e32 v98, 0, v98
	v_mul_f32_e32 v106, v98, v98
	v_max_f32_e32 v98, 0, v103
	v_max_f32_e32 v100, 0, v100
	s_waitcnt lgkmcnt(0)
	v_add_f32_e32 v103, v96, v97
	ds_bpermute_b32 v107, v175, v103
	v_mul_f32_e32 v97, v98, v98
	v_mul_f32_e32 v100, v100, v100
	v_cvt_pk_bf16_f32 v96, v100, v101
	v_max_f32_e32 v99, 0, v99
	s_waitcnt lgkmcnt(0)
; __device__ __forceinline__ float shx(float v, int lane, int mask) { return __int_as_float(__builtin_amdgcn_ds_bpermute((lane ^ mask) << 2, __float_as_int(v))); }
; __device__ __forceinline__ unsigned cvt_pk_bf16(float lo, float hi) { unsigned r; asm volatile("v_cvt_pk_bf16_f32 %0, %1, %2" : "=v"(r) : "v"(lo), "v"(hi)); return r; }
;     __device__ __forceinline__ void operator()(const f32x4 (&acc)[2][2][4][2], const Unit& u, int wr, int wc, int fr, int fq) const {
;     ...
; #pragma unroll
;         for (int ai = 0; ai < 2; ++ai)
; #pragma unroll
;             for (int m = 0; m < 4; ++m) {
;                 const int row = row0 + ai * 128 + m * 16;
;                 float ss = (sq[ai][m][0] + sq[ai][m][1]) + (sq[ai][m][2] + sq[ai][m][3]);
;                 ss += shx(ss, fq * 16 + fr, 16); ss += shx(ss, fq * 16 + fr, 32);
;                 const float rs = rsqrtf(ss * (1.0f / 1024.0f) + EPS);
; #pragma unroll
;                 for (int bj = 0; bj < 2; ++bj) {
;                     f32x4 v0 = acc[ai][bj][m][0] * rs, v1 = acc[ai][bj][m][1] * rs;
; #pragma unroll
;                     for (int j = 0; j < 4; ++j) { const float a = fmaxf(v0[j], 0.f), b = fmaxf(v1[j], 0.f); v0[j] = a * a; v1[j] = b * b; }
;                     u32x4 w; w.x = cvt_pk_bf16(v0[0], v0[1]); w.y = cvt_pk_bf16(v0[2], v0[3]); w.z = cvt_pk_bf16(v1[0], v1[1]); w.w = cvt_pk_bf16(v1[2], v1[3]);
;                     { const int col = col0 + bj * 128;
;                       *(u32x4*)(H + ((size_t)((row >> 8) * (DFF / 64) + (col >> 6)) * 256 + (row & 255)) * 64 + (col & 63)) = w; }
;                 }
	v_add_f32_e32 v98, v103, v107
	v_fmamk_f32 v98, v98, 0x3a800000, v181
	v_mul_f32_e32 v100, 0x4b800000, v98
	v_cmp_gt_f32_e32 vcc, s41, v98
	v_max_f32_e32 v102, 0, v102
	v_mul_f32_e32 v99, v99, v99
	v_cndmask_b32_e32 v98, v98, v100, vcc
	v_rsq_f32_e32 v100, v98
	v_mul_f32_e32 v102, v102, v102
	v_cvt_pk_bf16_f32 v97, v102, v97
	v_cvt_pk_bf16_f32 v98, v104, v105
	v_cvt_pk_bf16_f32 v99, v106, v99
	global_store_dwordx4 v[116:117], v[96:99], off offset:2048
	s_nop 1
	v_mul_f32_e32 v96, 0x45800000, v100
	v_cndmask_b32_e32 v96, v100, v96, vcc
	v_pk_mul_f32 v[90:91], v[90:91], v[96:97] op_sel_hi:[1,0]
	v_pk_mul_f32 v[88:89], v[88:89], v[96:97] op_sel_hi:[1,0]
	v_pk_mul_f32 v[94:95], v[94:95], v[96:97] op_sel_hi:[1,0]
	v_pk_mul_f32 v[92:93], v[92:93], v[96:97] op_sel_hi:[1,0]
	v_max_f32_e32 v88, 0, v88
	v_max_f32_e32 v89, 0, v89
	v_max_f32_e32 v90, 0, v90
	v_max_f32_e32 v92, 0, v92
	v_mul_f32_e32 v97, v88, v88
	v_max_f32_e32 v88, 0, v93
	v_mul_f32_e32 v93, v89, v89
	v_max_f32_e32 v89, 0, v94
	v_mul_f32_e32 v94, v90, v90
	v_max_f32_e32 v90, 0, v95
	v_mul_f32_e32 v92, v92, v92
	v_mul_f32_e32 v88, v88, v88
	v_mul_f32_e32 v89, v89, v89
	v_max_f32_e32 v91, 0, v91
	v_mul_f32_e32 v90, v90, v90
	v_mul_f32_e32 v91, v91, v91
	v_cvt_pk_bf16_f32 v88, v92, v88
	v_cvt_pk_bf16_f32 v89, v89, v90
	v_cvt_pk_bf16_f32 v90, v97, v93
	v_or_b32_e32 v92, 0x1000, v156
	v_mov_b32_e32 v93, v157
	v_cvt_pk_bf16_f32 v91, v94, v91
	v_lshl_add_u64 v[94:95], s[14:15], 0, v[92:93]
	v_pk_mul_f32 v[80:81], v[80:81], v[96:97] op_sel_hi:[1,0]
	v_lshl_add_u64 v[94:95], v[94:95], 0, v[168:169]
	v_pk_mul_f32 v[84:85], v[84:85], v[96:97] op_sel_hi:[1,0]
	v_max_f32_e32 v80, 0, v80
	global_store_dwordx4 v[94:95], v[88:91], off
	v_pk_mul_f32 v[86:87], v[86:87], v[96:97] op_sel_hi:[1,0]
	v_pk_mul_f32 v[82:83], v[82:83], v[96:97] op_sel_hi:[1,0]
	v_mul_f32_e32 v88, v80, v80
	v_max_f32_e32 v80, 0, v85
	v_max_f32_e32 v81, 0, v81
	v_mul_f32_e32 v85, v80, v80
	v_mul_f32_e32 v89, v81, v81
	v_max_f32_e32 v80, 0, v86
	v_max_f32_e32 v81, 0, v82
	v_mul_f32_e32 v82, v80, v80
	v_mul_f32_e32 v86, v81, v81
	v_mov_b32_e32 v80, v145
	v_mov_b32_e32 v81, v146
	v_mov_b32_e32 v145, v147
	v_pk_add_f32 v[80:81], v[80:81], v[144:145]
	v_max_f32_e32 v84, 0, v84
	v_add_f32_e32 v80, v80, v81
	ds_bpermute_b32 v81, v174, v80
	v_mul_f32_e32 v84, v84, v84
	v_max_f32_e32 v83, 0, v83
	v_max_f32_e32 v87, 0, v87
	v_mul_f32_e32 v83, v83, v83
	s_waitcnt lgkmcnt(0)
	v_add_f32_e32 v90, v80, v81
	ds_bpermute_b32 v91, v175, v90
	v_cvt_pk_bf16_f32 v80, v84, v85
	v_mul_f32_e32 v87, v87, v87
	v_cvt_pk_bf16_f32 v81, v82, v87
	v_cvt_pk_bf16_f32 v82, v88, v89
	s_waitcnt lgkmcnt(0)
	v_add_f32_e32 v84, v90, v91
	v_fmamk_f32 v84, v84, 0x3a800000, v181
	v_mul_f32_e32 v85, 0x4b800000, v84
	v_cmp_gt_f32_e32 vcc, s41, v84
	v_cvt_pk_bf16_f32 v83, v86, v83
	v_or_b32_e32 v156, 0x1800, v156
	s_nop 0
	v_cndmask_b32_e32 v84, v84, v85, vcc
	v_rsq_f32_e32 v86, v84
	v_lshl_add_u64 v[84:85], s[16:17], 0, v[92:93]
	v_lshl_add_u64 v[84:85], v[84:85], 0, v[168:169]
	global_store_dwordx4 v[84:85], v[80:83], off
	s_nop 1
	v_mul_f32_e32 v80, 0x45800000, v86
	v_cndmask_b32_e32 v80, v86, v80, vcc
	v_pk_mul_f32 v[74:75], v[74:75], v[80:81] op_sel_hi:[1,0]
	v_pk_mul_f32 v[72:73], v[72:73], v[80:81] op_sel_hi:[1,0]
	v_pk_mul_f32 v[78:79], v[78:79], v[80:81] op_sel_hi:[1,0]
	v_pk_mul_f32 v[76:77], v[76:77], v[80:81] op_sel_hi:[1,0]
	v_max_f32_e32 v72, 0, v72
	v_max_f32_e32 v73, 0, v73
	v_max_f32_e32 v74, 0, v74
	v_max_f32_e32 v76, 0, v76
	v_mul_f32_e32 v81, v72, v72
	v_max_f32_e32 v72, 0, v77
	v_mul_f32_e32 v77, v73, v73
	v_max_f32_e32 v73, 0, v78
	v_mul_f32_e32 v78, v74, v74
	v_max_f32_e32 v74, 0, v79
	v_mul_f32_e32 v76, v76, v76
	v_mul_f32_e32 v72, v72, v72
	v_mul_f32_e32 v73, v73, v73
	v_mul_f32_e32 v74, v74, v74
	v_max_f32_e32 v75, 0, v75
	v_cvt_pk_bf16_f32 v72, v76, v72
	v_cvt_pk_bf16_f32 v73, v73, v74
	v_cvt_pk_bf16_f32 v74, v81, v77
	v_lshl_add_u64 v[76:77], s[14:15], 0, v[156:157]
	v_pk_mul_f32 v[64:65], v[64:65], v[80:81] op_sel_hi:[1,0]
	v_mul_f32_e32 v75, v75, v75
	v_lshl_add_u64 v[76:77], v[76:77], 0, v[168:169]
	v_pk_mul_f32 v[68:69], v[68:69], v[80:81] op_sel_hi:[1,0]
	v_max_f32_e32 v64, 0, v64
	v_cvt_pk_bf16_f32 v75, v78, v75
	global_store_dwordx4 v[76:77], v[72:75], off
	v_pk_mul_f32 v[70:71], v[70:71], v[80:81] op_sel_hi:[1,0]
	v_pk_mul_f32 v[66:67], v[66:67], v[80:81] op_sel_hi:[1,0]
	v_mul_f32_e32 v72, v64, v64
	v_max_f32_e32 v64, 0, v69
	v_max_f32_e32 v65, 0, v65
	v_mul_f32_e32 v69, v64, v64
	v_mul_f32_e32 v73, v65, v65
	v_max_f32_e32 v64, 0, v70
	v_max_f32_e32 v65, 0, v66
	v_mul_f32_e32 v66, v64, v64
	v_mul_f32_e32 v70, v65, v65
	s_waitcnt vmcnt(10)
	v_mov_b32_e32 v64, v141
	v_mov_b32_e32 v65, v142
	v_mov_b32_e32 v141, v143
	v_pk_add_f32 v[64:65], v[64:65], v[140:141]
	v_max_f32_e32 v71, 0, v71
	v_add_f32_e32 v74, v64, v65
	ds_bpermute_b32 v75, v174, v74
	v_mul_f32_e32 v65, v71, v71
	v_max_f32_e32 v67, 0, v67
	v_max_f32_e32 v68, 0, v68
	v_mul_f32_e32 v67, v67, v67
	s_waitcnt lgkmcnt(0)
	v_add_f32_e32 v71, v74, v75
	ds_bpermute_b32 v74, v175, v71
	v_mul_f32_e32 v68, v68, v68
	v_cvt_pk_bf16_f32 v64, v68, v69
	v_cvt_pk_bf16_f32 v65, v66, v65
	v_cvt_pk_bf16_f32 v66, v72, v73
	v_cvt_pk_bf16_f32 v67, v70, v67
	s_waitcnt lgkmcnt(0)
; __device__ __forceinline__ float shx(float v, int lane, int mask) { return __int_as_float(__builtin_amdgcn_ds_bpermute((lane ^ mask) << 2, __float_as_int(v))); }
; __device__ __forceinline__ unsigned cvt_pk_bf16(float lo, float hi) { unsigned r; asm volatile("v_cvt_pk_bf16_f32 %0, %1, %2" : "=v"(r) : "v"(lo), "v"(hi)); return r; }
;     __device__ __forceinline__ void operator()(const f32x4 (&acc)[2][2][4][2], const Unit& u, int wr, int wc, int fr, int fq) const {
;     ...
; #pragma unroll
;         for (int ai = 0; ai < 2; ++ai)
; #pragma unroll
;             for (int m = 0; m < 4; ++m) {
;                 const int row = row0 + ai * 128 + m * 16;
;                 float ss = (sq[ai][m][0] + sq[ai][m][1]) + (sq[ai][m][2] + sq[ai][m][3]);
;                 ss += shx(ss, fq * 16 + fr, 16); ss += shx(ss, fq * 16 + fr, 32);
;                 const float rs = rsqrtf(ss * (1.0f / 1024.0f) + EPS);
; #pragma unroll
;                 for (int bj = 0; bj < 2; ++bj) {
;                     f32x4 v0 = acc[ai][bj][m][0] * rs, v1 = acc[ai][bj][m][1] * rs;
; #pragma unroll
;                     for (int j = 0; j < 4; ++j) { const float a = fmaxf(v0[j], 0.f), b = fmaxf(v1[j], 0.f); v0[j] = a * a; v1[j] = b * b; }
;                     u32x4 w; w.x = cvt_pk_bf16(v0[0], v0[1]); w.y = cvt_pk_bf16(v0[2], v0[3]); w.z = cvt_pk_bf16(v1[0], v1[1]); w.w = cvt_pk_bf16(v1[2], v1[3]);
;                     { const int col = col0 + bj * 128;
;                       *(u32x4*)(H + ((size_t)((row >> 8) * (DFF / 64) + (col >> 6)) * 256 + (row & 255)) * 64 + (col & 63)) = w; }
;                 }
	v_add_f32_e32 v70, v71, v74
	v_fmamk_f32 v70, v70, 0x3a800000, v181
	v_mul_f32_e32 v71, 0x4b800000, v70
	v_cmp_gt_f32_e32 vcc, s41, v70
	v_lshl_add_u64 v[68:69], s[16:17], 0, v[156:157]
	v_lshl_add_u64 v[68:69], v[68:69], 0, v[168:169]
	v_cndmask_b32_e32 v70, v70, v71, vcc
	v_rsq_f32_e32 v70, v70
	global_store_dwordx4 v[68:69], v[64:67], off
	s_mov_b32 s15, s6
	s_mov_b32 s14, s8
	v_ashrrev_i32_e32 v64, 2, v170
	v_and_b32_e32 v65, 0xffffffc0, v64
	v_mul_f32_e32 v64, 0x45800000, v70
	v_cndmask_b32_e32 v64, v70, v64, vcc
	v_pk_mul_f32 v[60:61], v[60:61], v[64:65] op_sel_hi:[1,0]
	v_pk_mul_f32 v[58:59], v[58:59], v[64:65] op_sel_hi:[1,0]
	v_pk_mul_f32 v[56:57], v[56:57], v[64:65] op_sel_hi:[1,0]
	v_pk_mul_f32 v[62:63], v[62:63], v[64:65] op_sel_hi:[1,0]
	v_max_f32_e32 v60, 0, v60
	v_max_f32_e32 v56, 0, v56
	v_max_f32_e32 v58, 0, v58
	v_mul_f32_e32 v60, v60, v60
	v_mul_f32_e32 v56, v56, v56
	v_max_f32_e32 v61, 0, v61
	v_max_f32_e32 v57, 0, v57
	v_max_f32_e32 v62, 0, v62
	v_mul_f32_e32 v66, v58, v58
	v_max_f32_e32 v58, 0, v63
	v_max_f32_e32 v59, 0, v59
	v_mul_f32_e32 v61, v61, v61
	v_mul_f32_e32 v57, v57, v57
	v_mul_f32_e32 v62, v62, v62
	v_mul_f32_e32 v63, v58, v58
	v_mul_f32_e32 v67, v59, v59
	v_cvt_pk_bf16_f32 v58, v60, v61
	v_cvt_pk_bf16_f32 v59, v62, v63
	v_cvt_pk_bf16_f32 v60, v56, v57
	v_add_u32_e32 v56, s7, v65
	v_ashrrev_i32_e32 v57, 31, v56
	v_lshlrev_b64 v[56:57], 15, v[56:57]
	v_lshlrev_b32_e32 v62, 7, v170
	v_lshl_add_u64 v[56:57], s[2:3], 0, v[56:57]
	v_and_b32_e32 v156, 0x6780, v62
	v_lshl_add_u64 v[62:63], v[56:57], 0, v[156:157]
	v_pk_mul_f32 v[48:49], v[48:49], v[64:65] op_sel_hi:[1,0]
	v_lshl_add_u64 v[62:63], v[62:63], 0, v[168:169]
	v_pk_mul_f32 v[52:53], v[52:53], v[64:65] op_sel_hi:[1,0]
	v_max_f32_e32 v48, 0, v48
	v_cvt_pk_bf16_f32 v61, v66, v67
	global_store_dwordx4 v[62:63], v[58:61], off
	v_pk_mul_f32 v[54:55], v[54:55], v[64:65] op_sel_hi:[1,0]
	v_pk_mul_f32 v[50:51], v[50:51], v[64:65] op_sel_hi:[1,0]
	v_mul_f32_e32 v58, v48, v48
	v_max_f32_e32 v48, 0, v53
	v_max_f32_e32 v49, 0, v49
	v_mul_f32_e32 v53, v48, v48
	v_mul_f32_e32 v59, v49, v49
	v_max_f32_e32 v48, 0, v54
	v_max_f32_e32 v49, 0, v50
	v_mul_f32_e32 v54, v48, v48
	v_mul_f32_e32 v60, v49, v49
	v_max_f32_e32 v48, 0, v55
	v_max_f32_e32 v49, 0, v51
	v_mul_f32_e32 v51, v48, v48
	v_mul_f32_e32 v55, v49, v49
	s_waitcnt vmcnt(11)
	v_mov_b32_e32 v48, v137
	v_mov_b32_e32 v49, v138
	v_mov_b32_e32 v137, v139
	v_pk_add_f32 v[48:49], v[48:49], v[136:137]
	v_max_f32_e32 v52, 0, v52
	v_add_f32_e32 v48, v48, v49
	ds_bpermute_b32 v49, v174, v48
	v_mul_f32_e32 v52, v52, v52
	v_cvt_pk_bf16_f32 v50, v52, v53
	v_cvt_pk_bf16_f32 v51, v54, v51
	v_cvt_pk_bf16_f32 v52, v58, v59
	s_waitcnt lgkmcnt(0)
	v_add_f32_e32 v54, v48, v49
	v_cvt_pk_bf16_f32 v53, v60, v55
	ds_bpermute_b32 v55, v175, v54
	v_add_u32_e32 v48, s9, v65
	v_ashrrev_i32_e32 v49, 31, v48
	v_lshlrev_b64 v[48:49], 15, v[48:49]
	v_lshl_add_u64 v[48:49], s[2:3], 0, v[48:49]
	s_waitcnt lgkmcnt(0)
	v_add_f32_e32 v54, v54, v55
	v_fmamk_f32 v54, v54, 0x3a800000, v181
	v_mul_f32_e32 v55, 0x4b800000, v54
	v_cmp_gt_f32_e32 vcc, s41, v54
	s_mov_b64 s[16:17], s[10:11]
	s_nop 0
	v_cndmask_b32_e32 v54, v54, v55, vcc
	v_rsq_f32_e32 v58, v54
	v_lshl_add_u64 v[54:55], v[48:49], 0, v[156:157]
	v_lshl_add_u64 v[54:55], v[54:55], 0, v[168:169]
	global_store_dwordx4 v[54:55], v[50:53], off
	s_nop 1
	v_mul_f32_e32 v50, 0x45800000, v58
	v_cndmask_b32_e32 v50, v58, v50, vcc
	v_pk_mul_f32 v[40:41], v[40:41], v[50:51] op_sel_hi:[1,0]
	v_pk_mul_f32 v[44:45], v[44:45], v[50:51] op_sel_hi:[1,0]
	v_pk_mul_f32 v[42:43], v[42:43], v[50:51] op_sel_hi:[1,0]
	v_max_f32_e32 v40, 0, v40
	v_pk_mul_f32 v[46:47], v[46:47], v[50:51] op_sel_hi:[1,0]
	v_mul_f32_e32 v51, v40, v40
	v_max_f32_e32 v40, 0, v45
	v_max_f32_e32 v41, 0, v41
	v_max_f32_e32 v42, 0, v42
	v_max_f32_e32 v44, 0, v44
	v_mul_f32_e32 v40, v40, v40
	v_mul_f32_e32 v45, v41, v41
	v_max_f32_e32 v41, 0, v46
	v_mul_f32_e32 v46, v42, v42
	v_max_f32_e32 v42, 0, v47
	v_max_f32_e32 v43, 0, v43
	v_pk_mul_f32 v[32:33], v[32:33], v[50:51] op_sel_hi:[1,0]
	v_mul_f32_e32 v44, v44, v44
	v_mul_f32_e32 v41, v41, v41
	v_mul_f32_e32 v42, v42, v42
	v_mul_f32_e32 v43, v43, v43
	v_cvt_pk_bf16_f32 v40, v44, v40
	v_pk_mul_f32 v[36:37], v[36:37], v[50:51] op_sel_hi:[1,0]
	v_max_f32_e32 v32, 0, v32
	v_cvt_pk_bf16_f32 v41, v41, v42
	v_cvt_pk_bf16_f32 v42, v51, v45
	v_cvt_pk_bf16_f32 v43, v46, v43
	global_store_dwordx4 v[62:63], v[40:43], off offset:2048
	v_max_f32_e32 v33, 0, v33
	v_pk_mul_f32 v[34:35], v[34:35], v[50:51] op_sel_hi:[1,0]
	v_mul_f32_e32 v40, v32, v32
	v_max_f32_e32 v32, 0, v37
	v_mul_f32_e32 v37, v32, v32
	v_mul_f32_e32 v41, v33, v33
	s_waitcnt vmcnt(12)
	v_mov_b32_e32 v32, v133
	v_mov_b32_e32 v33, v134
	v_mov_b32_e32 v133, v135
	v_pk_add_f32 v[32:33], v[32:33], v[132:133]
	v_pk_mul_f32 v[38:39], v[38:39], v[50:51] op_sel_hi:[1,0]
	v_add_f32_e32 v32, v32, v33
	ds_bpermute_b32 v33, v174, v32
	v_max_f32_e32 v34, 0, v34
	v_mul_f32_e32 v42, v34, v34
	v_max_f32_e32 v34, 0, v39
	v_max_f32_e32 v36, 0, v36
	s_waitcnt lgkmcnt(0)
	v_add_f32_e32 v39, v32, v33
	ds_bpermute_b32 v43, v175, v39
	v_mul_f32_e32 v33, v34, v34
	v_mul_f32_e32 v36, v36, v36
	v_cvt_pk_bf16_f32 v32, v36, v37
	v_max_f32_e32 v35, 0, v35
	s_waitcnt lgkmcnt(0)
; __device__ __forceinline__ float shx(float v, int lane, int mask) { return __int_as_float(__builtin_amdgcn_ds_bpermute((lane ^ mask) << 2, __float_as_int(v))); }
; __device__ __forceinline__ unsigned cvt_pk_bf16(float lo, float hi) { unsigned r; asm volatile("v_cvt_pk_bf16_f32 %0, %1, %2" : "=v"(r) : "v"(lo), "v"(hi)); return r; }
; #define PG8_WAIT_V(n) asm volatile("s_waitcnt vmcnt(" #n ")" ::: "memory")
; #define PG8_BAR __builtin_amdgcn_s_barrier()
; template <class Epi, class Sched>
; __device__ __forceinline__ void gemm_phase(const int wv, LAS unsigned char* lds, const Gemm g, const Sched& S, const Epi& E) {
;     ...
;         E(acc, cur, wr, wc, fr, fq); S.done(cur);
;         if (!has_next) break;
; #pragma unroll
;         for (int a = 0; a < 2; ++a)
; #pragma unroll
;             for (int b = 0; b < 2; ++b)
; #pragma unroll
;                 for (int m = 0; m < 4; ++m)
; #pragma unroll
;                     for (int n = 0; n < 2; ++n) acc[a][b][m][n] = (f32x4){0.f, 0.f, 0.f, 0.f};
;         cur = nxt; cA = nA; cB = nB; ++ui;
;     }
;     PG8_WAIT_V(0);
;     if (wr == 0) PG8_BAR;
;     __device__ __forceinline__ void operator()(const f32x4 (&acc)[2][2][4][2], const Unit& u, int wr, int wc, int fr, int fq) const {
;     ...
;             for (int m = 0; m < 4; ++m) {
;                 const int row = row0 + ai * 128 + m * 16;
;                 float ss = (sq[ai][m][0] + sq[ai][m][1]) + (sq[ai][m][2] + sq[ai][m][3]);
;                 ss += shx(ss, fq * 16 + fr, 16); ss += shx(ss, fq * 16 + fr, 32);
;                 const float rs = rsqrtf(ss * (1.0f / 1024.0f) + EPS);
; #pragma unroll
;                 for (int bj = 0; bj < 2; ++bj) {
;                     f32x4 v0 = acc[ai][bj][m][0] * rs, v1 = acc[ai][bj][m][1] * rs;
; #pragma unroll
;                     for (int j = 0; j < 4; ++j) { const float a = fmaxf(v0[j], 0.f), b = fmaxf(v1[j], 0.f); v0[j] = a * a; v1[j] = b * b; }
;                     u32x4 w; w.x = cvt_pk_bf16(v0[0], v0[1]); w.y = cvt_pk_bf16(v0[2], v0[3]); w.z = cvt_pk_bf16(v1[0], v1[1]); w.w = cvt_pk_bf16(v1[2], v1[3]);
;                     { const int col = col0 + bj * 128;
;                       *(u32x4*)(H + ((size_t)((row >> 8) * (DFF / 64) + (col >> 6)) * 256 + (row & 255)) * 64 + (col & 63)) = w; }
;                 }
	v_add_f32_e32 v34, v39, v43
	v_fmamk_f32 v34, v34, 0x3a800000, v181
	v_mul_f32_e32 v36, 0x4b800000, v34
	v_cmp_gt_f32_e32 vcc, s41, v34
	v_max_f32_e32 v38, 0, v38
	v_mul_f32_e32 v35, v35, v35
	v_cndmask_b32_e32 v34, v34, v36, vcc
	v_rsq_f32_e32 v36, v34
	v_mul_f32_e32 v38, v38, v38
	v_cvt_pk_bf16_f32 v33, v38, v33
	v_cvt_pk_bf16_f32 v34, v40, v41
	v_cvt_pk_bf16_f32 v35, v42, v35
	global_store_dwordx4 v[54:55], v[32:35], off offset:2048
	s_nop 1
	v_mul_f32_e32 v32, 0x45800000, v36
	v_cndmask_b32_e32 v32, v36, v32, vcc
	v_pk_mul_f32 v[26:27], v[26:27], v[32:33] op_sel_hi:[1,0]
	v_pk_mul_f32 v[24:25], v[24:25], v[32:33] op_sel_hi:[1,0]
	v_pk_mul_f32 v[30:31], v[30:31], v[32:33] op_sel_hi:[1,0]
	v_pk_mul_f32 v[28:29], v[28:29], v[32:33] op_sel_hi:[1,0]
	v_max_f32_e32 v24, 0, v24
	v_max_f32_e32 v25, 0, v25
	v_max_f32_e32 v26, 0, v26
	v_max_f32_e32 v28, 0, v28
	v_mul_f32_e32 v33, v24, v24
	v_max_f32_e32 v24, 0, v29
	v_mul_f32_e32 v29, v25, v25
	v_max_f32_e32 v25, 0, v30
	v_mul_f32_e32 v30, v26, v26
	v_max_f32_e32 v26, 0, v31
	v_mul_f32_e32 v28, v28, v28
	v_mul_f32_e32 v24, v24, v24
	v_mul_f32_e32 v25, v25, v25
	v_max_f32_e32 v27, 0, v27
	v_mul_f32_e32 v26, v26, v26
	v_mul_f32_e32 v27, v27, v27
	v_cvt_pk_bf16_f32 v24, v28, v24
	v_cvt_pk_bf16_f32 v25, v25, v26
	v_cvt_pk_bf16_f32 v26, v33, v29
	v_or_b32_e32 v28, 0x1000, v156
	v_mov_b32_e32 v29, v157
	v_cvt_pk_bf16_f32 v27, v30, v27
	v_lshl_add_u64 v[30:31], v[56:57], 0, v[28:29]
	v_pk_mul_f32 v[16:17], v[16:17], v[32:33] op_sel_hi:[1,0]
	v_lshl_add_u64 v[30:31], v[30:31], 0, v[168:169]
	v_pk_mul_f32 v[20:21], v[20:21], v[32:33] op_sel_hi:[1,0]
	v_max_f32_e32 v16, 0, v16
	global_store_dwordx4 v[30:31], v[24:27], off
	v_pk_mul_f32 v[22:23], v[22:23], v[32:33] op_sel_hi:[1,0]
	v_pk_mul_f32 v[18:19], v[18:19], v[32:33] op_sel_hi:[1,0]
	v_mul_f32_e32 v24, v16, v16
	v_max_f32_e32 v16, 0, v21
	v_max_f32_e32 v17, 0, v17
	v_mul_f32_e32 v21, v16, v16
	v_mul_f32_e32 v25, v17, v17
	v_max_f32_e32 v16, 0, v22
	v_max_f32_e32 v17, 0, v18
	v_mul_f32_e32 v18, v16, v16
	v_mul_f32_e32 v22, v17, v17
	s_waitcnt vmcnt(13)
	v_mov_b32_e32 v16, v129
	v_mov_b32_e32 v17, v130
	v_mov_b32_e32 v129, v131
	v_pk_add_f32 v[16:17], v[16:17], v[128:129]
	v_max_f32_e32 v20, 0, v20
	v_add_f32_e32 v16, v16, v17
	ds_bpermute_b32 v17, v174, v16
	v_mul_f32_e32 v20, v20, v20
	v_max_f32_e32 v19, 0, v19
	v_max_f32_e32 v23, 0, v23
	v_mul_f32_e32 v19, v19, v19
	s_waitcnt lgkmcnt(0)
	v_add_f32_e32 v26, v16, v17
	ds_bpermute_b32 v27, v175, v26
	v_cvt_pk_bf16_f32 v16, v20, v21
	v_mul_f32_e32 v23, v23, v23
	v_cvt_pk_bf16_f32 v17, v18, v23
	v_cvt_pk_bf16_f32 v18, v24, v25
	s_waitcnt lgkmcnt(0)
	v_add_f32_e32 v20, v26, v27
	v_fmamk_f32 v20, v20, 0x3a800000, v181
	v_mul_f32_e32 v21, 0x4b800000, v20
	v_cmp_gt_f32_e32 vcc, s41, v20
	v_cvt_pk_bf16_f32 v19, v22, v19
	v_or_b32_e32 v156, 0x1800, v156
	s_nop 0
	v_cndmask_b32_e32 v20, v20, v21, vcc
	v_rsq_f32_e32 v22, v20
	v_lshl_add_u64 v[20:21], v[48:49], 0, v[28:29]
	v_lshl_add_u64 v[20:21], v[20:21], 0, v[168:169]
	global_store_dwordx4 v[20:21], v[16:19], off
	s_nop 1
	v_mul_f32_e32 v16, 0x45800000, v22
	v_cndmask_b32_e32 v16, v22, v16, vcc
	v_pk_mul_f32 v[10:11], v[10:11], v[16:17] op_sel_hi:[1,0]
	v_pk_mul_f32 v[8:9], v[8:9], v[16:17] op_sel_hi:[1,0]
	v_pk_mul_f32 v[14:15], v[14:15], v[16:17] op_sel_hi:[1,0]
	v_pk_mul_f32 v[12:13], v[12:13], v[16:17] op_sel_hi:[1,0]
	v_max_f32_e32 v8, 0, v8
	v_max_f32_e32 v9, 0, v9
	v_max_f32_e32 v10, 0, v10
	v_max_f32_e32 v12, 0, v12
	v_mul_f32_e32 v17, v8, v8
	v_max_f32_e32 v8, 0, v13
	v_mul_f32_e32 v13, v9, v9
	v_max_f32_e32 v9, 0, v14
	v_mul_f32_e32 v14, v10, v10
	v_max_f32_e32 v10, 0, v15
	v_mul_f32_e32 v12, v12, v12
	v_mul_f32_e32 v8, v8, v8
	v_mul_f32_e32 v9, v9, v9
	v_mul_f32_e32 v10, v10, v10
	v_max_f32_e32 v11, 0, v11
	v_cvt_pk_bf16_f32 v8, v12, v8
	v_cvt_pk_bf16_f32 v9, v9, v10
	v_cvt_pk_bf16_f32 v10, v17, v13
	v_lshl_add_u64 v[12:13], v[56:57], 0, v[156:157]
	v_pk_mul_f32 v[2:3], v[2:3], v[16:17] op_sel_hi:[1,0]
	v_pk_mul_f32 v[0:1], v[0:1], v[16:17] op_sel_hi:[1,0]
	v_mul_f32_e32 v11, v11, v11
	v_lshl_add_u64 v[12:13], v[12:13], 0, v[168:169]
	v_pk_mul_f32 v[6:7], v[6:7], v[16:17] op_sel_hi:[1,0]
	v_pk_mul_f32 v[4:5], v[4:5], v[16:17] op_sel_hi:[1,0]
	v_max_f32_e32 v0, 0, v0
	v_max_f32_e32 v1, 0, v1
	v_max_f32_e32 v2, 0, v2
	v_cvt_pk_bf16_f32 v11, v14, v11
	global_store_dwordx4 v[12:13], v[8:11], off
	v_max_f32_e32 v4, 0, v4
	v_mul_f32_e32 v4, v4, v4
	v_mul_f32_e32 v8, v0, v0
	v_max_f32_e32 v0, 0, v5
	v_mul_f32_e32 v5, v1, v1
	v_max_f32_e32 v1, 0, v6
	v_mul_f32_e32 v6, v2, v2
	v_max_f32_e32 v2, 0, v7
	v_mul_f32_e32 v0, v0, v0
	v_mul_f32_e32 v1, v1, v1
	v_mul_f32_e32 v2, v2, v2
	v_max_f32_e32 v3, 0, v3
	v_cvt_pk_bf16_f32 v0, v4, v0
	v_cvt_pk_bf16_f32 v1, v1, v2
	v_cvt_pk_bf16_f32 v2, v8, v5
	v_lshl_add_u64 v[4:5], v[48:49], 0, v[156:157]
	v_mul_f32_e32 v3, v3, v3
	v_lshl_add_u64 v[4:5], v[4:5], 0, v[168:169]
	s_and_b64 vcc, exec, s[0:1]
	v_cvt_pk_bf16_f32 v3, v6, v3
	global_store_dwordx4 v[4:5], v[0:3], off
	s_cbranch_vccz .LBB0_718
	s_waitcnt vmcnt(0)
	s_cmpk_gt_u32 s22, 0xff
	s_cbranch_scc1 .LBB0_729
	s_barrier

; #define PG8_STAGE(bufoff, gbase, voff) do { _Pragma("unroll") for (int _i = 0; _i < 2; ++_i) \
;         __builtin_amdgcn_global_load_lds((const unsigned*)((const char*)(gbase) + (voff)[_i]), (LAS unsigned*)(lds + (bufoff) + ldsw + _i * 8192), 16, 0, 0); } while (0)
; #define PG8_LDA(dst, b, h) do { _Pragma("unroll") for (int m = 0; m < 4; ++m) _Pragma("unroll") for (int k = 0; k < 2; ++k) dst[m][k] = *(const LAS bf16x8*)(lds + PG8_SA(b, h) + aoff + m * 2048 + k * 1024); } while (0)
; #define PG8_WAIT_V(n) asm volatile("s_waitcnt vmcnt(" #n ")" ::: "memory")
; template <class Epi, class Sched>
; __device__ __forceinline__ void gemm_phase(const int wv, LAS unsigned char* lds, const Gemm g, const Sched& S, const Epi& E) {
;     ...
;         for (int t = 0; t < nt; t += 2) {
;             const bool last = (t == nt - 2);
;             const char* a1 = cA + (size_t)(t + 1) * kstepA;
;             const char* a2 = last ? nA : cA + (size_t)(t + 2) * kstepA; const char* b2 = last ? nB : cB + (size_t)(t + 2) * kstep;
;             const char* a3 = a2 + kstepA; const char* b3 = b2 + kstep;
;             if (last && has_next) S.a_ready(nxt);
;             PG8_LDB(B0, 0, 0); PG8_SCHED; PG8_LDA(At, 0, 0); PG8_STAGE(PG8_SA(1, 1), a1 + hstepA, voffA);
;             PG8_WAIT_L(8); PG8_BAR; PG8_WAIT_L(0); PG8_MMA(0, 0, At, B0); PG8_BAR; PG8_SCHED;
;             PG8_LDB(B1, 0, 1); PG8_STAGE(PG8_SB(0, 0), b2, voffB);
;             PG8_BAR; PG8_WAIT_L(0); PG8_MMA(0, 1, At, B1); PG8_BAR;
;             PG8_LDA(At, 0, 1); PG8_STAGE(PG8_SA(0, 0), a2, voffA);
;             PG8_BAR; PG8_WAIT_L(0); PG8_MMA(1, 0, At, B0); PG8_BAR; PG8_SCHED;
;             PG8_STAGE(PG8_SB(0, 1), b2 + hstepB, voffB);
;             PG8_WAIT_V(6); PG8_BAR; PG8_MMA(1, 1, At, B1); PG8_BAR;
;             PG8_LDB(B0, 1, 0); PG8_SCHED; PG8_LDA(At, 1, 0); PG8_STAGE(PG8_SA(0, 1), a2 + hstepA, voffA);
;             PG8_WAIT_L(8); PG8_BAR; PG8_WAIT_L(0); PG8_MMA(0, 0, At, B0); PG8_BAR; PG8_SCHED;
;             PG8_LDB(B1, 1, 1); PG8_STAGE(PG8_SB(1, 0), b3, voffB);
;             PG8_BAR; PG8_WAIT_L(0); PG8_MMA(0, 1, At, B1); PG8_BAR;
;             PG8_LDA(At, 1, 1); PG8_STAGE(PG8_SA(1, 0), a3, voffA);
;             PG8_BAR; PG8_WAIT_L(0); PG8_MMA(1, 0, At, B0); PG8_BAR; PG8_SCHED;
;             PG8_STAGE(PG8_SB(1, 1), b3 + hstepB, voffB);
;             PG8_WAIT_V(6); PG8_BAR; PG8_MMA(1, 1, At, B1); PG8_BAR;
.LBB0_789:
	ds_read_b128 v[144:147], v199
	ds_read_b128 v[148:151], v199 offset:1024
	ds_read_b128 v[152:155], v199 offset:2048
	ds_read_b128 v[156:159], v199 offset:3072
	s_add_u32 s20, s18, 0x4000
	s_addc_u32 s21, s19, 0
	s_cmp_eq_u32 s46, 60
	s_cselect_b32 s24, s42, s20
	s_cselect_b32 s25, s11, s21
	s_cselect_b32 s20, s43, s44
	s_cselect_b32 s21, s9, s45
	s_add_u32 s22, s24, 0x8000
	s_addc_u32 s23, s25, 0
	v_lshl_add_u64 v[192:193], s[18:19], 0, v[136:137]
	s_add_i32 m0, s17, 0xc000
	ds_read_b128 v[160:163], v200
	ds_read_b128 v[164:167], v200 offset:1024
	ds_read_b128 v[168:171], v200 offset:2048
	ds_read_b128 v[172:175], v200 offset:3072
	ds_read_b128 v[176:179], v200 offset:4096
	ds_read_b128 v[180:183], v200 offset:5120
	ds_read_b128 v[184:187], v200 offset:6144
	ds_read_b128 v[188:191], v200 offset:7168
	global_load_lds_dwordx4 v[192:193], off
	s_add_i32 m0, s17, 0xe000
	v_lshl_add_u64 v[192:193], s[18:19], 0, v[138:139]
	global_load_lds_dwordx4 v[192:193], off
	s_waitcnt lgkmcnt(8)
	s_barrier
	s_waitcnt lgkmcnt(0)
	v_mfma_f32_16x16x32_bf16 v[124:127], v[144:147], v[160:163], v[124:127]
	v_mfma_f32_16x16x32_bf16 v[120:123], v[152:155], v[160:163], v[120:123]
	v_mfma_f32_16x16x32_bf16 v[112:115], v[144:147], v[168:171], v[112:115]
	v_mfma_f32_16x16x32_bf16 v[104:107], v[152:155], v[168:171], v[104:107]
	v_mfma_f32_16x16x32_bf16 v[96:99], v[144:147], v[176:179], v[96:99]
	v_mfma_f32_16x16x32_bf16 v[88:91], v[152:155], v[176:179], v[88:91]
	v_mfma_f32_16x16x32_bf16 v[80:83], v[144:147], v[184:187], v[80:83]
	v_mfma_f32_16x16x32_bf16 v[72:75], v[152:155], v[184:187], v[72:75]
	v_mfma_f32_16x16x32_bf16 v[124:127], v[148:151], v[164:167], v[124:127]
	v_mfma_f32_16x16x32_bf16 v[120:123], v[156:159], v[164:167], v[120:123]
	v_mfma_f32_16x16x32_bf16 v[112:115], v[148:151], v[172:175], v[112:115]
	v_mfma_f32_16x16x32_bf16 v[104:107], v[156:159], v[172:175], v[104:107]
	v_mfma_f32_16x16x32_bf16 v[96:99], v[148:151], v[180:183], v[96:99]
	v_mfma_f32_16x16x32_bf16 v[88:91], v[156:159], v[180:183], v[88:91]
	v_mfma_f32_16x16x32_bf16 v[80:83], v[148:151], v[188:191], v[80:83]
	v_mfma_f32_16x16x32_bf16 v[72:75], v[156:159], v[188:191], v[72:75]
	s_barrier
	s_add_i32 s47, s39, s31
	v_lshl_add_u64 v[214:215], s[20:21], 0, v[130:131]
	s_mov_b32 m0, s47
	ds_read_b128 v[192:195], v201
	ds_read_b128 v[202:205], v201 offset:1024
	ds_read_b128 v[206:209], v201 offset:2048
	ds_read_b128 v[210:213], v201 offset:3072
	global_load_lds_dwordx4 v[214:215], off
	s_add_i32 m0, s47, 0x2000
	v_lshl_add_u64 v[216:217], s[20:21], 0, v[134:135]
	global_load_lds_dwordx4 v[216:217], off
	s_barrier
	s_waitcnt lgkmcnt(0)
	v_mfma_f32_16x16x32_bf16 v[116:119], v[192:195], v[160:163], v[116:119]
	v_mfma_f32_16x16x32_bf16 v[108:111], v[206:209], v[160:163], v[108:111]
	v_mfma_f32_16x16x32_bf16 v[100:103], v[192:195], v[168:171], v[100:103]
	v_mfma_f32_16x16x32_bf16 v[92:95], v[206:209], v[168:171], v[92:95]
	v_mfma_f32_16x16x32_bf16 v[84:87], v[192:195], v[176:179], v[84:87]
	v_mfma_f32_16x16x32_bf16 v[76:79], v[206:209], v[176:179], v[76:79]
	v_mfma_f32_16x16x32_bf16 v[68:71], v[192:195], v[184:187], v[68:71]
	v_mfma_f32_16x16x32_bf16 v[64:67], v[206:209], v[184:187], v[64:67]
	v_mfma_f32_16x16x32_bf16 v[116:119], v[202:205], v[164:167], v[116:119]
	v_mfma_f32_16x16x32_bf16 v[108:111], v[210:213], v[164:167], v[108:111]
	v_mfma_f32_16x16x32_bf16 v[100:103], v[202:205], v[172:175], v[100:103]
	v_mfma_f32_16x16x32_bf16 v[92:95], v[210:213], v[172:175], v[92:95]
	v_mfma_f32_16x16x32_bf16 v[84:87], v[202:205], v[180:183], v[84:87]
	v_mfma_f32_16x16x32_bf16 v[76:79], v[210:213], v[180:183], v[76:79]
	v_mfma_f32_16x16x32_bf16 v[68:71], v[202:205], v[188:191], v[68:71]
	v_mfma_f32_16x16x32_bf16 v[64:67], v[210:213], v[188:191], v[64:67]
	s_mov_b32 m0, s17
	v_lshl_add_u64 v[218:219], s[24:25], 0, v[128:129]
	s_barrier
	ds_read_b128 v[160:163], v200 offset:16384
	ds_read_b128 v[164:167], v200 offset:17408
	ds_read_b128 v[168:171], v200 offset:18432
	ds_read_b128 v[172:175], v200 offset:19456
	ds_read_b128 v[176:179], v200 offset:20480
	ds_read_b128 v[180:183], v200 offset:21504
	ds_read_b128 v[184:187], v200 offset:22528
	ds_read_b128 v[188:191], v200 offset:23552
	global_load_lds_dwordx4 v[218:219], off
	s_mov_b32 m0, s33
	v_lshl_add_u64 v[218:219], s[24:25], 0, v[132:133]
	global_load_lds_dwordx4 v[218:219], off
	s_barrier
	s_waitcnt lgkmcnt(0)
	v_mfma_f32_16x16x32_bf16 v[60:63], v[144:147], v[160:163], v[60:63]
	v_mfma_f32_16x16x32_bf16 v[56:59], v[152:155], v[160:163], v[56:59]
	v_mfma_f32_16x16x32_bf16 v[48:51], v[144:147], v[168:171], v[48:51]
	v_mfma_f32_16x16x32_bf16 v[40:43], v[152:155], v[168:171], v[40:43]
	v_mfma_f32_16x16x32_bf16 v[32:35], v[144:147], v[176:179], v[32:35]
	v_mfma_f32_16x16x32_bf16 v[24:27], v[152:155], v[176:179], v[24:27]
	v_mfma_f32_16x16x32_bf16 v[16:19], v[144:147], v[184:187], v[16:19]
	v_mfma_f32_16x16x32_bf16 v[8:11], v[152:155], v[184:187], v[8:11]
	v_mfma_f32_16x16x32_bf16 v[60:63], v[148:151], v[164:167], v[60:63]
	v_mfma_f32_16x16x32_bf16 v[56:59], v[156:159], v[164:167], v[56:59]
	v_mfma_f32_16x16x32_bf16 v[48:51], v[148:151], v[172:175], v[48:51]
	v_mfma_f32_16x16x32_bf16 v[40:43], v[156:159], v[172:175], v[40:43]
	v_mfma_f32_16x16x32_bf16 v[32:35], v[148:151], v[180:183], v[32:35]
	v_mfma_f32_16x16x32_bf16 v[24:27], v[156:159], v[180:183], v[24:27]
	v_mfma_f32_16x16x32_bf16 v[16:19], v[148:151], v[188:191], v[16:19]
	v_mfma_f32_16x16x32_bf16 v[8:11], v[156:159], v[188:191], v[8:11]
	s_barrier
; #define PG8_STAGE(bufoff, gbase, voff) do { _Pragma("unroll") for (int _i = 0; _i < 2; ++_i) \
;         __builtin_amdgcn_global_load_lds((const unsigned*)((const char*)(gbase) + (voff)[_i]), (LAS unsigned*)(lds + (bufoff) + ldsw + _i * 8192), 16, 0, 0); } while (0)
; #define PG8_LDA(dst, b, h) do { _Pragma("unroll") for (int m = 0; m < 4; ++m) _Pragma("unroll") for (int k = 0; k < 2; ++k) dst[m][k] = *(const LAS bf16x8*)(lds + PG8_SA(b, h) + aoff + m * 2048 + k * 1024); } while (0)
; #define PG8_LDB(dst, b, h) do { _Pragma("unroll") for (int n = 0; n < 2; ++n) _Pragma("unroll") for (int k = 0; k < 2; ++k) dst[n][k] = *(const LAS bf16x8*)(lds + PG8_SB(b, h) + boff + n * 2048 + k * 1024); } while (0)
; #define PG8_WAIT_V(n) asm volatile("s_waitcnt vmcnt(" #n ")" ::: "memory")
; #define PG8_WAIT_L(n) asm volatile("s_waitcnt lgkmcnt(" #n ")" ::: "memory")
; #define PG8_BAR __builtin_amdgcn_s_barrier()
; #define PG8_SCHED __builtin_amdgcn_sched_barrier(0)
; template <class Epi, class Sched>
; __device__ __forceinline__ void gemm_phase(const int wv, LAS unsigned char* lds, const Gemm g, const Sched& S, const Epi& E) {
;     ...
;             PG8_LDB(B0, 0, 0); PG8_SCHED; PG8_LDA(At, 0, 0); PG8_STAGE(PG8_SA(1, 1), a1 + hstepA, voffA);
;             PG8_WAIT_L(8); PG8_BAR; PG8_WAIT_L(0); PG8_MMA(0, 0, At, B0); PG8_BAR; PG8_SCHED;
;             PG8_LDB(B1, 0, 1); PG8_STAGE(PG8_SB(0, 0), b2, voffB);
;             PG8_BAR; PG8_WAIT_L(0); PG8_MMA(0, 1, At, B1); PG8_BAR;
;             PG8_LDA(At, 0, 1); PG8_STAGE(PG8_SA(0, 0), a2, voffA);
;             PG8_BAR; PG8_WAIT_L(0); PG8_MMA(1, 0, At, B0); PG8_BAR; PG8_SCHED;
;             PG8_STAGE(PG8_SB(0, 1), b2 + hstepB, voffB);
;             PG8_WAIT_V(6); PG8_BAR; PG8_MMA(1, 1, At, B1); PG8_BAR;
;             PG8_LDB(B0, 1, 0); PG8_SCHED; PG8_LDA(At, 1, 0); PG8_STAGE(PG8_SA(0, 1), a2 + hstepA, voffA);
;             PG8_WAIT_L(8); PG8_BAR; PG8_WAIT_L(0); PG8_MMA(0, 0, At, B0); PG8_BAR; PG8_SCHED;
;             PG8_LDB(B1, 1, 1); PG8_STAGE(PG8_SB(1, 0), b3, voffB);
;             PG8_BAR; PG8_WAIT_L(0); PG8_MMA(0, 1, At, B1); PG8_BAR;
;             PG8_LDA(At, 1, 1); PG8_STAGE(PG8_SA(1, 0), a3, voffA);
;             PG8_BAR; PG8_WAIT_L(0); PG8_MMA(1, 0, At, B0); PG8_BAR; PG8_SCHED;
;             PG8_STAGE(PG8_SB(1, 1), b3 + hstepB, voffB);
;             PG8_WAIT_V(6); PG8_BAR; PG8_MMA(1, 1, At, B1); PG8_BAR;
	s_add_u32 s48, s20, 0x100000
	s_addc_u32 s49, s21, 0
	s_add_i32 s47, s40, s31
	s_mov_b32 m0, s47
	v_lshl_add_u64 v[144:145], s[48:49], 0, v[130:131]
	global_load_lds_dwordx4 v[144:145], off
	s_add_i32 m0, s47, 0x2000
	v_lshl_add_u64 v[144:145], s[48:49], 0, v[134:135]
	global_load_lds_dwordx4 v[144:145], off
	s_waitcnt vmcnt(6)
	s_barrier
	v_mfma_f32_16x16x32_bf16 v[52:55], v[192:195], v[160:163], v[52:55]
	v_mfma_f32_16x16x32_bf16 v[44:47], v[206:209], v[160:163], v[44:47]
	v_mfma_f32_16x16x32_bf16 v[36:39], v[192:195], v[168:171], v[36:39]
	v_mfma_f32_16x16x32_bf16 v[28:31], v[206:209], v[168:171], v[28:31]
	v_mfma_f32_16x16x32_bf16 v[20:23], v[192:195], v[176:179], v[20:23]
	v_mfma_f32_16x16x32_bf16 v[12:15], v[206:209], v[176:179], v[12:15]
	v_mfma_f32_16x16x32_bf16 v[4:7], v[192:195], v[184:187], v[4:7]
	v_mfma_f32_16x16x32_bf16 v[0:3], v[206:209], v[184:187], v[0:3]
	v_mfma_f32_16x16x32_bf16 v[52:55], v[202:205], v[164:167], v[52:55]
	v_mfma_f32_16x16x32_bf16 v[44:47], v[210:213], v[164:167], v[44:47]
	v_mfma_f32_16x16x32_bf16 v[36:39], v[202:205], v[172:175], v[36:39]
	v_mfma_f32_16x16x32_bf16 v[28:31], v[210:213], v[172:175], v[28:31]
	v_mfma_f32_16x16x32_bf16 v[20:23], v[202:205], v[180:183], v[20:23]
	v_mfma_f32_16x16x32_bf16 v[12:15], v[210:213], v[180:183], v[12:15]
	v_mfma_f32_16x16x32_bf16 v[4:7], v[202:205], v[188:191], v[4:7]
	v_mfma_f32_16x16x32_bf16 v[0:3], v[210:213], v[188:191], v[0:3]
	s_add_i32 s47, 0, 0x18000
	v_add_u32_e32 v156, s47, v197
	s_barrier
	ds_read_b128 v[144:147], v156
	ds_read_b128 v[148:151], v156 offset:1024
	ds_read_b128 v[152:155], v156 offset:2048
	ds_read_b128 v[156:159], v156 offset:3072
	s_add_u32 s24, s24, 0x4000
	s_addc_u32 s25, s25, 0
	s_mov_b32 m0, s34
	v_lshl_add_u64 v[192:193], s[24:25], 0, v[128:129]
	ds_read_b128 v[160:163], v200 offset:32768
	ds_read_b128 v[164:167], v200 offset:33792
	ds_read_b128 v[168:171], v200 offset:34816
	ds_read_b128 v[172:175], v200 offset:35840
	ds_read_b128 v[176:179], v200 offset:36864
	ds_read_b128 v[180:183], v200 offset:37888
	ds_read_b128 v[184:187], v200 offset:38912
	ds_read_b128 v[188:191], v200 offset:39936
	global_load_lds_dwordx4 v[192:193], off
	s_mov_b32 m0, s35
	v_lshl_add_u64 v[192:193], s[24:25], 0, v[132:133]
	global_load_lds_dwordx4 v[192:193], off
	s_waitcnt lgkmcnt(8)
	s_barrier
	s_waitcnt lgkmcnt(0)
	v_mfma_f32_16x16x32_bf16 v[124:127], v[144:147], v[160:163], v[124:127]
	v_mfma_f32_16x16x32_bf16 v[120:123], v[152:155], v[160:163], v[120:123]
	v_mfma_f32_16x16x32_bf16 v[112:115], v[144:147], v[168:171], v[112:115]
	v_mfma_f32_16x16x32_bf16 v[104:107], v[152:155], v[168:171], v[104:107]
	v_mfma_f32_16x16x32_bf16 v[96:99], v[144:147], v[176:179], v[96:99]
	v_mfma_f32_16x16x32_bf16 v[88:91], v[152:155], v[176:179], v[88:91]
	v_mfma_f32_16x16x32_bf16 v[80:83], v[144:147], v[184:187], v[80:83]
	v_mfma_f32_16x16x32_bf16 v[72:75], v[152:155], v[184:187], v[72:75]
	v_mfma_f32_16x16x32_bf16 v[124:127], v[148:151], v[164:167], v[124:127]
	v_mfma_f32_16x16x32_bf16 v[120:123], v[156:159], v[164:167], v[120:123]
	v_mfma_f32_16x16x32_bf16 v[112:115], v[148:151], v[172:175], v[112:115]
	v_mfma_f32_16x16x32_bf16 v[104:107], v[156:159], v[172:175], v[104:107]
	v_mfma_f32_16x16x32_bf16 v[96:99], v[148:151], v[180:183], v[96:99]
	v_mfma_f32_16x16x32_bf16 v[88:91], v[156:159], v[180:183], v[88:91]
	v_mfma_f32_16x16x32_bf16 v[80:83], v[148:151], v[188:191], v[80:83]
	v_mfma_f32_16x16x32_bf16 v[72:75], v[156:159], v[188:191], v[72:75]
	s_barrier
	s_add_i32 s24, 0, 0x1c000
	s_add_i32 s25, s47, s31
	v_add_u32_e32 v210, s24, v197
	v_lshl_add_u64 v[214:215], v[214:215], 0, s[6:7]
	s_mov_b32 m0, s25
	ds_read_b128 v[192:195], v210
	ds_read_b128 v[202:205], v210 offset:1024
	ds_read_b128 v[206:209], v210 offset:2048
	ds_read_b128 v[210:213], v210 offset:3072
	global_load_lds_dwordx4 v[214:215], off
	s_add_i32 m0, s25, 0x2000
	v_lshl_add_u64 v[214:215], v[216:217], 0, s[6:7]
	global_load_lds_dwordx4 v[214:215], off
	s_barrier
	s_waitcnt lgkmcnt(0)
	v_mfma_f32_16x16x32_bf16 v[116:119], v[192:195], v[160:163], v[116:119]
	v_mfma_f32_16x16x32_bf16 v[108:111], v[206:209], v[160:163], v[108:111]
	v_mfma_f32_16x16x32_bf16 v[100:103], v[192:195], v[168:171], v[100:103]
	v_mfma_f32_16x16x32_bf16 v[92:95], v[206:209], v[168:171], v[92:95]
	v_mfma_f32_16x16x32_bf16 v[84:87], v[192:195], v[176:179], v[84:87]
	v_mfma_f32_16x16x32_bf16 v[76:79], v[206:209], v[176:179], v[76:79]
	v_mfma_f32_16x16x32_bf16 v[68:71], v[192:195], v[184:187], v[68:71]
	v_mfma_f32_16x16x32_bf16 v[64:67], v[206:209], v[184:187], v[64:67]
	v_mfma_f32_16x16x32_bf16 v[116:119], v[202:205], v[164:167], v[116:119]
	v_mfma_f32_16x16x32_bf16 v[108:111], v[210:213], v[164:167], v[108:111]
	v_mfma_f32_16x16x32_bf16 v[100:103], v[202:205], v[172:175], v[100:103]
	v_mfma_f32_16x16x32_bf16 v[92:95], v[210:213], v[172:175], v[92:95]
	v_mfma_f32_16x16x32_bf16 v[84:87], v[202:205], v[180:183], v[84:87]
	v_mfma_f32_16x16x32_bf16 v[76:79], v[210:213], v[180:183], v[76:79]
	v_mfma_f32_16x16x32_bf16 v[68:71], v[202:205], v[188:191], v[68:71]
	v_mfma_f32_16x16x32_bf16 v[64:67], v[210:213], v[188:191], v[64:67]
	s_mov_b32 m0, s37
	v_lshl_add_u64 v[214:215], s[22:23], 0, v[128:129]
	s_barrier
	ds_read_b128 v[160:163], v200 offset:49152
	ds_read_b128 v[164:167], v200 offset:50176
	ds_read_b128 v[168:171], v200 offset:51200
	ds_read_b128 v[172:175], v200 offset:52224
	ds_read_b128 v[176:179], v200 offset:53248
	ds_read_b128 v[180:183], v200 offset:54272
	ds_read_b128 v[184:187], v200 offset:55296
	ds_read_b128 v[188:191], v200 offset:56320
	global_load_lds_dwordx4 v[214:215], off
	s_mov_b32 m0, s38
	v_lshl_add_u64 v[214:215], s[22:23], 0, v[132:133]
	global_load_lds_dwordx4 v[214:215], off
	s_barrier
; #define PG8_STAGE(bufoff, gbase, voff) do { _Pragma("unroll") for (int _i = 0; _i < 2; ++_i) \
;         __builtin_amdgcn_global_load_lds((const unsigned*)((const char*)(gbase) + (voff)[_i]), (LAS unsigned*)(lds + (bufoff) + ldsw + _i * 8192), 16, 0, 0); } while (0)
; #define PG8_LDA(dst, b, h) do { _Pragma("unroll") for (int m = 0; m < 4; ++m) _Pragma("unroll") for (int k = 0; k < 2; ++k) dst[m][k] = *(const LAS bf16x8*)(lds + PG8_SA(b, h) + aoff + m * 2048 + k * 1024); } while (0)
; #define PG8_LDB(dst, b, h) do { _Pragma("unroll") for (int n = 0; n < 2; ++n) _Pragma("unroll") for (int k = 0; k < 2; ++k) dst[n][k] = *(const LAS bf16x8*)(lds + PG8_SB(b, h) + boff + n * 2048 + k * 1024); } while (0)
; #define PG8_WAIT_V(n) asm volatile("s_waitcnt vmcnt(" #n ")" ::: "memory")
; #define PG8_WAIT_L(n) asm volatile("s_waitcnt lgkmcnt(" #n ")" ::: "memory")
; template <class Epi, class Sched>
; __device__ __forceinline__ void gemm_phase(const int wv, LAS unsigned char* lds, const Gemm g, const Sched& S, const Epi& E) {
;     ...
;             PG8_WAIT_V(6); PG8_BAR; PG8_MMA(1, 1, At, B1); PG8_BAR;
;             PG8_LDB(B0, 1, 0); PG8_SCHED; PG8_LDA(At, 1, 0); PG8_STAGE(PG8_SA(0, 1), a2 + hstepA, voffA);
;             PG8_WAIT_L(8); PG8_BAR; PG8_WAIT_L(0); PG8_MMA(0, 0, At, B0); PG8_BAR; PG8_SCHED;
;             PG8_LDB(B1, 1, 1); PG8_STAGE(PG8_SB(1, 0), b3, voffB);
;             PG8_BAR; PG8_WAIT_L(0); PG8_MMA(0, 1, At, B1); PG8_BAR;
;             PG8_LDA(At, 1, 1); PG8_STAGE(PG8_SA(1, 0), a3, voffA);
;             PG8_BAR; PG8_WAIT_L(0); PG8_MMA(1, 0, At, B0); PG8_BAR; PG8_SCHED;
;             PG8_STAGE(PG8_SB(1, 1), b3 + hstepB, voffB);
;             PG8_WAIT_V(6); PG8_BAR; PG8_MMA(1, 1, At, B1); PG8_BAR;
;         }
;     __device__ __forceinline__ void operator()(const f32x4 (&acc)[2][2][4][2], const Unit& u, int wr, int wc, int fr, int fq) const {
;         const int row0 = u.pm * 256 + wr * 64 + fr; const int col0 = u.pn * 256 + wc * 32 + 4 * fq;
;         u32x2 xv[2][4][2][2];
; #pragma unroll
;         for (int ai = 0; ai < 2; ++ai)
; #pragma unroll
;             for (int m = 0; m < 4; ++m)
; #pragma unroll
;                 for (int bj = 0; bj < 2; ++bj)
; #pragma unroll
;                     for (int n = 0; n < 2; ++n) xv[ai][m][bj][n] = *(const u32x2*)(x1b + (size_t)(row0 + ai * 128 + m * 16) * 1024 + col0 + bj * 128 + n * 16);
	s_waitcnt lgkmcnt(0)
	v_mfma_f32_16x16x32_bf16 v[60:63], v[144:147], v[160:163], v[60:63]
	v_mfma_f32_16x16x32_bf16 v[56:59], v[152:155], v[160:163], v[56:59]
	v_mfma_f32_16x16x32_bf16 v[48:51], v[144:147], v[168:171], v[48:51]
	v_mfma_f32_16x16x32_bf16 v[40:43], v[152:155], v[168:171], v[40:43]
	v_mfma_f32_16x16x32_bf16 v[32:35], v[144:147], v[176:179], v[32:35]
	v_mfma_f32_16x16x32_bf16 v[24:27], v[152:155], v[176:179], v[24:27]
	v_mfma_f32_16x16x32_bf16 v[16:19], v[144:147], v[184:187], v[16:19]
	v_mfma_f32_16x16x32_bf16 v[8:11], v[152:155], v[184:187], v[8:11]
	v_mfma_f32_16x16x32_bf16 v[60:63], v[148:151], v[164:167], v[60:63]
	v_mfma_f32_16x16x32_bf16 v[56:59], v[156:159], v[164:167], v[56:59]
	v_mfma_f32_16x16x32_bf16 v[48:51], v[148:151], v[172:175], v[48:51]
	v_mfma_f32_16x16x32_bf16 v[40:43], v[156:159], v[172:175], v[40:43]
	v_mfma_f32_16x16x32_bf16 v[32:35], v[148:151], v[180:183], v[32:35]
	v_mfma_f32_16x16x32_bf16 v[24:27], v[156:159], v[180:183], v[24:27]
	v_mfma_f32_16x16x32_bf16 v[16:19], v[148:151], v[188:191], v[16:19]
	v_mfma_f32_16x16x32_bf16 v[8:11], v[156:159], v[188:191], v[8:11]
	s_barrier
	s_add_u32 s20, s20, 0x100080
	s_addc_u32 s21, s21, 0
	s_add_i32 s22, s24, s31
	s_mov_b32 m0, s22
	v_lshl_add_u64 v[144:145], s[20:21], 0, v[130:131]
	global_load_lds_dwordx4 v[144:145], off
	s_add_i32 m0, s22, 0x2000
	v_lshl_add_u64 v[144:145], s[20:21], 0, v[134:135]
	global_load_lds_dwordx4 v[144:145], off
	s_waitcnt vmcnt(6)
	s_barrier
	v_mfma_f32_16x16x32_bf16 v[52:55], v[192:195], v[160:163], v[52:55]
	v_mfma_f32_16x16x32_bf16 v[44:47], v[206:209], v[160:163], v[44:47]
	v_mfma_f32_16x16x32_bf16 v[36:39], v[192:195], v[168:171], v[36:39]
	v_mfma_f32_16x16x32_bf16 v[28:31], v[206:209], v[168:171], v[28:31]
	v_mfma_f32_16x16x32_bf16 v[20:23], v[192:195], v[176:179], v[20:23]
	v_mfma_f32_16x16x32_bf16 v[12:15], v[206:209], v[176:179], v[12:15]
	v_mfma_f32_16x16x32_bf16 v[4:7], v[192:195], v[184:187], v[4:7]
	v_mfma_f32_16x16x32_bf16 v[0:3], v[206:209], v[184:187], v[0:3]
	v_mfma_f32_16x16x32_bf16 v[52:55], v[202:205], v[164:167], v[52:55]
	v_mfma_f32_16x16x32_bf16 v[44:47], v[210:213], v[164:167], v[44:47]
	v_mfma_f32_16x16x32_bf16 v[36:39], v[202:205], v[172:175], v[36:39]
	v_mfma_f32_16x16x32_bf16 v[28:31], v[210:213], v[172:175], v[28:31]
	v_mfma_f32_16x16x32_bf16 v[20:23], v[202:205], v[180:183], v[20:23]
	v_mfma_f32_16x16x32_bf16 v[12:15], v[210:213], v[180:183], v[12:15]
	v_mfma_f32_16x16x32_bf16 v[4:7], v[202:205], v[188:191], v[4:7]
	v_mfma_f32_16x16x32_bf16 v[0:3], v[210:213], v[188:191], v[0:3]
	s_add_i32 s46, s46, 2
	s_add_u32 s44, s44, 0x100
	s_addc_u32 s45, s45, 0
	s_add_u32 s18, s18, 0x10000
	s_addc_u32 s19, s19, 0
	s_cmp_gt_u32 s46, 61
	s_barrier
	s_cbranch_scc0 .LBB0_789
	v_lshl_add_u32 v146, s16, 8, v196
	v_lshl_or_b32 v148, s41, 8, v198
	v_ashrrev_i32_e32 v149, 31, v148
	v_ashrrev_i32_e32 v147, 31, v146
	v_lshl_add_u64 v[150:151], v[148:149], 1, s[2:3]
	v_lshlrev_b64 v[144:145], 11, v[146:147]
	v_lshl_add_u64 v[144:145], v[150:151], 0, v[144:145]
	global_load_dwordx2 v[202:203], v[144:145], off
	global_load_dwordx2 v[204:205], v[144:145], off offset:32
	global_load_dwordx2 v[206:207], v[144:145], off offset:256
	v_or_b32_e32 v208, 16, v146
	global_load_dwordx2 v[210:211], v[144:145], off offset:288
	v_ashrrev_i32_e32 v209, 31, v208
	v_lshlrev_b64 v[144:145], 11, v[208:209]
	v_lshl_add_u64 v[152:153], v[150:151], 0, v[144:145]
	global_load_dwordx2 v[212:213], v[152:153], off
	global_load_dwordx2 v[214:215], v[152:153], off offset:32
	global_load_dwordx2 v[216:217], v[152:153], off offset:256
	global_load_dwordx2 v[218:219], v[152:153], off offset:288
	v_or_b32_e32 v192, 32, v146
	v_or_b32_e32 v182, 48, v146
	v_add_u32_e32 v174, 0x80, v146
	v_add_u32_e32 v164, 0x90, v146
	v_add_u32_e32 v154, 0xa0, v146
	v_add_u32_e32 v144, 0xb0, v146
	v_ashrrev_i32_e32 v193, 31, v192
	v_ashrrev_i32_e32 v183, 31, v182
	v_ashrrev_i32_e32 v175, 31, v174
	v_ashrrev_i32_e32 v165, 31, v164
	v_ashrrev_i32_e32 v155, 31, v154
	v_ashrrev_i32_e32 v145, 31, v144
	v_lshlrev_b64 v[146:147], 12, v[146:147]
	v_lshlrev_b64 v[156:157], 11, v[192:193]
	v_lshlrev_b64 v[158:159], 11, v[182:183]
	v_lshlrev_b64 v[160:161], 11, v[174:175]
	v_lshlrev_b64 v[162:163], 11, v[164:165]
	v_lshlrev_b64 v[166:167], 11, v[154:155]
	v_lshlrev_b64 v[148:149], 2, v[148:149]
	v_lshlrev_b64 v[168:169], 11, v[144:145]
	v_lshl_add_u64 v[146:147], s[4:5], 0, v[146:147]
	v_lshl_add_u64 v[156:157], v[150:151], 0, v[156:157]
	v_lshl_add_u64 v[158:159], v[150:151], 0, v[158:159]
	v_lshl_add_u64 v[160:161], v[150:151], 0, v[160:161]
	v_lshl_add_u64 v[162:163], v[150:151], 0, v[162:163]
	v_lshl_add_u64 v[152:153], v[150:151], 0, v[166:167]
	v_lshl_add_u64 v[220:221], v[150:151], 0, v[168:169]
	v_lshl_add_u64 v[222:223], v[146:147], 0, v[148:149]
	global_load_dwordx2 v[224:225], v[156:157], off
	global_load_dwordx2 v[226:227], v[156:157], off offset:32
	global_load_dwordx2 v[228:229], v[156:157], off offset:256
	global_load_dwordx2 v[230:231], v[156:157], off offset:288
	global_load_dwordx2 v[232:233], v[158:159], off
	global_load_dwordx2 v[194:195], v[158:159], off offset:32
	global_load_dwordx2 v[190:191], v[158:159], off offset:256
	global_load_dwordx2 v[188:189], v[158:159], off offset:288
	global_load_dwordx2 v[186:187], v[160:161], off
	global_load_dwordx2 v[184:185], v[160:161], off offset:32
	global_load_dwordx2 v[180:181], v[160:161], off offset:256
	global_load_dwordx2 v[178:179], v[160:161], off offset:288
	global_load_dwordx2 v[176:177], v[162:163], off
	global_load_dwordx2 v[172:173], v[162:163], off offset:32
	global_load_dwordx2 v[170:171], v[162:163], off offset:256
	global_load_dwordx2 v[168:169], v[162:163], off offset:288
	global_load_dwordx2 v[166:167], v[152:153], off
	s_nop 0
	global_load_dwordx2 v[162:163], v[152:153], off offset:32
	global_load_dwordx2 v[160:161], v[152:153], off offset:256
	global_load_dwordx2 v[158:159], v[152:153], off offset:288
	global_load_dwordx2 v[156:157], v[220:221], off
	s_nop 0
	global_load_dwordx2 v[152:153], v[220:221], off offset:32
	global_load_dwordx2 v[150:151], v[220:221], off offset:256
	global_load_dwordx2 v[146:147], v[220:221], off offset:288
	s_and_b64 vcc, exec, s[0:1]
	s_mov_b32 s41, s8
	s_mov_b32 s16, s10
	s_mov_b64 s[18:19], s[14:15]
	s_mov_b64 s[20:21], s[12:13]
	s_waitcnt vmcnt(0)
; __device__ __forceinline__ float bflo(unsigned u) { return __uint_as_float(u << 16); }
; __device__ __forceinline__ float bfhi(unsigned u) { return __uint_as_float(u & 0xffff0000u); }
;     __device__ __forceinline__ void operator()(const f32x4 (&acc)[2][2][4][2], const Unit& u, int wr, int wc, int fr, int fq) const {
;     ...
; #pragma unroll
;         for (int ai = 0; ai < 2; ++ai)
; #pragma unroll
;             for (int m = 0; m < 4; ++m)
; #pragma unroll
;                 for (int bj = 0; bj < 2; ++bj)
; #pragma unroll
;                     for (int n = 0; n < 2; ++n) {
;                         const size_t o = (size_t)(row0 + ai * 128 + m * 16) * 1024 + col0 + bj * 128 + n * 16;
;                         const u32x2 v = xv[ai][m][bj][n]; const f32x4 a = acc[ai][bj][m][n];
;                         *(f32x4*)(out + o) = (f32x4){bflo(v.x) + a[0], bfhi(v.x) + a[1], bflo(v.y) + a[2], bfhi(v.y) + a[3]};
;                     }
	v_lshlrev_b32_e32 v220, 16, v202
	v_and_b32_e32 v221, 0xffff0000, v202
	v_lshlrev_b32_e32 v202, 16, v203
	v_and_b32_e32 v203, 0xffff0000, v203
	v_lshlrev_b32_e32 v234, 16, v204
	v_and_b32_e32 v235, 0xffff0000, v204
	v_lshlrev_b32_e32 v204, 16, v205
	v_and_b32_e32 v205, 0xffff0000, v205
	v_pk_add_f32 v[124:125], v[124:125], v[220:221]
	v_pk_add_f32 v[126:127], v[126:127], v[202:203]
	v_pk_add_f32 v[120:121], v[120:121], v[234:235]
	v_lshlrev_b32_e32 v236, 16, v206
	v_and_b32_e32 v237, 0xffff0000, v206
	v_pk_add_f32 v[122:123], v[122:123], v[204:205]
	global_store_dwordx4 v[222:223], v[124:127], off
	global_store_dwordx4 v[222:223], v[120:123], off offset:64
	v_pk_add_f32 v[116:117], v[116:117], v[236:237]
	s_nop 0
	v_lshlrev_b32_e32 v120, 16, v207
	v_and_b32_e32 v121, 0xffff0000, v207
	v_pk_add_f32 v[118:119], v[118:119], v[120:121]
	global_store_dwordx4 v[222:223], v[116:119], off offset:512
	s_nop 1
	v_lshlrev_b32_e32 v116, 16, v210
	v_and_b32_e32 v117, 0xffff0000, v210
	v_pk_add_f32 v[108:109], v[108:109], v[116:117]
	v_lshlrev_b32_e32 v116, 16, v211
	v_and_b32_e32 v117, 0xffff0000, v211
	v_pk_add_f32 v[110:111], v[110:111], v[116:117]
	global_store_dwordx4 v[222:223], v[108:111], off offset:576
	v_lshlrev_b64 v[116:117], 12, v[208:209]
	s_nop 0
	v_lshlrev_b32_e32 v108, 16, v212
	v_and_b32_e32 v109, 0xffff0000, v212
	v_pk_add_f32 v[108:109], v[112:113], v[108:109]
	v_lshlrev_b32_e32 v110, 16, v213
	v_and_b32_e32 v111, 0xffff0000, v213
	v_lshl_add_u64 v[112:113], s[4:5], 0, v[116:117]
	v_pk_add_f32 v[110:111], v[114:115], v[110:111]
	v_lshl_add_u64 v[112:113], v[112:113], 0, v[148:149]
	global_store_dwordx4 v[112:113], v[108:111], off
	s_nop 1
	v_lshlrev_b32_e32 v108, 16, v214
	v_and_b32_e32 v109, 0xffff0000, v214
	v_pk_add_f32 v[104:105], v[104:105], v[108:109]
	v_lshlrev_b32_e32 v108, 16, v215
	v_and_b32_e32 v109, 0xffff0000, v215
	v_pk_add_f32 v[106:107], v[106:107], v[108:109]
	global_store_dwordx4 v[112:113], v[104:107], off offset:64
	s_nop 1
	v_lshlrev_b32_e32 v104, 16, v216
	v_and_b32_e32 v105, 0xffff0000, v216
	v_pk_add_f32 v[100:101], v[100:101], v[104:105]
	v_lshlrev_b32_e32 v104, 16, v217
	v_and_b32_e32 v105, 0xffff0000, v217
	v_pk_add_f32 v[102:103], v[102:103], v[104:105]
	global_store_dwordx4 v[112:113], v[100:103], off offset:512
	s_nop 1
	v_lshlrev_b32_e32 v100, 16, v218
	v_and_b32_e32 v101, 0xffff0000, v218
	v_pk_add_f32 v[92:93], v[92:93], v[100:101]
	v_lshlrev_b32_e32 v100, 16, v219
	v_and_b32_e32 v101, 0xffff0000, v219
	v_pk_add_f32 v[94:95], v[94:95], v[100:101]
	global_store_dwordx4 v[112:113], v[92:95], off offset:576
	v_lshlrev_b64 v[100:101], 12, v[192:193]
	s_nop 0
	v_lshlrev_b32_e32 v92, 16, v224
	v_and_b32_e32 v93, 0xffff0000, v224
	v_pk_add_f32 v[92:93], v[96:97], v[92:93]
	v_lshlrev_b32_e32 v94, 16, v225
	v_and_b32_e32 v95, 0xffff0000, v225
	v_lshl_add_u64 v[96:97], s[4:5], 0, v[100:101]
	v_pk_add_f32 v[94:95], v[98:99], v[94:95]
	v_lshl_add_u64 v[96:97], v[96:97], 0, v[148:149]
	global_store_dwordx4 v[96:97], v[92:95], off
	s_nop 1
	v_lshlrev_b32_e32 v92, 16, v226
	v_and_b32_e32 v93, 0xffff0000, v226
	v_pk_add_f32 v[88:89], v[88:89], v[92:93]
	v_lshlrev_b32_e32 v92, 16, v227
	v_and_b32_e32 v93, 0xffff0000, v227
	v_pk_add_f32 v[90:91], v[90:91], v[92:93]
	global_store_dwordx4 v[96:97], v[88:91], off offset:64
	s_nop 1
	v_lshlrev_b32_e32 v88, 16, v228
	v_and_b32_e32 v89, 0xffff0000, v228
	v_pk_add_f32 v[84:85], v[84:85], v[88:89]
	v_lshlrev_b32_e32 v88, 16, v229
	v_and_b32_e32 v89, 0xffff0000, v229
	v_pk_add_f32 v[86:87], v[86:87], v[88:89]
	global_store_dwordx4 v[96:97], v[84:87], off offset:512
	s_nop 1
	v_lshlrev_b32_e32 v84, 16, v230
	v_and_b32_e32 v85, 0xffff0000, v230
	v_pk_add_f32 v[76:77], v[76:77], v[84:85]
	v_lshlrev_b32_e32 v84, 16, v231
	v_and_b32_e32 v85, 0xffff0000, v231
	v_pk_add_f32 v[78:79], v[78:79], v[84:85]
	global_store_dwordx4 v[96:97], v[76:79], off offset:576
	v_lshlrev_b64 v[84:85], 12, v[182:183]
	s_nop 0
	v_lshlrev_b32_e32 v76, 16, v232
	v_and_b32_e32 v77, 0xffff0000, v232
	v_pk_add_f32 v[76:77], v[80:81], v[76:77]
	v_lshlrev_b32_e32 v78, 16, v233
	v_and_b32_e32 v79, 0xffff0000, v233
	v_lshl_add_u64 v[80:81], s[4:5], 0, v[84:85]
	v_pk_add_f32 v[78:79], v[82:83], v[78:79]
	v_lshl_add_u64 v[80:81], v[80:81], 0, v[148:149]
	global_store_dwordx4 v[80:81], v[76:79], off
	s_nop 1
	v_lshlrev_b32_e32 v76, 16, v194
	v_and_b32_e32 v77, 0xffff0000, v194
	v_pk_add_f32 v[72:73], v[72:73], v[76:77]
	v_lshlrev_b32_e32 v76, 16, v195
	v_and_b32_e32 v77, 0xffff0000, v195
	v_pk_add_f32 v[74:75], v[74:75], v[76:77]
	global_store_dwordx4 v[80:81], v[72:75], off offset:64
	s_nop 1
	v_lshlrev_b32_e32 v72, 16, v190
	v_and_b32_e32 v73, 0xffff0000, v190
	v_pk_add_f32 v[68:69], v[68:69], v[72:73]
	v_lshlrev_b32_e32 v72, 16, v191
	v_and_b32_e32 v73, 0xffff0000, v191
	v_pk_add_f32 v[70:71], v[70:71], v[72:73]
	global_store_dwordx4 v[80:81], v[68:71], off offset:512
	s_nop 1
	v_lshlrev_b32_e32 v68, 16, v188
	v_and_b32_e32 v69, 0xffff0000, v188
	v_pk_add_f32 v[64:65], v[64:65], v[68:69]
	v_lshlrev_b32_e32 v68, 16, v189
	v_and_b32_e32 v69, 0xffff0000, v189
	v_pk_add_f32 v[66:67], v[66:67], v[68:69]
	global_store_dwordx4 v[80:81], v[64:67], off offset:576
	s_nop 1
; __device__ __forceinline__ float bflo(unsigned u) { return __uint_as_float(u << 16); }
; __device__ __forceinline__ float bfhi(unsigned u) { return __uint_as_float(u & 0xffff0000u); }
; #define PG8_WAIT_V(n) asm volatile("s_waitcnt vmcnt(" #n ")" ::: "memory")
; #define PG8_BAR __builtin_amdgcn_s_barrier()
; template <class Epi, class Sched>
; __device__ __forceinline__ void gemm_phase(const int wv, LAS unsigned char* lds, const Gemm g, const Sched& S, const Epi& E) {
;     ...
;         E(acc, cur, wr, wc, fr, fq); S.done(cur);
;         if (!has_next) break;
; #pragma unroll
;         for (int a = 0; a < 2; ++a)
; #pragma unroll
;             for (int b = 0; b < 2; ++b)
; #pragma unroll
;                 for (int m = 0; m < 4; ++m)
; #pragma unroll
;                     for (int n = 0; n < 2; ++n) acc[a][b][m][n] = (f32x4){0.f, 0.f, 0.f, 0.f};
;         cur = nxt; cA = nA; cB = nB; ++ui;
;     }
;     PG8_WAIT_V(0);
;     if (wr == 0) PG8_BAR;
;     __device__ __forceinline__ void operator()(const f32x4 (&acc)[2][2][4][2], const Unit& u, int wr, int wc, int fr, int fq) const {
;     ...
; #pragma unroll
;         for (int ai = 0; ai < 2; ++ai)
; #pragma unroll
;             for (int m = 0; m < 4; ++m)
; #pragma unroll
;                 for (int bj = 0; bj < 2; ++bj)
; #pragma unroll
;                     for (int n = 0; n < 2; ++n) {
;                         const size_t o = (size_t)(row0 + ai * 128 + m * 16) * 1024 + col0 + bj * 128 + n * 16;
;                         const u32x2 v = xv[ai][m][bj][n]; const f32x4 a = acc[ai][bj][m][n];
;                         *(f32x4*)(out + o) = (f32x4){bflo(v.x) + a[0], bfhi(v.x) + a[1], bflo(v.y) + a[2], bfhi(v.y) + a[3]};
;                     }
	v_lshlrev_b64 v[64:65], 12, v[174:175]
	v_lshlrev_b32_e32 v66, 16, v186
	v_and_b32_e32 v67, 0xffff0000, v186
	v_pk_add_f32 v[60:61], v[60:61], v[66:67]
	v_lshlrev_b32_e32 v66, 16, v187
	v_and_b32_e32 v67, 0xffff0000, v187
	v_lshl_add_u64 v[64:65], s[4:5], 0, v[64:65]
	v_pk_add_f32 v[62:63], v[62:63], v[66:67]
	v_lshl_add_u64 v[64:65], v[64:65], 0, v[148:149]
	global_store_dwordx4 v[64:65], v[60:63], off
	s_nop 1
	v_lshlrev_b32_e32 v60, 16, v184
	v_and_b32_e32 v61, 0xffff0000, v184
	v_pk_add_f32 v[56:57], v[56:57], v[60:61]
	v_lshlrev_b32_e32 v60, 16, v185
	v_and_b32_e32 v61, 0xffff0000, v185
	v_pk_add_f32 v[58:59], v[58:59], v[60:61]
	global_store_dwordx4 v[64:65], v[56:59], off offset:64
	s_nop 1
	v_lshlrev_b32_e32 v56, 16, v180
	v_and_b32_e32 v57, 0xffff0000, v180
	v_pk_add_f32 v[52:53], v[52:53], v[56:57]
	v_lshlrev_b32_e32 v56, 16, v181
	v_and_b32_e32 v57, 0xffff0000, v181
	v_pk_add_f32 v[54:55], v[54:55], v[56:57]
	global_store_dwordx4 v[64:65], v[52:55], off offset:512
	s_nop 1
	v_lshlrev_b32_e32 v52, 16, v178
	v_and_b32_e32 v53, 0xffff0000, v178
	v_pk_add_f32 v[44:45], v[44:45], v[52:53]
	v_lshlrev_b32_e32 v52, 16, v179
	v_and_b32_e32 v53, 0xffff0000, v179
	v_pk_add_f32 v[46:47], v[46:47], v[52:53]
	global_store_dwordx4 v[64:65], v[44:47], off offset:576
	v_lshlrev_b64 v[52:53], 12, v[164:165]
	s_nop 0
	v_lshlrev_b32_e32 v44, 16, v176
	v_and_b32_e32 v45, 0xffff0000, v176
	v_pk_add_f32 v[44:45], v[48:49], v[44:45]
	v_lshlrev_b32_e32 v46, 16, v177
	v_and_b32_e32 v47, 0xffff0000, v177
	v_lshl_add_u64 v[48:49], s[4:5], 0, v[52:53]
	v_pk_add_f32 v[46:47], v[50:51], v[46:47]
	v_lshl_add_u64 v[48:49], v[48:49], 0, v[148:149]
	global_store_dwordx4 v[48:49], v[44:47], off
	s_nop 1
	v_lshlrev_b32_e32 v44, 16, v172
	v_and_b32_e32 v45, 0xffff0000, v172
	v_pk_add_f32 v[40:41], v[40:41], v[44:45]
	v_lshlrev_b32_e32 v44, 16, v173
	v_and_b32_e32 v45, 0xffff0000, v173
	v_pk_add_f32 v[42:43], v[42:43], v[44:45]
	global_store_dwordx4 v[48:49], v[40:43], off offset:64
	s_nop 1
	v_lshlrev_b32_e32 v40, 16, v170
	v_and_b32_e32 v41, 0xffff0000, v170
	v_pk_add_f32 v[36:37], v[36:37], v[40:41]
	v_lshlrev_b32_e32 v40, 16, v171
	v_and_b32_e32 v41, 0xffff0000, v171
	v_pk_add_f32 v[38:39], v[38:39], v[40:41]
	global_store_dwordx4 v[48:49], v[36:39], off offset:512
	s_nop 1
	v_lshlrev_b32_e32 v36, 16, v168
	v_and_b32_e32 v37, 0xffff0000, v168
	v_pk_add_f32 v[28:29], v[28:29], v[36:37]
	v_lshlrev_b32_e32 v36, 16, v169
	v_and_b32_e32 v37, 0xffff0000, v169
	v_pk_add_f32 v[30:31], v[30:31], v[36:37]
	global_store_dwordx4 v[48:49], v[28:31], off offset:576
	v_lshlrev_b64 v[36:37], 12, v[154:155]
	s_nop 0
	v_lshlrev_b32_e32 v28, 16, v166
	v_and_b32_e32 v29, 0xffff0000, v166
	v_pk_add_f32 v[28:29], v[32:33], v[28:29]
	v_lshlrev_b32_e32 v30, 16, v167
	v_and_b32_e32 v31, 0xffff0000, v167
	v_lshl_add_u64 v[32:33], s[4:5], 0, v[36:37]
	v_pk_add_f32 v[30:31], v[34:35], v[30:31]
	v_lshl_add_u64 v[32:33], v[32:33], 0, v[148:149]
	global_store_dwordx4 v[32:33], v[28:31], off
	s_nop 1
	v_lshlrev_b32_e32 v28, 16, v162
	v_and_b32_e32 v29, 0xffff0000, v162
	v_pk_add_f32 v[24:25], v[24:25], v[28:29]
	v_lshlrev_b32_e32 v28, 16, v163
	v_and_b32_e32 v29, 0xffff0000, v163
	v_pk_add_f32 v[26:27], v[26:27], v[28:29]
	global_store_dwordx4 v[32:33], v[24:27], off offset:64
	s_nop 1
	v_lshlrev_b32_e32 v24, 16, v160
	v_and_b32_e32 v25, 0xffff0000, v160
	v_pk_add_f32 v[20:21], v[20:21], v[24:25]
	v_lshlrev_b32_e32 v24, 16, v161
	v_and_b32_e32 v25, 0xffff0000, v161
	v_pk_add_f32 v[22:23], v[22:23], v[24:25]
	global_store_dwordx4 v[32:33], v[20:23], off offset:512
	s_nop 1
	v_lshlrev_b32_e32 v20, 16, v158
	v_and_b32_e32 v21, 0xffff0000, v158
	v_pk_add_f32 v[12:13], v[12:13], v[20:21]
	v_lshlrev_b32_e32 v20, 16, v159
	v_and_b32_e32 v21, 0xffff0000, v159
	v_pk_add_f32 v[14:15], v[14:15], v[20:21]
	global_store_dwordx4 v[32:33], v[12:15], off offset:576
	v_lshlrev_b64 v[20:21], 12, v[144:145]
	s_nop 0
	v_lshlrev_b32_e32 v12, 16, v156
	v_and_b32_e32 v13, 0xffff0000, v156
	v_pk_add_f32 v[12:13], v[16:17], v[12:13]
	v_lshlrev_b32_e32 v14, 16, v157
	v_and_b32_e32 v15, 0xffff0000, v157
	v_lshl_add_u64 v[16:17], s[4:5], 0, v[20:21]
	v_pk_add_f32 v[14:15], v[18:19], v[14:15]
	v_lshl_add_u64 v[16:17], v[16:17], 0, v[148:149]
	global_store_dwordx4 v[16:17], v[12:15], off
	s_nop 1
	v_lshlrev_b32_e32 v12, 16, v152
	v_and_b32_e32 v13, 0xffff0000, v152
	v_pk_add_f32 v[8:9], v[8:9], v[12:13]
	v_lshlrev_b32_e32 v12, 16, v153
	v_and_b32_e32 v13, 0xffff0000, v153
	v_pk_add_f32 v[10:11], v[10:11], v[12:13]
	global_store_dwordx4 v[16:17], v[8:11], off offset:64
	s_nop 1
	v_lshlrev_b32_e32 v8, 16, v150
	v_and_b32_e32 v9, 0xffff0000, v150
	v_pk_add_f32 v[4:5], v[4:5], v[8:9]
	v_lshlrev_b32_e32 v8, 16, v151
	v_and_b32_e32 v9, 0xffff0000, v151
	v_pk_add_f32 v[6:7], v[6:7], v[8:9]
	global_store_dwordx4 v[16:17], v[4:7], off offset:512
	s_nop 1
	v_lshlrev_b32_e32 v4, 16, v146
	v_and_b32_e32 v5, 0xffff0000, v146
	v_pk_add_f32 v[0:1], v[0:1], v[4:5]
	v_lshlrev_b32_e32 v4, 16, v147
	v_and_b32_e32 v5, 0xffff0000, v147
	v_pk_add_f32 v[2:3], v[2:3], v[4:5]
	global_store_dwordx4 v[16:17], v[0:3], off offset:576
	s_cbranch_vccz .LBB0_782
	s_waitcnt vmcnt(0)
	s_cmpk_gt_u32 s26, 0xff
	s_cbranch_scc1 .LBB0_793
	s_barrier
